# attention-A loop: s_setprio 1 for the QK/softmax/PV segment, 0 for the K/V LDS write + barrier segment (plus GEMM loop priorities)
# speedup vs baseline: 1.0258x; 1.0094x over previous
; #define MFMA32(a, b, c) __builtin_amdgcn_mfma_f32_32x32x16_bf16((a), (b), (c), 0, 0, 0)
; __device__ __forceinline__ void attn_item_A(const Params& p, int layer, int head, int q0u, char* lds) {
;     ...
;   for (int t = 0; t < ntiles; ++t) {
;     const int buf = t & 1;
;     const bool more = (t + 1 < ntiles);
;     if (more) { ATT_LOADK(t + 1); ATT_LOADV(t + 1); }
;     const u16* kt_ = Ks + buf * 32 * KLD + r * KLD + 8 * h;
;     bf16x8 a0, a1, b0, b1;
;     {
;       f32x16 sx, sy;
; #pragma unroll
;       for (int e = 0; e < 16; ++e) { sx[e] = 0.f; sy[e] = 0.f; }
; #pragma unroll
;       for (int s = 0; s < 4; ++s) {
;         const bf16x8 kf = *(const bf16x8*)(kt_ + 16 * s);
;         const bf16x8 qf = *(const bf16x8*)(Qs + s * 1024);
;         sx = MFMA32(kf, qf, sx);
;       }
; #pragma unroll
;       for (int s = 4; s < 8; ++s) {
;         const bf16x8 kf = *(const bf16x8*)(kt_ + 16 * s);
;         const bf16x8 qf = *(const bf16x8*)(Qs + s * 1024);
;         sy = MFMA32(kf, qf, sy);
;       }
;       {
;         float w[16];
; #pragma unroll
;         for (int e = 0; e < 16; ++e) { w[e] = __builtin_amdgcn_exp2f(fmaf(sx[e], CS, -bA)); lA += w[e]; }
;         const u32x4 p0 = {pk2(w[0], w[1]), pk2(w[2], w[3]), pk2(w[4], w[5]), pk2(w[6], w[7])};
;         const u32x4 p1 = {pk2(w[8], w[9]), pk2(w[10], w[11]), pk2(w[12], w[13]), pk2(w[14], w[15])};
;         a0 = __builtin_bit_cast(bf16x8, p0); a1 = __builtin_bit_cast(bf16x8, p1);
;       }
;       {
;         float w[16];
; #pragma unroll
;         for (int e = 0; e < 16; ++e) { w[e] = __builtin_amdgcn_exp2f(fmaf(sy[e], CS, -bB)); lB += w[e]; }
;         const u32x4 p0 = {pk2(w[0], w[1]), pk2(w[2], w[3]), pk2(w[4], w[5]), pk2(w[6], w[7])};
;         const u32x4 p1 = {pk2(w[8], w[9]), pk2(w[10], w[11]), pk2(w[12], w[13]), pk2(w[14], w[15])};
;         b0 = __builtin_bit_cast(bf16x8, p0); b1 = __builtin_bit_cast(bf16x8, p1);
;       }
;     }
;     const u16* vt = Vt + buf * 128 * VLD + r * VLD + 4 * h;
; #pragma unroll
;     for (int d = 0; d < 4; d += 2) {
;       const s16x4 l0 = *(const s16x4*)(vt + d * 32 * VLD), h0 = *(const s16x4*)(vt + d * 32 * VLD + 8);
;       const s16x4 l1 = *(const s16x4*)(vt + d * 32 * VLD + 16), h1 = *(const s16x4*)(vt + d * 32 * VLD + 24);
;       const s16x4 m0 = *(const s16x4*)(vt + (d + 1) * 32 * VLD), n0 = *(const s16x4*)(vt + (d + 1) * 32 * VLD + 8);
.LBB0_1571:
	s_setprio 1
	s_and_b32 s1, s8, 1
	s_mul_i32 s7, s1, 0x2200
	v_add_u32_e32 v197, v193, v194
	v_add_u32_e32 v210, s7, v196
	ds_read_b128 v[128:131], v197 offset:37888
	ds_read_b128 v[160:163], v197 offset:38912
	ds_read_b128 v[144:147], v197 offset:41984
	ds_read_b128 v[178:181], v197 offset:43008
	ds_read_b128 v[132:135], v210
	ds_read_b128 v[198:201], v210 offset:32
	ds_read_b128 v[148:151], v210 offset:128
	ds_read_b128 v[202:205], v210 offset:160
	ds_read_b128 v[206:209], v210 offset:64
	ds_read_b128 v[216:219], v210 offset:96
	ds_read_b128 v[220:223], v210 offset:192
	ds_read_b128 v[224:227], v210 offset:224
	s_waitcnt lgkmcnt(7)
	v_mfma_f32_32x32x16_bf16 v[128:143], v[132:135], v[128:131], 0
	s_ashr_i32 s7, s6, 31
	s_add_i32 s8, s8, 1
	s_waitcnt lgkmcnt(5)
	v_mfma_f32_32x32x16_bf16 v[144:159], v[148:151], v[144:147], 0
	v_mfma_f32_32x32x16_bf16 v[128:143], v[198:201], v[160:163], v[128:143]
	s_waitcnt lgkmcnt(4)
	v_mfma_f32_32x32x16_bf16 v[144:159], v[202:205], v[178:181], v[144:159]
	s_waitcnt lgkmcnt(3)
	v_mfma_f32_32x32x16_bf16 v[128:143], v[206:209], v[240:243], v[128:143]
	v_lshl_add_u64 v[178:179], s[6:7], 1, v[170:171]
	s_mul_i32 s7, s1, 0x2400
	v_add_u32_e32 v210, s7, v175
	v_add_u32_e32 v212, 0x4000, v210
	v_add_u32_e32 v215, 0x4800, v210
	v_add_u32_e32 v238, 0x5000, v210
	s_waitcnt lgkmcnt(1)
	v_mfma_f32_32x32x16_bf16 v[144:159], v[220:223], v[248:251], v[144:159]
	v_add_u32_e32 v160, s6, v195
	v_mad_i64_i32 v[180:181], s[10:11], v160, s63, v[176:177]
	global_load_dwordx4 v[160:163], v[180:181], off offset:1040
	v_add_u32_e32 v210, 0x5800, v210
	s_xor_b32 s1, s1, 1
	s_add_i32 s6, s6, 32
	v_mfma_f32_32x32x16_bf16 v[128:143], v[216:219], v[244:247], v[128:143]
	ds_read2_b64 v[198:201], v212 offset0:128 offset1:130
	s_mul_i32 s7, s1, 0x2200
	s_mulk_i32 s1, 0x2400
	s_cmp_eq_u32 s0, s8
	s_waitcnt lgkmcnt(1)
	v_mfma_f32_32x32x16_bf16 v[144:159], v[224:227], v[252:255], v[144:159]
	s_nop 5
	v_fmamk_f32 v128, v128, 0x3e38aa3b, v173
	v_fmamk_f32 v129, v129, 0x3e38aa3b, v173
	v_fmamk_f32 v130, v130, 0x3e38aa3b, v173
	v_fmamk_f32 v131, v131, 0x3e38aa3b, v173
	v_fmamk_f32 v132, v132, 0x3e38aa3b, v173
	v_fmamk_f32 v133, v133, 0x3e38aa3b, v173
	v_fmamk_f32 v202, v134, 0x3e38aa3b, v173
	v_fmamk_f32 v135, v135, 0x3e38aa3b, v173
	v_fmamk_f32 v203, v144, 0x3e38aa3b, v164
	v_fmamk_f32 v145, v145, 0x3e38aa3b, v164
	v_fmamk_f32 v204, v146, 0x3e38aa3b, v164
	v_fmamk_f32 v205, v147, 0x3e38aa3b, v164
	v_fmamk_f32 v206, v148, 0x3e38aa3b, v164
	v_fmamk_f32 v207, v149, 0x3e38aa3b, v164
	v_fmamk_f32 v208, v150, 0x3e38aa3b, v164
	v_fmamk_f32 v209, v151, 0x3e38aa3b, v164
	v_exp_f32_e32 v150, v128
	v_exp_f32_e32 v148, v129
	v_exp_f32_e32 v146, v130
	v_exp_f32_e32 v144, v131
	v_exp_f32_e32 v134, v132
	v_exp_f32_e32 v130, v133
	v_exp_f32_e32 v132, v202
	v_exp_f32_e32 v128, v135
	v_exp_f32_e32 v151, v203
	v_exp_f32_e32 v149, v145
	v_exp_f32_e32 v147, v204
	v_exp_f32_e32 v145, v205
	v_exp_f32_e32 v135, v206
	v_exp_f32_e32 v131, v207
	v_exp_f32_e32 v133, v208
	v_exp_f32_e32 v129, v209
	v_cvt_pk_bf16_f32 v202, v150, v148
	v_cvt_pk_bf16_f32 v203, v146, v144
	v_cvt_pk_bf16_f32 v204, v134, v130
	v_cvt_pk_bf16_f32 v205, v132, v128
	v_cvt_pk_bf16_f32 v206, v151, v149
	v_cvt_pk_bf16_f32 v207, v147, v145
	v_cvt_pk_bf16_f32 v208, v135, v131
	v_cvt_pk_bf16_f32 v209, v133, v129
	s_waitcnt lgkmcnt(0)
	v_mfma_f32_32x32x16_bf16 v[64:79], v[202:205], v[198:201], v[64:79]
	v_fmamk_f32 v152, v152, 0x3e38aa3b, v164
	v_fmamk_f32 v153, v153, 0x3e38aa3b, v164
	v_fmamk_f32 v154, v154, 0x3e38aa3b, v164
	v_fmamk_f32 v155, v155, 0x3e38aa3b, v164
	v_fmamk_f32 v156, v156, 0x3e38aa3b, v164
	v_fmamk_f32 v157, v157, 0x3e38aa3b, v164
	v_fmamk_f32 v158, v158, 0x3e38aa3b, v164
	v_mfma_f32_32x32x16_bf16 v[48:63], v[206:209], v[198:201], v[48:63]
	ds_read2_b64 v[198:201], v215 offset0:160 offset1:162
	ds_read2_b64 v[216:219], v212 offset0:132 offset1:134
	ds_read2_b64 v[220:223], v238 offset0:192 offset1:194
	ds_read2_b64 v[224:227], v210 offset0:224 offset1:226
	v_fmamk_f32 v159, v159, 0x3e38aa3b, v164
	v_exp_f32_e32 v213, v152
	v_exp_f32_e32 v229, v153
	v_exp_f32_e32 v231, v154
	v_exp_f32_e32 v233, v157
	s_waitcnt lgkmcnt(1)
	v_mfma_f32_32x32x16_bf16 v[96:111], v[202:205], v[220:223], v[96:111]
	v_exp_f32_e32 v235, v158
	v_exp_f32_e32 v237, v159
	v_fmamk_f32 v136, v136, 0x3e38aa3b, v173
	v_fmamk_f32 v137, v137, 0x3e38aa3b, v173
	v_fmamk_f32 v138, v138, 0x3e38aa3b, v173
	v_fmamk_f32 v139, v139, 0x3e38aa3b, v173
	v_fmamk_f32 v140, v140, 0x3e38aa3b, v173
	v_mfma_f32_32x32x16_bf16 v[16:31], v[206:209], v[220:223], v[16:31]
	v_exp_f32_e32 v221, v155
	v_exp_f32_e32 v223, v156
	global_load_dwordx4 v[152:155], v[180:181], off offset:1024
	global_load_dwordx4 v[156:159], v[178:179], off
	v_fmamk_f32 v141, v141, 0x3e38aa3b, v173
	global_load_dwordx4 v[178:181], v[178:179], off offset:16
	v_fmamk_f32 v142, v142, 0x3e38aa3b, v173
	v_fmamk_f32 v143, v143, 0x3e38aa3b, v173
	v_exp_f32_e32 v212, v136
	v_exp_f32_e32 v228, v137
	v_exp_f32_e32 v230, v138
	v_exp_f32_e32 v220, v139
	v_exp_f32_e32 v222, v140
	v_exp_f32_e32 v232, v141
	v_exp_f32_e32 v234, v142
	v_exp_f32_e32 v236, v143
	v_mfma_f32_32x32x16_bf16 v[80:95], v[202:205], v[198:201], v[80:95]
	v_cvt_pk_bf16_f32 v136, v212, v228
	v_cvt_pk_bf16_f32 v137, v230, v220
	v_cvt_pk_bf16_f32 v138, v222, v232
	v_cvt_pk_bf16_f32 v139, v234, v236
	v_cvt_pk_bf16_f32 v140, v213, v229
	v_cvt_pk_bf16_f32 v141, v231, v221
	v_cvt_pk_bf16_f32 v142, v223, v233
	v_mfma_f32_32x32x16_bf16 v[32:47], v[206:209], v[198:201], v[32:47]
	v_cvt_pk_bf16_f32 v143, v235, v237
	ds_read2_b64 v[198:201], v215 offset0:164 offset1:166
	v_add_f32_e64 v150, v168, v150
	v_add_f32_e64 v151, v169, v151
	v_add_f32_e64 v148, v148, v150
	v_add_f32_e64 v149, v149, v151
	v_pk_add_f32 v[146:147], v[146:147], v[148:149]
	s_waitcnt lgkmcnt(1)
; __device__ __forceinline__ void attn_item_A(const Params& p, int layer, int head, int q0u, char* lds) {
;     ...
; #pragma unroll
;       for (int s = 0; s < 4; ++s) {
;         const bf16x8 kf = *(const bf16x8*)(kt_ + 16 * s);
;         const bf16x8 qf = *(const bf16x8*)(Qs + s * 1024);
;         sx = MFMA32(kf, qf, sx);
;       }
; #pragma unroll
;       for (int s = 4; s < 8; ++s) {
;         const bf16x8 kf = *(const bf16x8*)(kt_ + 16 * s);
;         const bf16x8 qf = *(const bf16x8*)(Qs + s * 1024);
;         sy = MFMA32(kf, qf, sy);
;       }
;       {
;         float w[16];
; #pragma unroll
;         for (int e = 0; e < 16; ++e) { w[e] = __builtin_amdgcn_exp2f(fmaf(sx[e], CS, -bA)); lA += w[e]; }
;         const u32x4 p0 = {pk2(w[0], w[1]), pk2(w[2], w[3]), pk2(w[4], w[5]), pk2(w[6], w[7])};
;         const u32x4 p1 = {pk2(w[8], w[9]), pk2(w[10], w[11]), pk2(w[12], w[13]), pk2(w[14], w[15])};
;         a0 = __builtin_bit_cast(bf16x8, p0); a1 = __builtin_bit_cast(bf16x8, p1);
;       }
;       {
;         float w[16];
; #pragma unroll
;         for (int e = 0; e < 16; ++e) { w[e] = __builtin_amdgcn_exp2f(fmaf(sy[e], CS, -bB)); lB += w[e]; }
;         const u32x4 p0 = {pk2(w[0], w[1]), pk2(w[2], w[3]), pk2(w[4], w[5]), pk2(w[6], w[7])};
;         const u32x4 p1 = {pk2(w[8], w[9]), pk2(w[10], w[11]), pk2(w[12], w[13]), pk2(w[14], w[15])};
;         b0 = __builtin_bit_cast(bf16x8, p0); b1 = __builtin_bit_cast(bf16x8, p1);
;       }
;     }
;     const u16* vt = Vt + buf * 128 * VLD + r * VLD + 4 * h;
; #pragma unroll
;     for (int d = 0; d < 4; d += 2) {
;       const s16x4 l0 = *(const s16x4*)(vt + d * 32 * VLD), h0 = *(const s16x4*)(vt + d * 32 * VLD + 8);
;       const s16x4 l1 = *(const s16x4*)(vt + d * 32 * VLD + 16), h1 = *(const s16x4*)(vt + d * 32 * VLD + 24);
;       const s16x4 m0 = *(const s16x4*)(vt + (d + 1) * 32 * VLD), n0 = *(const s16x4*)(vt + (d + 1) * 32 * VLD + 8);
;       const s16x4 m1 = *(const s16x4*)(vt + (d + 1) * 32 * VLD + 16), n1 = *(const s16x4*)(vt + (d + 1) * 32 * VLD + 24);
;       const bf16x8 v0 = {l0[0], l0[1], l0[2], l0[3], h0[0], h0[1], h0[2], h0[3]};
;       const bf16x8 v1 = {l1[0], l1[1], l1[2], l1[3], h1[0], h1[1], h1[2], h1[3]};
;       const bf16x8 u0 = {m0[0], m0[1], m0[2], m0[3], n0[0], n0[1], n0[2], n0[3]};
;       const bf16x8 u1 = {m1[0], m1[1], m1[2], m1[3], n1[0], n1[1], n1[2], n1[3]};
	v_mfma_f32_32x32x16_bf16 v[112:127], v[202:205], v[224:227], v[112:127]
	ds_read2_b64 v[202:205], v210 offset0:228 offset1:230
	v_add_f32_e64 v144, v144, v146
	v_add_f32_e64 v145, v145, v147
	v_add_f32_e64 v134, v134, v144
	v_add_f32_e64 v135, v135, v145
	v_pk_add_f32 v[130:131], v[130:131], v[134:135]
	v_mfma_f32_32x32x16_bf16 v[0:15], v[206:209], v[224:227], v[0:15]
	v_add_f32_e64 v130, v132, v130
	v_add_f32_e64 v131, v133, v131
	v_add_u32_e32 v206, s7, v172
	v_add_f32_e64 v128, v128, v130
	v_add_f32_e64 v129, v129, v131
	v_add_u32_e32 v207, s1, v174
	v_pk_add_f32 v[128:129], v[212:213], v[128:129]
	v_add_u32_e32 v208, 0x4400, v207
	v_pk_add_f32 v[128:129], v[228:229], v[128:129]
	s_waitcnt lgkmcnt(1)
	v_mfma_f32_32x32x16_bf16 v[80:95], v[136:139], v[198:201], v[80:95]
	v_add_f32_e64 v128, v230, v128
	v_add_f32_e64 v129, v231, v129
	v_add_u32_e32 v207, 0x4410, v207
	v_add_f32_e64 v128, v220, v128
	v_add_f32_e64 v129, v221, v129
	v_pk_add_f32 v[128:129], v[222:223], v[128:129]
	s_nop 0
	v_pk_add_f32 v[128:129], v[232:233], v[128:129]
	v_mfma_f32_32x32x16_bf16 v[32:47], v[140:143], v[198:201], v[32:47]
	ds_read2_b64 v[198:201], v238 offset0:196 offset1:198
	v_add_f32_e64 v128, v234, v128
	v_add_f32_e64 v129, v235, v129
	s_setprio 0
	s_waitcnt vmcnt(2)
	ds_write_b128 v206, v[152:155]
	ds_write_b128 v206, v[160:163] offset:16
	s_waitcnt vmcnt(1)
	ds_write2_b64 v208, v[156:157], v[158:159] offset1:1
	s_waitcnt vmcnt(0)
	ds_write2_b64 v207, v[178:179], v[180:181] offset1:1
	v_mfma_f32_32x32x16_bf16 v[64:79], v[136:139], v[216:219], v[64:79]
	v_add_f32_e64 v168, v236, v128
	v_add_f32_e64 v169, v237, v129
	s_waitcnt lgkmcnt(0)
	s_barrier
	v_mfma_f32_32x32x16_bf16 v[48:63], v[140:143], v[216:219], v[48:63]
	v_mfma_f32_32x32x16_bf16 v[96:111], v[136:139], v[198:201], v[96:111]
	v_mfma_f32_32x32x16_bf16 v[16:31], v[140:143], v[198:201], v[16:31]
	v_mfma_f32_32x32x16_bf16 v[112:127], v[136:139], v[202:205], v[112:127]
	v_mfma_f32_32x32x16_bf16 v[0:15], v[140:143], v[202:205], v[0:15]
	s_cbranch_scc0 .LBB0_1571
	s_and_b32 s0, s0, 1
	s_mul_i32 s1, s0, 0x2200
	v_add_u32_e32 v170, s1, v196
	ds_read_b128 v[128:131], v170
	ds_read_b128 v[132:135], v197 offset:37888
	ds_read_b128 v[136:139], v197 offset:38912
	ds_read_b128 v[140:143], v170 offset:32
	s_mulk_i32 s0, 0x2400
	s_waitcnt lgkmcnt(2)
	v_mfma_f32_32x32x16_bf16 v[144:159], v[128:131], v[132:135], 0
	ds_read_b128 v[128:131], v170 offset:64
	ds_read_b128 v[132:135], v197 offset:39936
	ds_read_b128 v[160:163], v197 offset:40960
	ds_read_b128 v[176:179], v170 offset:96
	s_waitcnt lgkmcnt(4)
	v_mfma_f32_32x32x16_bf16 v[144:159], v[140:143], v[136:139], v[144:159]
	s_waitcnt lgkmcnt(2)
	v_mfma_f32_32x32x16_bf16 v[144:159], v[128:131], v[132:135], v[144:159]
	ds_read_b128 v[128:131], v170 offset:128
	ds_read_b128 v[132:135], v197 offset:41984
	ds_read_b128 v[198:201], v197 offset:43008
	ds_read_b128 v[202:205], v170 offset:160
	ds_read_b128 v[206:209], v197 offset:44032
	ds_read_b128 v[194:197], v197 offset:45056
	ds_read_b128 v[216:219], v170 offset:192
	ds_read_b128 v[220:223], v170 offset:224
	s_waitcnt lgkmcnt(6)
	v_mfma_f32_32x32x16_bf16 v[128:143], v[128:131], v[132:135], 0
	s_waitcnt lgkmcnt(4)
	v_mfma_f32_32x32x16_bf16 v[128:143], v[202:205], v[198:201], v[128:143]
	s_waitcnt lgkmcnt(1)
	v_mfma_f32_32x32x16_bf16 v[128:143], v[216:219], v[206:209], v[128:143]
	s_waitcnt lgkmcnt(0)
	v_mfma_f32_32x32x16_bf16 v[128:143], v[220:223], v[194:197], v[128:143]
	v_mfma_f32_32x32x16_bf16 v[144:159], v[176:179], v[160:163], v[144:159]
	s_nop 10
	v_fmamk_f32 v128, v128, 0x3e38aa3b, v164
	v_exp_f32_e32 v194, v128
	v_fmamk_f32 v128, v129, 0x3e38aa3b, v164
	v_exp_f32_e32 v195, v128
	v_fmamk_f32 v128, v130, 0x3e38aa3b, v164
	v_exp_f32_e32 v196, v128
	v_fmamk_f32 v128, v131, 0x3e38aa3b, v164
	v_fmamk_f32 v144, v144, 0x3e38aa3b, v173
	v_exp_f32_e32 v160, v144
	v_fmamk_f32 v144, v155, 0x3e38aa3b, v173
	v_exp_f32_e32 v197, v128
	v_fmamk_f32 v128, v132, 0x3e38aa3b, v164
	v_fmamk_f32 v132, v134, 0x3e38aa3b, v164
	v_fmamk_f32 v145, v145, 0x3e38aa3b, v173
	v_fmamk_f32 v146, v146, 0x3e38aa3b, v173
	v_fmamk_f32 v147, v147, 0x3e38aa3b, v173
	v_fmamk_f32 v148, v148, 0x3e38aa3b, v173
	v_fmamk_f32 v149, v149, 0x3e38aa3b, v173
	v_fmamk_f32 v150, v150, 0x3e38aa3b, v173
	v_fmamk_f32 v151, v151, 0x3e38aa3b, v173
	v_exp_f32_e32 v179, v144
	v_fmamk_f32 v144, v156, 0x3e38aa3b, v173
	v_exp_f32_e32 v198, v128
	v_fmamk_f32 v128, v133, 0x3e38aa3b, v164
	v_add_u32_e32 v156, s0, v175
	v_exp_f32_e32 v175, v132
	v_fmamk_f32 v132, v135, 0x3e38aa3b, v164
	v_exp_f32_e32 v161, v145
	v_exp_f32_e32 v162, v146
	v_exp_f32_e32 v163, v147
	v_exp_f32_e32 v170, v148
	v_exp_f32_e32 v171, v149
	v_exp_f32_e32 v172, v150
	v_exp_f32_e32 v174, v151
	v_exp_f32_e32 v199, v128
	v_exp_f32_e32 v200, v132
	v_fmamk_f32 v152, v152, 0x3e38aa3b, v173
	v_exp_f32_e32 v180, v144
	v_fmamk_f32 v144, v157, 0x3e38aa3b, v173
	v_exp_f32_e32 v176, v152
	v_exp_f32_e32 v181, v144
	v_fmamk_f32 v144, v158, 0x3e38aa3b, v173
	v_add_u32_e32 v152, 0x4000, v156
	v_fmamk_f32 v136, v136, 0x3e38aa3b, v164
	v_exp_f32_e32 v193, v144
	v_cvt_pk_bf16_f32 v144, v160, v161
	v_cvt_pk_bf16_f32 v145, v162, v163
	v_cvt_pk_bf16_f32 v146, v170, v171
	v_cvt_pk_bf16_f32 v147, v172, v174
	ds_read2_b64 v[128:131], v152 offset0:128 offset1:130
	v_cvt_pk_bf16_f32 v132, v194, v195
	v_cvt_pk_bf16_f32 v133, v196, v197
	v_cvt_pk_bf16_f32 v134, v198, v199
	v_cvt_pk_bf16_f32 v135, v175, v200
	v_exp_f32_e32 v201, v136
	v_fmamk_f32 v136, v137, 0x3e38aa3b, v164
	v_exp_f32_e32 v202, v136
	v_fmamk_f32 v136, v138, 0x3e38aa3b, v164
	v_exp_f32_e32 v203, v136
	v_fmamk_f32 v136, v139, 0x3e38aa3b, v164
	v_fmamk_f32 v153, v153, 0x3e38aa3b, v173
	v_exp_f32_e32 v204, v136
	v_fmamk_f32 v136, v140, 0x3e38aa3b, v164
	v_exp_f32_e32 v177, v153
	v_add_u32_e32 v153, 0x4800, v156
	v_exp_f32_e32 v205, v136
	v_fmamk_f32 v136, v141, 0x3e38aa3b, v164
	v_fmamk_f32 v154, v154, 0x3e38aa3b, v173
	v_fmac_f32_e32 v173, 0x3e38aa3b, v159
	s_waitcnt lgkmcnt(0)
; __device__ __forceinline__ void attn_item_A(const Params& p, int layer, int head, int q0u, char* lds) {
;     ...
;     const u16* vt = Vt + buf * 128 * VLD + r * VLD + 4 * h;
; #pragma unroll
;     for (int d = 0; d < 4; d += 2) {
;       const s16x4 l0 = *(const s16x4*)(vt + d * 32 * VLD), h0 = *(const s16x4*)(vt + d * 32 * VLD + 8);
;       const s16x4 l1 = *(const s16x4*)(vt + d * 32 * VLD + 16), h1 = *(const s16x4*)(vt + d * 32 * VLD + 24);
;       const s16x4 m0 = *(const s16x4*)(vt + (d + 1) * 32 * VLD), n0 = *(const s16x4*)(vt + (d + 1) * 32 * VLD + 8);
;       const s16x4 m1 = *(const s16x4*)(vt + (d + 1) * 32 * VLD + 16), n1 = *(const s16x4*)(vt + (d + 1) * 32 * VLD + 24);
;       const bf16x8 v0 = {l0[0], l0[1], l0[2], l0[3], h0[0], h0[1], h0[2], h0[3]};
;       const bf16x8 v1 = {l1[0], l1[1], l1[2], l1[3], h1[0], h1[1], h1[2], h1[3]};
;       const bf16x8 u0 = {m0[0], m0[1], m0[2], m0[3], n0[0], n0[1], n0[2], n0[3]};
;       const bf16x8 u1 = {m1[0], m1[1], m1[2], m1[3], n1[0], n1[1], n1[2], n1[3]};
;       o1[d] = MFMA32(a0, v0, o1[d]);
;       o2[d] = MFMA32(b0, v0, o2[d]);
;       o1[d + 1] = MFMA32(a0, u0, o1[d + 1]);
;       o2[d + 1] = MFMA32(b0, u0, o2[d + 1]);
;       o1[d] = MFMA32(a1, v1, o1[d]);
;       o2[d] = MFMA32(b1, v1, o2[d]);
;       o1[d + 1] = MFMA32(a1, u1, o1[d + 1]);
;       o2[d + 1] = MFMA32(b1, u1, o2[d + 1]);
;     }
;     if (more) { ATT_STOREK(buf ^ 1); ATT_STOREV(buf ^ 1); }
;     __syncthreads();
;   }
;   int lane_e = lane; asm volatile("" : "+v"(lane_e));
;   const int r_e = lane_e & 31, h_e = lane_e >> 5;
;   lA += __shfl_xor(lA, 32); lB += __shfl_xor(lB, 32);
;   const float lam = ((const float*)(p.ws + OFF_LAM))[layer];
;   const float iA = 1.f / lA, iB = lam / lB;
;   u16* Mx = (u16*)(p.ws + OFF_M);
;   const int orow0 = q0u + wid * 32;
;   const float lam_init = 0.8f - 0.6f * expf(-0.3f * (float)layer);
;   float sw[4];
; #pragma unroll
;   for (int d = 0; d < 4; ++d) sw[d] = p.subln[layer * 128 + d * 32 + r_e] * (1.f - lam_init);
; #pragma unroll
;   for (int e = 0; e < 16; ++e) {
;     const int qq = crow(e, h_e);
;     const float ia = __shfl(iA, qq), ib = __shfl(iB, qq);
;     float ov[4];
;     float ss = 0.f;
; #pragma unroll
;     for (int d = 0; d < 4; ++d) { ov[d] = o1[d][e] * ia - o2[d][e] * ib; ss += ov[d] * ov[d]; }
; #pragma unroll
;     for (int x = 16; x >= 1; x >>= 1) ss += __shfl_xor(ss, x);
	v_mfma_f32_32x32x16_bf16 v[64:79], v[144:147], v[128:131], v[64:79]
	v_exp_f32_e32 v206, v136
	v_fmamk_f32 v136, v142, 0x3e38aa3b, v164
	v_fmac_f32_e32 v164, 0x3e38aa3b, v143
	v_exp_f32_e32 v178, v154
	v_exp_f32_e32 v173, v173
	v_exp_f32_e32 v207, v136
	v_exp_f32_e32 v164, v164
	v_mfma_f32_32x32x16_bf16 v[48:63], v[132:135], v[128:131], v[48:63]
	ds_read2_b64 v[128:131], v153 offset0:160 offset1:162
	v_cvt_pk_bf16_f32 v148, v176, v177
	v_cvt_pk_bf16_f32 v149, v178, v179
	v_cvt_pk_bf16_f32 v150, v180, v181
	v_cvt_pk_bf16_f32 v151, v193, v173
	v_cvt_pk_bf16_f32 v136, v201, v202
	v_cvt_pk_bf16_f32 v137, v203, v204
	s_waitcnt lgkmcnt(0)
	v_mfma_f32_32x32x16_bf16 v[80:95], v[144:147], v[128:131], v[80:95]
	v_cvt_pk_bf16_f32 v138, v205, v206
	v_cvt_pk_bf16_f32 v139, v207, v164
	v_add_f32_e32 v160, v168, v160
	v_add_f32_e32 v160, v161, v160
	v_mfma_f32_32x32x16_bf16 v[32:47], v[132:135], v[128:131], v[32:47]
	ds_read2_b64 v[128:131], v152 offset0:132 offset1:134
	v_add_u32_e32 v152, 0x5000, v156
	v_add_u32_e32 v156, 0x5800, v156
	s_waitcnt lgkmcnt(0)
	v_mfma_f32_32x32x16_bf16 v[64:79], v[148:151], v[128:131], v[64:79]
	v_mfma_f32_32x32x16_bf16 v[48:63], v[136:139], v[128:131], v[48:63]
	ds_read2_b64 v[128:131], v153 offset0:164 offset1:166
	ds_read2_b64 v[140:143], v152 offset0:192 offset1:194
	ds_read2_b64 v[152:155], v152 offset0:196 offset1:198
	s_waitcnt lgkmcnt(2)
	v_mfma_f32_32x32x16_bf16 v[80:95], v[148:151], v[128:131], v[80:95]
	v_mfma_f32_32x32x16_bf16 v[32:47], v[136:139], v[128:131], v[32:47]
	ds_read2_b64 v[128:131], v156 offset0:224 offset1:226
	ds_read2_b64 v[156:159], v156 offset0:228 offset1:230
	s_waitcnt lgkmcnt(0)
	s_barrier
	global_load_dword v208, v165, s[16:17]
	v_and_b32_e32 v209, 31, v167
	v_mfma_f32_32x32x16_bf16 v[96:111], v[144:147], v[140:143], v[96:111]
	v_lshlrev_b32_e32 v210, 2, v209
	global_load_dword v212, v210, s[54:55]
	global_load_dword v213, v210, s[54:55] offset:128
	global_load_dword v215, v210, s[54:55] offset:256
	v_mfma_f32_32x32x16_bf16 v[16:31], v[132:135], v[140:143], v[16:31]
	v_add_f32_e32 v141, v169, v194
	v_add_f32_e32 v141, v195, v141
	v_add_f32_e32 v141, v196, v141
	v_add_f32_e32 v141, v197, v141
	v_add_f32_e32 v140, v162, v160
	v_add_f32_e32 v140, v163, v140
	v_add_f32_e32 v140, v170, v140
	v_mfma_f32_32x32x16_bf16 v[112:127], v[144:147], v[128:131], v[112:127]
	v_add_f32_e32 v140, v171, v140
	v_add_f32_e32 v140, v172, v140
	v_add_f32_e32 v140, v174, v140
	v_add_f32_e32 v140, v176, v140
	v_add_f32_e32 v140, v177, v140
	v_add_f32_e32 v140, v178, v140
	v_add_f32_e32 v140, v179, v140
	v_mfma_f32_32x32x16_bf16 v[0:15], v[132:135], v[128:131], v[0:15]
	v_add_f32_e32 v128, v198, v141
	v_add_f32_e32 v128, v199, v128
	v_add_f32_e32 v128, v175, v128
	v_add_f32_e32 v128, v200, v128
	v_add_f32_e32 v128, v201, v128
	v_add_f32_e32 v128, v202, v128
	v_add_f32_e32 v128, v203, v128
	v_add_f32_e32 v128, v204, v128
	v_add_f32_e32 v128, v205, v128
	v_add_f32_e32 v128, v206, v128
	v_add_f32_e32 v128, v207, v128
	v_add_f32_e32 v128, v164, v128
	ds_bpermute_b32 v129, v192, v128
	v_add_f32_e32 v130, v180, v140
	v_add_f32_e32 v130, v181, v130
	v_add_f32_e32 v130, v193, v130
	v_add_f32_e32 v130, v173, v130
	s_waitcnt lgkmcnt(0)
	v_add_f32_e32 v128, v128, v129
	ds_bpermute_b32 v133, v192, v130
	v_mfma_f32_32x32x16_bf16 v[0:15], v[136:139], v[156:159], v[0:15]
	v_mov_b32_e32 v143, v32
	v_mov_b32_e32 v140, v64
	v_mov_b32_e32 v142, v48
	s_waitcnt lgkmcnt(0)
	v_add_f32_e32 v133, v130, v133
	v_mov_b32_e32 v141, v80
	v_mov_b32_e32 v80, v65
	v_lshlrev_b32_e32 v164, 1, v209
	v_mfma_f32_32x32x16_bf16 v[16:31], v[136:139], v[152:155], v[16:31]
	s_nop 2
	v_mov_b32_e32 v146, v0
	v_xor_b32_e32 v0, 16, v214
	s_waitcnt vmcnt(3)
	v_div_scale_f32 v129, s[0:1], v128, v128, v208
	v_rcp_f32_e32 v131, v129
	v_mfma_f32_32x32x16_bf16 v[96:111], v[148:151], v[152:155], v[96:111]
	s_nop 2
	v_mov_b32_e32 v147, v16
	s_waitcnt vmcnt(1)
	v_mul_f32_e32 v130, 0x3f4ccccd, v213
	v_fma_f32 v132, -v129, v131, 1.0
	v_fmac_f32_e32 v131, v132, v131
	v_div_scale_f32 v132, vcc, v208, v128, v208
	v_mul_f32_e32 v134, v132, v131
	v_fma_f32 v135, -v129, v134, v132
	v_fmac_f32_e32 v134, v135, v131
	v_fma_f32 v129, -v129, v134, v132
	v_div_fmas_f32 v129, v129, v131, v134
	v_div_scale_f32 v134, s[0:1], v133, v133, 1.0
	v_rcp_f32_e32 v135, v134
	v_mfma_f32_32x32x16_bf16 v[112:127], v[148:151], v[156:159], v[112:127]
	v_div_fixup_f32 v132, v129, v128, v208
	v_mov_b32_e32 v145, v96
	v_fma_f32 v136, -v134, v135, 1.0
	v_fmac_f32_e32 v135, v136, v135
	v_div_scale_f32 v136, vcc, 1.0, v133, 1.0
	v_mul_f32_e32 v137, v136, v135
	v_fma_f32 v138, -v134, v137, v136
	v_fmac_f32_e32 v137, v138, v135
	v_fma_f32 v134, -v134, v137, v136
	v_div_fmas_f32 v134, v134, v135, v137
	v_ashrrev_i32_e32 v135, 3, v167
	v_div_fixup_f32 v133, v134, v133, 1.0
	v_and_b32_e32 v134, -4, v135
	v_cmp_lt_i32_e32 vcc, v0, v188
	v_or_b32_e32 v150, 1, v134
	v_and_or_b32 v136, v135, 60, v187
	v_cndmask_b32_e32 v16, v214, v0, vcc
	v_and_or_b32 v0, v150, 61, v187
	v_lshlrev_b32_e32 v137, 2, v136
	v_lshlrev_b32_e32 v32, 2, v0
	ds_bpermute_b32 v138, v137, v132
	ds_bpermute_b32 v0, v32, v132
	ds_bpermute_b32 v136, v137, v133
	ds_bpermute_b32 v64, v32, v133
	v_mov_b32_e32 v32, v49
	s_waitcnt lgkmcnt(3)
	v_pk_mul_f32 v[142:143], v[142:143], v[138:139] op_sel_hi:[1,0]
	v_mov_b32_e32 v144, v112
	v_pk_mul_f32 v[138:139], v[146:147], v[138:139] op_sel_hi:[1,0]
	v_lshlrev_b32_e32 v48, 2, v16
	s_waitcnt lgkmcnt(2)
	v_pk_mul_f32 v[32:33], v[32:33], v[0:1] op_sel_hi:[1,0]
	v_mov_b32_e32 v16, v1
	s_waitcnt lgkmcnt(1)
; DI u16 f2bf(float a) { return (u16)(pk2(a, 0.f) & 0xffffu); }
; DI int crow(int i, int h) { return (i & 3) + 8 * (i >> 2) + 4 * h; }
; __device__ __forceinline__ void attn_item_A(const Params& p, int layer, int head, int q0u, char* lds) {
;     ...
; #pragma unroll
;   for (int e = 0; e < 16; ++e) {
;     const int qq = crow(e, h_e);
;     const float ia = __shfl(iA, qq), ib = __shfl(iB, qq);
;     float ov[4];
;     float ss = 0.f;
; #pragma unroll
;     for (int d = 0; d < 4; ++d) { ov[d] = o1[d][e] * ia - o2[d][e] * ib; ss += ov[d] * ov[d]; }
; #pragma unroll
;     for (int x = 16; x >= 1; x >>= 1) ss += __shfl_xor(ss, x);
;     const float rs = rsqrtf(ss * (1.f / 128.f) + LN_EPS);
;     const size_t rowoff = (size_t)(orow0 + qq) * LDX + ocol + r_e;
; #pragma unroll
;     for (int d = 0; d < 4; ++d) Mx[rowoff + d * 32] = f2bf(ov[d] * rs * sw[d]);
;   }
	v_pk_fma_f32 v[140:141], v[140:141], v[136:137], v[142:143] op_sel_hi:[1,0,1] neg_lo:[0,0,1] neg_hi:[0,0,1]
	v_pk_fma_f32 v[136:137], v[144:145], v[136:137], v[138:139] op_sel_hi:[1,0,1] neg_lo:[0,0,1] neg_hi:[0,0,1]
	s_waitcnt lgkmcnt(0)
	v_pk_fma_f32 v[144:145], v[80:81], v[64:65], v[32:33] op_sel_hi:[1,0,1] neg_lo:[0,0,1] neg_hi:[0,0,1]
	v_mov_b32_e32 v96, v113
	v_pk_mul_f32 v[0:1], v[16:17], v[0:1] op_sel_hi:[1,0]
	v_pk_mul_f32 v[142:143], v[140:141], v[140:141]
	v_pk_mul_f32 v[32:33], v[144:145], v[144:145]
	v_pk_fma_f32 v[96:97], v[96:97], v[64:65], v[0:1] op_sel_hi:[1,0,1] neg_lo:[0,0,1] neg_hi:[0,0,1]
	v_pk_mul_f32 v[138:139], v[136:137], v[136:137]
	v_pk_mul_f32 v[0:1], v[96:97], v[96:97]
	v_mov_b32_e32 v16, v32
	v_mov_b32_e32 v17, v142
	v_mov_b32_e32 v142, v33
	v_pk_add_f32 v[16:17], v[16:17], v[142:143]
	v_mov_b32_e32 v32, v1
	v_mov_b32_e32 v33, v139
	v_pk_add_f32 v[16:17], v[32:33], v[16:17]
	v_mov_b32_e32 v1, v138
	v_pk_add_f32 v[0:1], v[0:1], v[16:17]
	ds_bpermute_b32 v17, v48, v1
	ds_bpermute_b32 v16, v48, v0
	v_xor_b32_e32 v32, 8, v214
	v_cmp_lt_i32_e32 vcc, v32, v188
	s_add_u32 s0, s31, s4
	s_addc_u32 s1, s34, s5
	v_cndmask_b32_e32 v32, v214, v32, vcc
	v_lshlrev_b32_e32 v49, 2, v32
	s_waitcnt lgkmcnt(0)
	v_pk_add_f32 v[0:1], v[0:1], v[16:17]
	ds_bpermute_b32 v17, v49, v1
	ds_bpermute_b32 v16, v49, v0
	v_xor_b32_e32 v32, 4, v214
	v_cmp_lt_i32_e32 vcc, v32, v188
	v_mul_f32_e32 v131, 0x3f4ccccd, v212
	s_waitcnt vmcnt(0)
	v_mul_f32_e32 v129, 0x3f4ccccd, v215
	v_cndmask_b32_e32 v32, v214, v32, vcc
	v_lshlrev_b32_e32 v64, 2, v32
	s_waitcnt lgkmcnt(0)
	v_pk_add_f32 v[0:1], v[0:1], v[16:17]
	ds_bpermute_b32 v17, v64, v1
	ds_bpermute_b32 v16, v64, v0
	v_xor_b32_e32 v32, 2, v214
	v_cmp_lt_i32_e32 vcc, v32, v188
	v_or_b32_e32 v152, 2, v134
	v_or_b32_e32 v135, 3, v135
	v_cndmask_b32_e32 v32, v214, v32, vcc
	v_lshlrev_b32_e32 v65, 2, v32
	s_waitcnt lgkmcnt(0)
	v_pk_add_f32 v[0:1], v[0:1], v[16:17]
	ds_bpermute_b32 v17, v65, v1
	ds_bpermute_b32 v16, v65, v0
	v_xor_b32_e32 v32, 1, v214
	v_cmp_lt_i32_e32 vcc, v32, v188
	v_mov_b32_e32 v148, v2
	v_and_or_b32 v2, v135, 63, v187
	v_cndmask_b32_e32 v32, v214, v32, vcc
	v_lshlrev_b32_e32 v80, 2, v32
	s_waitcnt lgkmcnt(0)
	v_pk_add_f32 v[0:1], v[0:1], v[16:17]
	ds_bpermute_b32 v33, v80, v1
	ds_bpermute_b32 v32, v80, v0
	v_lshl_add_u64 v[16:17], s[0:1], 0, v[164:165]
	v_mov_b32_e32 v149, v18
	v_lshlrev_b32_e32 v18, 2, v2
	ds_bpermute_b32 v2, v18, v132
	s_waitcnt lgkmcnt(1)
	v_pk_add_f32 v[0:1], v[0:1], v[32:33]
	v_mov_b64_e32 v[32:33], s[30:31]
	v_pk_fma_f32 v[112:113], v[0:1], s[28:29], v[32:33] op_sel_hi:[1,0,0]
	v_mov_b32_e32 v142, v50
	v_mul_f32_e32 v0, 0x4b800000, v113
	v_cmp_gt_f32_e32 vcc, s80, v113
	ds_bpermute_b32 v50, v18, v133
	v_mov_b32_e32 v143, v34
	v_cndmask_b32_e32 v0, v113, v0, vcc
	v_rsq_f32_e32 v81, v0
	v_add_u32_e32 v0, v134, v191
	v_mad_i64_i32 v[0:1], s[0:1], v0, s77, v[16:17]
	v_mul_f32_e32 v113, 0x45800000, v81
	v_cndmask_b32_e32 v81, v81, v113, vcc
	v_mul_f32_e32 v113, v140, v81
	v_mul_f32_e32 v113, v131, v113
	v_cvt_pk_bf16_f32 v113, v113, s0
	global_store_short v[0:1], v113, off
	v_mul_f32_e32 v113, v141, v81
	v_mul_f32_e32 v113, v130, v113
	v_cvt_pk_bf16_f32 v113, v113, s0
	global_store_short v[0:1], v113, off offset:64
	v_mul_f32_e32 v113, v137, v81
	v_mul_f32_e32 v113, v129, v113
	v_cvt_pk_bf16_f32 v137, v113, s0
	v_mul_f32_e32 v113, 0x4b800000, v112
	v_cmp_gt_f32_e32 vcc, s80, v112
	v_mov_b32_e32 v34, v51
	v_mov_b32_e32 v140, v66
	v_cndmask_b32_e32 v112, v112, v113, vcc
	v_rsq_f32_e32 v151, v112
	v_and_or_b32 v112, v152, 62, v187
	v_lshlrev_b32_e32 v113, 2, v112
	ds_bpermute_b32 v138, v113, v132
	ds_bpermute_b32 v112, v113, v133
	v_mov_b32_e32 v141, v82
	v_mov_b32_e32 v82, v67
	s_waitcnt lgkmcnt(3)
	v_pk_mul_f32 v[34:35], v[34:35], v[2:3] op_sel_hi:[1,0]
	s_waitcnt lgkmcnt(1)
	v_pk_mul_f32 v[142:143], v[142:143], v[138:139] op_sel_hi:[1,0]
	v_mov_b32_e32 v18, v3
	s_waitcnt lgkmcnt(0)
	v_pk_fma_f32 v[140:141], v[140:141], v[112:113], v[142:143] op_sel_hi:[1,0,1] neg_lo:[0,0,1] neg_hi:[0,0,1]
	v_mov_b32_e32 v146, v114
	v_mov_b32_e32 v147, v98
	v_pk_mul_f32 v[138:139], v[148:149], v[138:139] op_sel_hi:[1,0]
	v_pk_fma_f32 v[66:67], v[82:83], v[50:51], v[34:35] op_sel_hi:[1,0,1] neg_lo:[0,0,1] neg_hi:[0,0,1]
	v_mov_b32_e32 v98, v115
	v_pk_mul_f32 v[2:3], v[18:19], v[2:3] op_sel_hi:[1,0]
	v_pk_mul_f32 v[142:143], v[140:141], v[140:141]
	v_pk_fma_f32 v[112:113], v[146:147], v[112:113], v[138:139] op_sel_hi:[1,0,1] neg_lo:[0,0,1] neg_hi:[0,0,1]
	v_pk_mul_f32 v[34:35], v[66:67], v[66:67]
	v_pk_fma_f32 v[50:51], v[98:99], v[50:51], v[2:3] op_sel_hi:[1,0,1] neg_lo:[0,0,1] neg_hi:[0,0,1]
	v_pk_mul_f32 v[138:139], v[112:113], v[112:113]
	v_pk_mul_f32 v[2:3], v[50:51], v[50:51]
	v_mov_b32_e32 v18, v34
	v_mov_b32_e32 v19, v142
	v_mov_b32_e32 v142, v35
	v_pk_add_f32 v[18:19], v[18:19], v[142:143]
	v_mov_b32_e32 v34, v3
	v_mov_b32_e32 v35, v139
	v_pk_add_f32 v[18:19], v[34:35], v[18:19]
	v_mov_b32_e32 v3, v138
	v_pk_add_f32 v[2:3], v[2:3], v[18:19]
	ds_bpermute_b32 v19, v48, v3
	ds_bpermute_b32 v18, v48, v2
	v_mul_f32_e32 v35, 0x45800000, v151
	v_cndmask_b32_e32 v35, v151, v35, vcc
	v_mul_f32_e32 v34, v136, v81
	v_mul_f32_e32 v81, v144, v35
	s_waitcnt lgkmcnt(0)
	v_pk_add_f32 v[18:19], v[2:3], v[18:19]
	ds_bpermute_b32 v83, v49, v19
	ds_bpermute_b32 v82, v49, v18
	v_add_u32_e32 v2, v150, v191
	v_mad_i64_i32 v[2:3], s[0:1], v2, s77, v[16:17]
	v_mul_f32_e32 v81, v131, v81
	s_waitcnt lgkmcnt(0)
	v_pk_add_f32 v[18:19], v[18:19], v[82:83]
	ds_bpermute_b32 v83, v64, v19
	ds_bpermute_b32 v82, v64, v18
	v_cvt_pk_bf16_f32 v81, v81, s0
	global_store_short v[2:3], v81, off
	v_mul_f32_e32 v81, v145, v35
	v_mul_f32_e32 v81, v130, v81
	s_waitcnt lgkmcnt(0)
; DI u16 f2bf(float a) { return (u16)(pk2(a, 0.f) & 0xffffu); }
; DI int crow(int i, int h) { return (i & 3) + 8 * (i >> 2) + 4 * h; }
; __device__ __forceinline__ void attn_item_A(const Params& p, int layer, int head, int q0u, char* lds) {
;     ...
; #pragma unroll
;   for (int e = 0; e < 16; ++e) {
;     const int qq = crow(e, h_e);
;     const float ia = __shfl(iA, qq), ib = __shfl(iB, qq);
;     float ov[4];
;     float ss = 0.f;
; #pragma unroll
;     for (int d = 0; d < 4; ++d) { ov[d] = o1[d][e] * ia - o2[d][e] * ib; ss += ov[d] * ov[d]; }
; #pragma unroll
;     for (int x = 16; x >= 1; x >>= 1) ss += __shfl_xor(ss, x);
;     const float rs = rsqrtf(ss * (1.f / 128.f) + LN_EPS);
;     const size_t rowoff = (size_t)(orow0 + qq) * LDX + ocol + r_e;
; #pragma unroll
;     for (int d = 0; d < 4; ++d) Mx[rowoff + d * 32] = f2bf(ov[d] * rs * sw[d]);
;   }
	v_pk_add_f32 v[18:19], v[18:19], v[82:83]
	ds_bpermute_b32 v83, v65, v19
	ds_bpermute_b32 v82, v65, v18
	v_cvt_pk_bf16_f32 v81, v81, s0
	global_store_short v[2:3], v81, off offset:64
	v_mul_f32_e32 v81, v97, v35
	v_mul_f32_e32 v81, v129, v81
	s_waitcnt lgkmcnt(0)
	v_pk_add_f32 v[18:19], v[18:19], v[82:83]
	ds_bpermute_b32 v83, v80, v19
	ds_bpermute_b32 v82, v80, v18
	v_cvt_pk_bf16_f32 v81, v81, s0
	global_store_short v[2:3], v81, off offset:128
	v_mov_b32_e32 v136, v116
	v_add_u32_e32 v116, 9, v134
	s_waitcnt lgkmcnt(0)
	v_pk_add_f32 v[18:19], v[18:19], v[82:83]
	v_mov_b32_e32 v138, v4
	v_pk_fma_f32 v[82:83], v[18:19], s[28:29], v[32:33] op_sel_hi:[1,0,0]
	v_and_or_b32 v4, v116, 61, v187
	v_mul_f32_e32 v18, 0x4b800000, v83
	v_cmp_gt_f32_e32 vcc, s80, v83
	v_mov_b32_e32 v139, v20
	v_lshlrev_b32_e32 v20, 2, v4
	v_cndmask_b32_e32 v18, v83, v18, vcc
	v_rsq_f32_e32 v81, v18
	v_add_u32_e32 v18, v152, v191
	v_mad_i64_i32 v[18:19], s[0:1], v18, s77, v[16:17]
	v_mul_f32_e32 v83, 0x45800000, v81
	v_cndmask_b32_e32 v81, v81, v83, vcc
	v_mul_f32_e32 v83, v140, v81
	v_mul_f32_e32 v83, v131, v83
	v_cvt_pk_bf16_f32 v83, v83, s0
	global_store_short v[18:19], v83, off
	v_mul_f32_e32 v83, v141, v81
	v_mul_f32_e32 v83, v130, v83
	v_cvt_pk_bf16_f32 v83, v83, s0
	global_store_short v[18:19], v83, off offset:64
	v_mul_f32_e32 v83, v113, v81
	v_mul_f32_e32 v83, v129, v83
	v_cvt_pk_bf16_f32 v113, v83, s0
	v_mul_f32_e32 v83, 0x4b800000, v82
	v_cmp_gt_f32_e32 vcc, s80, v82
	v_add_u32_e32 v141, 8, v134
	v_mul_f32_e32 v35, v96, v35
	v_cndmask_b32_e32 v82, v82, v83, vcc
	v_rsq_f32_e32 v140, v82
	v_and_or_b32 v82, v141, 60, v187
	v_lshlrev_b32_e32 v83, 2, v82
	ds_bpermute_b32 v96, v83, v132
	ds_bpermute_b32 v4, v20, v132
	ds_bpermute_b32 v82, v83, v133
	v_mov_b32_e32 v114, v52
	ds_bpermute_b32 v52, v20, v133
	v_mov_b32_e32 v115, v36
	v_mov_b32_e32 v36, v53
	v_mov_b32_e32 v98, v68
	v_mov_b32_e32 v99, v84
	s_waitcnt lgkmcnt(3)
	v_pk_mul_f32 v[114:115], v[114:115], v[96:97] op_sel_hi:[1,0]
	v_mov_b32_e32 v84, v69
	s_waitcnt lgkmcnt(2)
	v_pk_mul_f32 v[36:37], v[36:37], v[4:5] op_sel_hi:[1,0]
	v_mov_b32_e32 v20, v5
	global_store_short v[0:1], v137, off offset:128
	s_waitcnt lgkmcnt(1)
	v_pk_fma_f32 v[98:99], v[98:99], v[82:83], v[114:115] op_sel_hi:[1,0,1] neg_lo:[0,0,1] neg_hi:[0,0,1]
	v_mov_b32_e32 v137, v100
	v_pk_mul_f32 v[96:97], v[138:139], v[96:97] op_sel_hi:[1,0]
	s_waitcnt lgkmcnt(0)
	v_pk_fma_f32 v[68:69], v[84:85], v[52:53], v[36:37] op_sel_hi:[1,0,1] neg_lo:[0,0,1] neg_hi:[0,0,1]
	v_mov_b32_e32 v100, v117
	v_pk_mul_f32 v[4:5], v[20:21], v[4:5] op_sel_hi:[1,0]
	v_pk_mul_f32 v[114:115], v[98:99], v[98:99]
	v_pk_fma_f32 v[82:83], v[136:137], v[82:83], v[96:97] op_sel_hi:[1,0,1] neg_lo:[0,0,1] neg_hi:[0,0,1]
	v_pk_mul_f32 v[36:37], v[68:69], v[68:69]
	v_pk_fma_f32 v[52:53], v[100:101], v[52:53], v[4:5] op_sel_hi:[1,0,1] neg_lo:[0,0,1] neg_hi:[0,0,1]
	v_pk_mul_f32 v[96:97], v[82:83], v[82:83]
	v_pk_mul_f32 v[4:5], v[52:53], v[52:53]
	v_mov_b32_e32 v20, v36
	v_mov_b32_e32 v21, v114
	v_mov_b32_e32 v114, v37
	v_pk_add_f32 v[20:21], v[20:21], v[114:115]
	v_mov_b32_e32 v36, v5
	v_mov_b32_e32 v37, v97
	v_pk_add_f32 v[20:21], v[36:37], v[20:21]
	v_mov_b32_e32 v5, v96
	v_pk_add_f32 v[4:5], v[4:5], v[20:21]
	ds_bpermute_b32 v21, v48, v5
	ds_bpermute_b32 v20, v48, v4
	v_mul_f32_e32 v37, 0x45800000, v140
	v_cndmask_b32_e32 v37, v140, v37, vcc
	v_mul_f32_e32 v66, v66, v37
	v_mul_f32_e32 v66, v131, v66
	s_waitcnt lgkmcnt(0)
	v_pk_add_f32 v[20:21], v[4:5], v[20:21]
	ds_bpermute_b32 v85, v49, v21
	ds_bpermute_b32 v84, v49, v20
	v_add_u32_e32 v4, v135, v191
	v_mad_i64_i32 v[4:5], s[0:1], v4, s77, v[16:17]
	v_mul_f32_e32 v36, v112, v81
	s_waitcnt lgkmcnt(0)
	v_pk_add_f32 v[20:21], v[20:21], v[84:85]
	ds_bpermute_b32 v85, v64, v21
	ds_bpermute_b32 v84, v64, v20
	v_cvt_pk_bf16_f32 v66, v66, s0
	global_store_short v[4:5], v66, off
	v_mul_f32_e32 v81, v67, v37
	v_mul_f32_e32 v51, v51, v37
	s_waitcnt lgkmcnt(0)
	v_pk_add_f32 v[20:21], v[20:21], v[84:85]
	ds_bpermute_b32 v67, v65, v21
	ds_bpermute_b32 v66, v65, v20
	v_mul_f32_e32 v51, v129, v51
	v_cvt_pk_bf16_f32 v51, v51, s0
	global_store_short v[4:5], v51, off offset:128
	v_mul_f32_e32 v37, v50, v37
	s_waitcnt lgkmcnt(0)
	v_pk_add_f32 v[20:21], v[20:21], v[66:67]
	ds_bpermute_b32 v67, v80, v21
	ds_bpermute_b32 v66, v80, v20
	v_mul_f32_e32 v81, v130, v81
	v_cvt_pk_bf16_f32 v81, v81, s0
	global_store_short v[4:5], v81, off offset:64
	global_store_short v[18:19], v113, off offset:128
	s_waitcnt lgkmcnt(0)
	v_pk_add_f32 v[20:21], v[20:21], v[66:67]
	v_add_u32_e32 v113, 10, v134
	v_pk_fma_f32 v[50:51], v[20:21], s[28:29], v[32:33] op_sel_hi:[1,0,0]
	v_mov_b32_e32 v96, v54
	v_mul_f32_e32 v20, 0x4b800000, v51
	v_cmp_gt_f32_e32 vcc, s80, v51
	v_mov_b32_e32 v97, v38
	v_mov_b32_e32 v100, v6
	v_cndmask_b32_e32 v20, v51, v20, vcc
	v_rsq_f32_e32 v51, v20
	v_add_u32_e32 v20, v141, v191
	v_mad_i64_i32 v[20:21], s[0:1], v20, s77, v[16:17]
	v_mul_f32_e32 v66, 0x45800000, v51
	v_cndmask_b32_e32 v81, v51, v66, vcc
	v_mul_f32_e32 v51, v98, v81
	v_mul_f32_e32 v51, v131, v51
	v_cvt_pk_bf16_f32 v51, v51, s0
	global_store_short v[20:21], v51, off
	v_mul_f32_e32 v51, v99, v81
	v_mul_f32_e32 v51, v130, v51
	v_cvt_pk_bf16_f32 v51, v51, s0
	global_store_short v[20:21], v51, off offset:64
	v_mul_f32_e32 v51, v83, v81
	v_mul_f32_e32 v51, v129, v51
	v_cvt_pk_bf16_f32 v83, v51, s0
	v_mul_f32_e32 v51, 0x4b800000, v50
	v_cmp_gt_f32_e32 vcc, s80, v50
	v_mov_b32_e32 v101, v22
	v_mov_b32_e32 v84, v70
	v_cndmask_b32_e32 v50, v50, v51, vcc
	v_rsq_f32_e32 v112, v50
	v_and_or_b32 v50, v113, 62, v187
	v_lshlrev_b32_e32 v51, 2, v50
	ds_bpermute_b32 v66, v51, v132
	ds_bpermute_b32 v50, v51, v133
	v_mov_b32_e32 v85, v86
	v_mov_b32_e32 v98, v118
	v_mov_b32_e32 v99, v102
	s_waitcnt lgkmcnt(1)
; DI u16 f2bf(float a) { return (u16)(pk2(a, 0.f) & 0xffffu); }
; DI int crow(int i, int h) { return (i & 3) + 8 * (i >> 2) + 4 * h; }
; __device__ __forceinline__ void attn_item_A(const Params& p, int layer, int head, int q0u, char* lds) {
;     ...
; #pragma unroll
;   for (int e = 0; e < 16; ++e) {
;     const int qq = crow(e, h_e);
;     const float ia = __shfl(iA, qq), ib = __shfl(iB, qq);
;     float ov[4];
;     float ss = 0.f;
; #pragma unroll
;     for (int d = 0; d < 4; ++d) { ov[d] = o1[d][e] * ia - o2[d][e] * ib; ss += ov[d] * ov[d]; }
; #pragma unroll
;     for (int x = 16; x >= 1; x >>= 1) ss += __shfl_xor(ss, x);
;     const float rs = rsqrtf(ss * (1.f / 128.f) + LN_EPS);
;     const size_t rowoff = (size_t)(orow0 + qq) * LDX + ocol + r_e;
; #pragma unroll
;     for (int d = 0; d < 4; ++d) Mx[rowoff + d * 32] = f2bf(ov[d] * rs * sw[d]);
;   }
	v_pk_mul_f32 v[96:97], v[96:97], v[66:67] op_sel_hi:[1,0]
	v_pk_mul_f32 v[66:67], v[100:101], v[66:67] op_sel_hi:[1,0]
	s_waitcnt lgkmcnt(0)
	v_pk_fma_f32 v[84:85], v[84:85], v[50:51], v[96:97] op_sel_hi:[1,0,1] neg_lo:[0,0,1] neg_hi:[0,0,1]
	v_pk_fma_f32 v[50:51], v[98:99], v[50:51], v[66:67] op_sel_hi:[1,0,1] neg_lo:[0,0,1] neg_hi:[0,0,1]
	v_add_u32_e32 v98, 11, v134
	v_and_or_b32 v6, v98, 63, v187
	v_lshlrev_b32_e32 v22, 2, v6
	ds_bpermute_b32 v6, v22, v132
	ds_bpermute_b32 v54, v22, v133
	v_mov_b32_e32 v38, v55
	v_mov_b32_e32 v86, v71
	v_mov_b32_e32 v22, v7
	s_waitcnt lgkmcnt(1)
	v_pk_mul_f32 v[38:39], v[38:39], v[6:7] op_sel_hi:[1,0]
	v_mov_b32_e32 v102, v119
	s_waitcnt lgkmcnt(0)
	v_pk_fma_f32 v[70:71], v[86:87], v[54:55], v[38:39] op_sel_hi:[1,0,1] neg_lo:[0,0,1] neg_hi:[0,0,1]
	v_pk_mul_f32 v[6:7], v[22:23], v[6:7] op_sel_hi:[1,0]
	v_pk_mul_f32 v[96:97], v[84:85], v[84:85]
	v_pk_mul_f32 v[38:39], v[70:71], v[70:71]
	v_pk_fma_f32 v[54:55], v[102:103], v[54:55], v[6:7] op_sel_hi:[1,0,1] neg_lo:[0,0,1] neg_hi:[0,0,1]
	v_pk_mul_f32 v[66:67], v[50:51], v[50:51]
	v_pk_mul_f32 v[6:7], v[54:55], v[54:55]
	v_mov_b32_e32 v22, v38
	v_mov_b32_e32 v23, v96
	v_mov_b32_e32 v96, v39
	v_pk_add_f32 v[22:23], v[22:23], v[96:97]
	v_mov_b32_e32 v38, v7
	v_mov_b32_e32 v39, v67
	v_pk_add_f32 v[22:23], v[38:39], v[22:23]
	v_mov_b32_e32 v7, v66
	v_pk_add_f32 v[6:7], v[6:7], v[22:23]
	ds_bpermute_b32 v23, v48, v7
	ds_bpermute_b32 v22, v48, v6
	v_mul_f32_e32 v39, 0x45800000, v112
	v_cndmask_b32_e32 v39, v112, v39, vcc
	v_mul_f32_e32 v68, v68, v39
	v_mul_f32_e32 v53, v53, v39
	s_waitcnt lgkmcnt(0)
	v_pk_add_f32 v[22:23], v[6:7], v[22:23]
	ds_bpermute_b32 v67, v49, v23
	ds_bpermute_b32 v66, v49, v22
	v_add_u32_e32 v6, v116, v191
	v_mad_i64_i32 v[6:7], s[0:1], v6, s77, v[16:17]
	v_mul_f32_e32 v68, v131, v68
	s_waitcnt lgkmcnt(0)
	v_pk_add_f32 v[22:23], v[22:23], v[66:67]
	ds_bpermute_b32 v67, v64, v23
	ds_bpermute_b32 v66, v64, v22
	v_mul_f32_e32 v53, v129, v53
	v_cvt_pk_bf16_f32 v68, v68, s0
	v_cvt_pk_bf16_f32 v53, v53, s0
	global_store_short v[6:7], v68, off
	s_waitcnt lgkmcnt(0)
	v_pk_add_f32 v[22:23], v[22:23], v[66:67]
	ds_bpermute_b32 v67, v65, v23
	ds_bpermute_b32 v66, v65, v22
	v_mul_f32_e32 v68, v69, v39
	global_store_short v[6:7], v53, off offset:128
	v_mul_f32_e32 v39, v52, v39
	v_mul_f32_e32 v38, v82, v81
	s_waitcnt lgkmcnt(0)
	v_pk_add_f32 v[22:23], v[22:23], v[66:67]
	ds_bpermute_b32 v67, v80, v23
	ds_bpermute_b32 v66, v80, v22
	v_mul_f32_e32 v68, v130, v68
	v_cvt_pk_bf16_f32 v68, v68, s0
	v_add_u32_e32 v97, 16, v134
	global_store_short v[20:21], v83, off offset:128
	s_waitcnt lgkmcnt(0)
	v_pk_add_f32 v[22:23], v[22:23], v[66:67]
	v_mov_b32_e32 v82, v56
	v_pk_fma_f32 v[52:53], v[22:23], s[28:29], v[32:33] op_sel_hi:[1,0,0]
	v_mov_b32_e32 v83, v40
	v_mul_f32_e32 v22, 0x4b800000, v53
	v_cmp_gt_f32_e32 vcc, s80, v53
	v_mov_b32_e32 v86, v8
	v_mov_b32_e32 v87, v24
	v_cndmask_b32_e32 v22, v53, v22, vcc
	v_rsq_f32_e32 v53, v22
	v_add_u32_e32 v22, v113, v191
	v_mad_i64_i32 v[22:23], s[0:1], v22, s77, v[16:17]
	v_mul_f32_e32 v66, 0x45800000, v53
	v_cndmask_b32_e32 v81, v53, v66, vcc
	v_mul_f32_e32 v53, v84, v81
	v_mul_f32_e32 v53, v131, v53
	v_cvt_pk_bf16_f32 v53, v53, s0
	global_store_short v[22:23], v53, off
	v_mul_f32_e32 v53, v85, v81
	v_mul_f32_e32 v53, v130, v53
	v_cvt_pk_bf16_f32 v53, v53, s0
	global_store_short v[22:23], v53, off offset:64
	v_mul_f32_e32 v53, 0x4b800000, v52
	v_cmp_gt_f32_e32 vcc, s80, v52
	global_store_short v[6:7], v68, off offset:64
	v_mov_b32_e32 v68, v72
	v_cndmask_b32_e32 v52, v52, v53, vcc
	v_rsq_f32_e32 v96, v52
	v_and_or_b32 v52, v97, 60, v187
	v_lshlrev_b32_e32 v53, 2, v52
	ds_bpermute_b32 v66, v53, v132
	ds_bpermute_b32 v52, v53, v133
	v_mov_b32_e32 v69, v88
	v_mov_b32_e32 v84, v120
	v_mov_b32_e32 v85, v104
	s_waitcnt lgkmcnt(1)
	v_pk_mul_f32 v[82:83], v[82:83], v[66:67] op_sel_hi:[1,0]
	v_pk_mul_f32 v[66:67], v[86:87], v[66:67] op_sel_hi:[1,0]
	s_waitcnt lgkmcnt(0)
	v_pk_fma_f32 v[68:69], v[68:69], v[52:53], v[82:83] op_sel_hi:[1,0,1] neg_lo:[0,0,1] neg_hi:[0,0,1]
	v_pk_fma_f32 v[52:53], v[84:85], v[52:53], v[66:67] op_sel_hi:[1,0,1] neg_lo:[0,0,1] neg_hi:[0,0,1]
	v_add_u32_e32 v84, 17, v134
	v_and_or_b32 v8, v84, 61, v187
	v_lshlrev_b32_e32 v24, 2, v8
	ds_bpermute_b32 v8, v24, v132
	ds_bpermute_b32 v56, v24, v133
	v_mov_b32_e32 v40, v57
	v_mov_b32_e32 v88, v73
	v_mov_b32_e32 v24, v9
	s_waitcnt lgkmcnt(1)
	v_pk_mul_f32 v[40:41], v[40:41], v[8:9] op_sel_hi:[1,0]
	v_mov_b32_e32 v104, v121
	s_waitcnt lgkmcnt(0)
	v_pk_fma_f32 v[72:73], v[88:89], v[56:57], v[40:41] op_sel_hi:[1,0,1] neg_lo:[0,0,1] neg_hi:[0,0,1]
	v_pk_mul_f32 v[8:9], v[24:25], v[8:9] op_sel_hi:[1,0]
	v_pk_mul_f32 v[82:83], v[68:69], v[68:69]
	v_pk_mul_f32 v[40:41], v[72:73], v[72:73]
	v_pk_fma_f32 v[56:57], v[104:105], v[56:57], v[8:9] op_sel_hi:[1,0,1] neg_lo:[0,0,1] neg_hi:[0,0,1]
	v_pk_mul_f32 v[66:67], v[52:53], v[52:53]
	v_pk_mul_f32 v[8:9], v[56:57], v[56:57]
	v_mov_b32_e32 v24, v40
	v_mov_b32_e32 v25, v82
	v_mov_b32_e32 v82, v41
	v_pk_add_f32 v[24:25], v[24:25], v[82:83]
	v_mov_b32_e32 v40, v9
	v_mov_b32_e32 v41, v67
	v_pk_add_f32 v[24:25], v[40:41], v[24:25]
	v_mov_b32_e32 v9, v66
	v_pk_add_f32 v[8:9], v[8:9], v[24:25]
	ds_bpermute_b32 v25, v48, v9
	ds_bpermute_b32 v24, v48, v8
	v_mul_f32_e32 v51, v51, v81
	v_mul_f32_e32 v51, v129, v51
	v_cvt_pk_bf16_f32 v51, v51, s0
	global_store_short v[22:23], v51, off offset:128
	s_waitcnt lgkmcnt(0)
	v_pk_add_f32 v[24:25], v[8:9], v[24:25]
	v_mul_f32_e32 v40, v50, v81
	ds_bpermute_b32 v51, v49, v25
	ds_bpermute_b32 v50, v49, v24
	v_mul_f32_e32 v41, 0x45800000, v96
	v_cndmask_b32_e32 v41, v96, v41, vcc
	v_add_u32_e32 v8, v98, v191
	v_mul_f32_e32 v66, v70, v41
	s_waitcnt lgkmcnt(0)
; DI u16 f2bf(float a) { return (u16)(pk2(a, 0.f) & 0xffffu); }
; DI int crow(int i, int h) { return (i & 3) + 8 * (i >> 2) + 4 * h; }
; __device__ __forceinline__ void attn_item_A(const Params& p, int layer, int head, int q0u, char* lds) {
;     ...
; #pragma unroll
;   for (int e = 0; e < 16; ++e) {
;     const int qq = crow(e, h_e);
;     const float ia = __shfl(iA, qq), ib = __shfl(iB, qq);
;     float ov[4];
;     float ss = 0.f;
; #pragma unroll
;     for (int d = 0; d < 4; ++d) { ov[d] = o1[d][e] * ia - o2[d][e] * ib; ss += ov[d] * ov[d]; }
; #pragma unroll
;     for (int x = 16; x >= 1; x >>= 1) ss += __shfl_xor(ss, x);
;     const float rs = rsqrtf(ss * (1.f / 128.f) + LN_EPS);
;     const size_t rowoff = (size_t)(orow0 + qq) * LDX + ocol + r_e;
; #pragma unroll
;     for (int d = 0; d < 4; ++d) Mx[rowoff + d * 32] = f2bf(ov[d] * rs * sw[d]);
;   }
	v_pk_add_f32 v[24:25], v[24:25], v[50:51]
	ds_bpermute_b32 v51, v64, v25
	ds_bpermute_b32 v50, v64, v24
	v_mad_i64_i32 v[8:9], s[0:1], v8, s77, v[16:17]
	v_mul_f32_e32 v66, v131, v66
	s_nop 0
	v_cvt_pk_bf16_f32 v66, v66, s0
	s_waitcnt lgkmcnt(0)
	v_pk_add_f32 v[24:25], v[24:25], v[50:51]
	ds_bpermute_b32 v51, v65, v25
	ds_bpermute_b32 v50, v65, v24
	global_store_short v[8:9], v66, off
	v_mul_f32_e32 v66, v71, v41
	v_mul_f32_e32 v55, v55, v41
	v_mul_f32_e32 v41, v54, v41
	s_waitcnt lgkmcnt(0)
	v_pk_add_f32 v[24:25], v[24:25], v[50:51]
	ds_bpermute_b32 v51, v80, v25
	ds_bpermute_b32 v50, v80, v24
	v_mul_f32_e32 v66, v130, v66
	v_mul_f32_e32 v55, v129, v55
	v_cvt_pk_bf16_f32 v66, v66, s0
	v_cvt_pk_bf16_f32 v55, v55, s0
	s_waitcnt lgkmcnt(0)
	v_pk_add_f32 v[24:25], v[24:25], v[50:51]
	v_add_u32_e32 v86, 18, v134
	v_pk_fma_f32 v[50:51], v[24:25], s[28:29], v[32:33] op_sel_hi:[1,0,0]
	global_store_short v[8:9], v66, off offset:64
	v_mul_f32_e32 v24, 0x4b800000, v51
	v_cmp_gt_f32_e32 vcc, s80, v51
	v_mov_b32_e32 v66, v74
	v_add_u32_e32 v74, 19, v134
	v_cndmask_b32_e32 v24, v51, v24, vcc
	v_rsq_f32_e32 v51, v24
	v_add_u32_e32 v24, v97, v191
	v_mad_i64_i32 v[24:25], s[0:1], v24, s77, v[16:17]
	v_mul_f32_e32 v54, 0x45800000, v51
	v_cndmask_b32_e32 v81, v51, v54, vcc
	v_mul_f32_e32 v51, v68, v81
	v_mul_f32_e32 v51, v131, v51
	v_cvt_pk_bf16_f32 v51, v51, s0
	global_store_short v[24:25], v51, off
	v_mul_f32_e32 v51, v69, v81
	v_mul_f32_e32 v51, v130, v51
	v_cvt_pk_bf16_f32 v51, v51, s0
	global_store_short v[24:25], v51, off offset:64
	v_mul_f32_e32 v51, v53, v81
	v_mul_f32_e32 v51, v129, v51
	v_cvt_pk_bf16_f32 v53, v51, s0
	v_mul_f32_e32 v51, 0x4b800000, v50
	v_cmp_gt_f32_e32 vcc, s80, v50
	v_mov_b32_e32 v82, v10
	v_and_or_b32 v10, v74, 63, v187
	v_cndmask_b32_e32 v50, v50, v51, vcc
	v_rsq_f32_e32 v85, v50
	v_and_or_b32 v50, v86, 62, v187
	v_lshlrev_b32_e32 v51, 2, v50
	ds_bpermute_b32 v54, v51, v132
	ds_bpermute_b32 v50, v51, v133
	v_mov_b32_e32 v68, v58
	v_mov_b32_e32 v69, v42
	v_mov_b32_e32 v83, v26
	v_lshlrev_b32_e32 v26, 2, v10
	global_store_short v[8:9], v55, off offset:128
	v_mov_b32_e32 v67, v90
	s_waitcnt lgkmcnt(1)
	v_pk_mul_f32 v[68:69], v[68:69], v[54:55] op_sel_hi:[1,0]
	v_mov_b32_e32 v70, v122
	v_mov_b32_e32 v71, v106
	v_pk_mul_f32 v[54:55], v[82:83], v[54:55] op_sel_hi:[1,0]
	ds_bpermute_b32 v10, v26, v132
	s_waitcnt lgkmcnt(1)
	v_pk_fma_f32 v[66:67], v[66:67], v[50:51], v[68:69] op_sel_hi:[1,0,1] neg_lo:[0,0,1] neg_hi:[0,0,1]
	v_pk_fma_f32 v[50:51], v[70:71], v[50:51], v[54:55] op_sel_hi:[1,0,1] neg_lo:[0,0,1] neg_hi:[0,0,1]
	ds_bpermute_b32 v54, v26, v133
	v_mov_b32_e32 v42, v59
	v_mov_b32_e32 v90, v75
	s_waitcnt lgkmcnt(1)
	v_pk_mul_f32 v[42:43], v[42:43], v[10:11] op_sel_hi:[1,0]
	v_mov_b32_e32 v26, v11
	s_waitcnt lgkmcnt(0)
	v_pk_fma_f32 v[42:43], v[90:91], v[54:55], v[42:43] op_sel_hi:[1,0,1] neg_lo:[0,0,1] neg_hi:[0,0,1]
	v_mov_b32_e32 v106, v123
	v_pk_mul_f32 v[10:11], v[26:27], v[10:11] op_sel_hi:[1,0]
	v_pk_mul_f32 v[68:69], v[66:67], v[66:67]
	v_pk_mul_f32 v[58:59], v[42:43], v[42:43]
	v_pk_fma_f32 v[54:55], v[106:107], v[54:55], v[10:11] op_sel_hi:[1,0,1] neg_lo:[0,0,1] neg_hi:[0,0,1]
	v_pk_mul_f32 v[70:71], v[50:51], v[50:51]
	v_pk_mul_f32 v[10:11], v[54:55], v[54:55]
	v_mov_b32_e32 v26, v58
	v_mov_b32_e32 v27, v68
	v_mov_b32_e32 v68, v59
	v_pk_add_f32 v[26:27], v[26:27], v[68:69]
	v_mov_b32_e32 v58, v11
	v_mov_b32_e32 v59, v71
	v_pk_add_f32 v[26:27], v[58:59], v[26:27]
	v_mov_b32_e32 v11, v70
	v_pk_add_f32 v[10:11], v[10:11], v[26:27]
	ds_bpermute_b32 v27, v48, v11
	ds_bpermute_b32 v26, v48, v10
	v_mul_f32_e32 v75, v52, v81
	v_mul_f32_e32 v52, 0x45800000, v85
	global_store_short v[24:25], v53, off offset:128
	v_cndmask_b32_e32 v58, v85, v52, vcc
	s_waitcnt lgkmcnt(0)
	v_pk_add_f32 v[26:27], v[10:11], v[26:27]
	ds_bpermute_b32 v53, v49, v27
	ds_bpermute_b32 v52, v49, v26
	v_add_u32_e32 v10, v84, v191
	v_mul_f32_e32 v59, v72, v58
	v_mad_i64_i32 v[10:11], s[0:1], v10, s77, v[16:17]
	s_waitcnt lgkmcnt(0)
	v_pk_add_f32 v[26:27], v[26:27], v[52:53]
	ds_bpermute_b32 v53, v64, v27
	ds_bpermute_b32 v52, v64, v26
	v_mul_f32_e32 v59, v131, v59
	v_cvt_pk_bf16_f32 v59, v59, s0
	v_mul_f32_e32 v72, v56, v58
	global_store_short v[10:11], v59, off
	s_waitcnt lgkmcnt(0)
	v_pk_add_f32 v[26:27], v[26:27], v[52:53]
	ds_bpermute_b32 v53, v65, v27
	ds_bpermute_b32 v52, v65, v26
	v_mul_f32_e32 v59, v73, v58
	v_mul_f32_e32 v57, v57, v58
	v_mul_f32_e32 v59, v130, v59
	v_mul_f32_e32 v57, v129, v57
	s_waitcnt lgkmcnt(0)
	v_pk_add_f32 v[26:27], v[26:27], v[52:53]
	ds_bpermute_b32 v53, v80, v27
	ds_bpermute_b32 v52, v80, v26
	v_cvt_pk_bf16_f32 v59, v59, s0
	v_cvt_pk_bf16_f32 v57, v57, s0
	v_add_u32_e32 v82, 24, v134
	v_mov_b32_e32 v70, v12
	s_waitcnt lgkmcnt(0)
	v_pk_add_f32 v[26:27], v[26:27], v[52:53]
	v_mov_b32_e32 v71, v28
	v_pk_fma_f32 v[52:53], v[26:27], s[28:29], v[32:33] op_sel_hi:[1,0,0]
	global_store_short v[10:11], v57, off offset:128
	v_mul_f32_e32 v26, 0x4b800000, v53
	v_cmp_gt_f32_e32 vcc, s80, v53
	global_store_short v[10:11], v59, off offset:64
	v_mov_b32_e32 v58, v76
	v_cndmask_b32_e32 v26, v53, v26, vcc
	v_rsq_f32_e32 v53, v26
	v_add_u32_e32 v26, v86, v191
	v_mad_i64_i32 v[26:27], s[0:1], v26, s77, v[16:17]
	v_mul_f32_e32 v56, 0x45800000, v53
	v_cndmask_b32_e32 v73, v53, v56, vcc
	v_mul_f32_e32 v53, v66, v73
	v_mul_f32_e32 v53, v131, v53
	v_cvt_pk_bf16_f32 v53, v53, s0
	global_store_short v[26:27], v53, off
	v_mul_f32_e32 v53, v67, v73
	v_mul_f32_e32 v53, v130, v53
	v_cvt_pk_bf16_f32 v53, v53, s0
	global_store_short v[26:27], v53, off offset:64
	v_mul_f32_e32 v53, 0x4b800000, v52
	v_cmp_gt_f32_e32 vcc, s80, v52
	v_mov_b32_e32 v66, v60
	v_mov_b32_e32 v67, v44
	v_cndmask_b32_e32 v52, v52, v53, vcc
	v_rsq_f32_e32 v81, v52
	v_and_or_b32 v52, v82, 60, v187
	v_lshlrev_b32_e32 v53, 2, v52
	ds_bpermute_b32 v56, v53, v132
	ds_bpermute_b32 v52, v53, v133
	v_mov_b32_e32 v59, v92
	v_mov_b32_e32 v68, v124
	v_mov_b32_e32 v69, v108
	s_waitcnt lgkmcnt(1)
; DI u16 f2bf(float a) { return (u16)(pk2(a, 0.f) & 0xffffu); }
; DI int crow(int i, int h) { return (i & 3) + 8 * (i >> 2) + 4 * h; }
; __device__ __forceinline__ void attn_item_A(const Params& p, int layer, int head, int q0u, char* lds) {
;     ...
; #pragma unroll
;   for (int e = 0; e < 16; ++e) {
;     const int qq = crow(e, h_e);
;     const float ia = __shfl(iA, qq), ib = __shfl(iB, qq);
;     float ov[4];
;     float ss = 0.f;
; #pragma unroll
;     for (int d = 0; d < 4; ++d) { ov[d] = o1[d][e] * ia - o2[d][e] * ib; ss += ov[d] * ov[d]; }
; #pragma unroll
;     for (int x = 16; x >= 1; x >>= 1) ss += __shfl_xor(ss, x);
;     const float rs = rsqrtf(ss * (1.f / 128.f) + LN_EPS);
;     const size_t rowoff = (size_t)(orow0 + qq) * LDX + ocol + r_e;
; #pragma unroll
;     for (int d = 0; d < 4; ++d) Mx[rowoff + d * 32] = f2bf(ov[d] * rs * sw[d]);
;   }
	v_pk_mul_f32 v[66:67], v[66:67], v[56:57] op_sel_hi:[1,0]
	v_pk_mul_f32 v[56:57], v[70:71], v[56:57] op_sel_hi:[1,0]
	v_add_u32_e32 v70, 25, v134
	v_and_or_b32 v12, v70, 61, v187
	v_lshlrev_b32_e32 v28, 2, v12
	ds_bpermute_b32 v12, v28, v132
	s_waitcnt lgkmcnt(1)
	v_pk_fma_f32 v[58:59], v[58:59], v[52:53], v[66:67] op_sel_hi:[1,0,1] neg_lo:[0,0,1] neg_hi:[0,0,1]
	v_pk_fma_f32 v[52:53], v[68:69], v[52:53], v[56:57] op_sel_hi:[1,0,1] neg_lo:[0,0,1] neg_hi:[0,0,1]
	ds_bpermute_b32 v56, v28, v133
	v_mov_b32_e32 v44, v61
	v_mov_b32_e32 v92, v77
	s_waitcnt lgkmcnt(1)
	v_pk_mul_f32 v[44:45], v[44:45], v[12:13] op_sel_hi:[1,0]
	v_mov_b32_e32 v28, v13
	s_waitcnt lgkmcnt(0)
	v_pk_fma_f32 v[44:45], v[92:93], v[56:57], v[44:45] op_sel_hi:[1,0,1] neg_lo:[0,0,1] neg_hi:[0,0,1]
	v_mov_b32_e32 v108, v125
	v_pk_mul_f32 v[12:13], v[28:29], v[12:13] op_sel_hi:[1,0]
	v_pk_mul_f32 v[66:67], v[58:59], v[58:59]
	v_pk_mul_f32 v[60:61], v[44:45], v[44:45]
	v_pk_fma_f32 v[28:29], v[108:109], v[56:57], v[12:13] op_sel_hi:[1,0,1] neg_lo:[0,0,1] neg_hi:[0,0,1]
	v_pk_mul_f32 v[68:69], v[52:53], v[52:53]
	v_pk_mul_f32 v[12:13], v[28:29], v[28:29]
	v_mov_b32_e32 v56, v60
	v_mov_b32_e32 v57, v66
	v_mov_b32_e32 v66, v61
	v_pk_add_f32 v[56:57], v[56:57], v[66:67]
	v_mov_b32_e32 v60, v13
	v_mov_b32_e32 v61, v69
	v_pk_add_f32 v[56:57], v[60:61], v[56:57]
	v_mov_b32_e32 v13, v68
	v_pk_add_f32 v[12:13], v[12:13], v[56:57]
	ds_bpermute_b32 v57, v48, v13
	ds_bpermute_b32 v56, v48, v12
	v_mul_f32_e32 v51, v51, v73
	v_mul_f32_e32 v51, v129, v51
	v_cvt_pk_bf16_f32 v51, v51, s0
	v_mul_f32_e32 v68, v50, v73
	v_mul_f32_e32 v50, 0x45800000, v81
	global_store_short v[26:27], v51, off offset:128
	v_cndmask_b32_e32 v60, v81, v50, vcc
	s_waitcnt lgkmcnt(0)
	v_pk_add_f32 v[50:51], v[12:13], v[56:57]
	ds_bpermute_b32 v57, v49, v51
	ds_bpermute_b32 v56, v49, v50
	v_add_u32_e32 v12, v74, v191
	v_mul_f32_e32 v42, v42, v60
	v_mad_i64_i32 v[12:13], s[0:1], v12, s77, v[16:17]
	s_waitcnt lgkmcnt(0)
	v_pk_add_f32 v[50:51], v[50:51], v[56:57]
	ds_bpermute_b32 v57, v64, v51
	ds_bpermute_b32 v56, v64, v50
	v_mul_f32_e32 v42, v131, v42
	v_cvt_pk_bf16_f32 v42, v42, s0
	global_store_short v[12:13], v42, off
	v_mul_f32_e32 v61, v43, v60
	s_waitcnt lgkmcnt(0)
	v_pk_add_f32 v[42:43], v[50:51], v[56:57]
	ds_bpermute_b32 v51, v65, v43
	ds_bpermute_b32 v50, v65, v42
	v_mul_f32_e32 v69, v54, v60
	v_mul_f32_e32 v55, v55, v60
	v_mul_f32_e32 v56, v130, v61
	v_mul_f32_e32 v55, v129, v55
	s_waitcnt lgkmcnt(0)
	v_pk_add_f32 v[42:43], v[42:43], v[50:51]
	ds_bpermute_b32 v51, v80, v43
	ds_bpermute_b32 v50, v80, v42
	v_cvt_pk_bf16_f32 v56, v56, s0
	v_cvt_pk_bf16_f32 v55, v55, s0
	global_load_dword v128, v210, s[54:55] offset:384
	v_add_u32_e32 v74, 26, v134
	s_waitcnt lgkmcnt(0)
	v_pk_add_f32 v[42:43], v[42:43], v[50:51]
	v_add_u32_e32 v76, 27, v134
	v_pk_fma_f32 v[42:43], v[42:43], s[28:29], v[32:33] op_sel_hi:[1,0,0]
	v_mov_b32_e32 v66, v14
	v_mul_f32_e32 v50, 0x4b800000, v43
	v_cmp_gt_f32_e32 vcc, s80, v43
	v_mov_b32_e32 v67, v30
	v_and_or_b32 v14, v76, 63, v187
	v_cndmask_b32_e32 v43, v43, v50, vcc
	v_rsq_f32_e32 v43, v43
	v_add_u32_e32 v50, v82, v191
	v_mad_i64_i32 v[50:51], s[0:1], v50, s77, v[16:17]
	v_mul_f32_e32 v54, 0x45800000, v43
	v_cndmask_b32_e32 v71, v43, v54, vcc
	v_mul_f32_e32 v43, v58, v71
	v_mul_f32_e32 v43, v131, v43
	v_cvt_pk_bf16_f32 v43, v43, s0
	global_store_short v[50:51], v43, off
	v_mul_f32_e32 v43, v59, v71
	v_mul_f32_e32 v43, v130, v43
	v_cvt_pk_bf16_f32 v43, v43, s0
	global_store_short v[50:51], v43, off offset:64
	v_mul_f32_e32 v43, v53, v71
	v_mul_f32_e32 v43, v129, v43
	v_cvt_pk_bf16_f32 v53, v43, s0
	v_mul_f32_e32 v43, 0x4b800000, v42
	v_cmp_gt_f32_e32 vcc, s80, v42
	v_mov_b32_e32 v58, v62
	v_mov_b32_e32 v59, v46
	v_cndmask_b32_e32 v42, v42, v43, vcc
	v_rsq_f32_e32 v73, v42
	v_and_or_b32 v42, v74, 62, v187
	v_lshlrev_b32_e32 v43, 2, v42
	ds_bpermute_b32 v54, v43, v132
	ds_bpermute_b32 v42, v43, v133
	global_store_short v[12:13], v56, off offset:64
	global_store_short v[12:13], v55, off offset:128
	v_mov_b32_e32 v56, v78
	v_mov_b32_e32 v57, v94
	s_waitcnt lgkmcnt(1)
	v_pk_mul_f32 v[58:59], v[58:59], v[54:55] op_sel_hi:[1,0]
	v_mov_b32_e32 v60, v126
	v_mov_b32_e32 v61, v110
	v_pk_mul_f32 v[54:55], v[66:67], v[54:55] op_sel_hi:[1,0]
	v_lshlrev_b32_e32 v14, 2, v14
	s_waitcnt lgkmcnt(0)
	v_pk_fma_f32 v[56:57], v[56:57], v[42:43], v[58:59] op_sel_hi:[1,0,1] neg_lo:[0,0,1] neg_hi:[0,0,1]
	v_pk_fma_f32 v[42:43], v[60:61], v[42:43], v[54:55] op_sel_hi:[1,0,1] neg_lo:[0,0,1] neg_hi:[0,0,1]
	ds_bpermute_b32 v55, v14, v132
	ds_bpermute_b32 v54, v14, v133
	v_mov_b32_e32 v46, v63
	v_mov_b32_e32 v94, v79
	v_pk_mul_f32 v[58:59], v[56:57], v[56:57]
	s_waitcnt lgkmcnt(1)
	v_mov_b32_e32 v14, v55
	v_pk_mul_f32 v[46:47], v[46:47], v[14:15] op_sel_hi:[1,0]
	v_mov_b32_e32 v14, v127
	s_waitcnt lgkmcnt(0)
; DI u16 f2bf(float a) { return (u16)(pk2(a, 0.f) & 0xffffu); }
; DI int crow(int i, int h) { return (i & 3) + 8 * (i >> 2) + 4 * h; }
; __device__ __forceinline__ void attn_item_A(const Params& p, int layer, int head, int q0u, char* lds) {
;     ...
; #pragma unroll
;   for (int e = 0; e < 16; ++e) {
;     const int qq = crow(e, h_e);
;     const float ia = __shfl(iA, qq), ib = __shfl(iB, qq);
;     float ov[4];
;     float ss = 0.f;
; #pragma unroll
;     for (int d = 0; d < 4; ++d) { ov[d] = o1[d][e] * ia - o2[d][e] * ib; ss += ov[d] * ov[d]; }
; #pragma unroll
;     for (int x = 16; x >= 1; x >>= 1) ss += __shfl_xor(ss, x);
;     const float rs = rsqrtf(ss * (1.f / 128.f) + LN_EPS);
;     const size_t rowoff = (size_t)(orow0 + qq) * LDX + ocol + r_e;
; #pragma unroll
;     for (int d = 0; d < 4; ++d) Mx[rowoff + d * 32] = f2bf(ov[d] * rs * sw[d]);
;   }
	v_pk_mul_f32 v[14:15], v[14:15], v[54:55]
	v_pk_fma_f32 v[46:47], v[94:95], v[54:55], v[46:47] op_sel_hi:[1,0,1] neg_lo:[0,0,1] neg_hi:[0,0,1]
	v_mul_f32_e32 v67, v111, v54
	v_mul_f32_e32 v31, v31, v55
	v_mov_b32_e32 v66, v14
	v_mov_b32_e32 v30, v15
	v_pk_mul_f32 v[62:63], v[46:47], v[46:47]
	v_pk_add_f32 v[14:15], v[66:67], v[30:31] neg_lo:[0,1] neg_hi:[0,1]
	v_pk_mul_f32 v[60:61], v[42:43], v[42:43]
	v_pk_mul_f32 v[30:31], v[14:15], v[14:15]
	v_mov_b32_e32 v54, v62
	v_mov_b32_e32 v55, v58
	v_mov_b32_e32 v58, v63
	v_pk_add_f32 v[54:55], v[54:55], v[58:59]
	v_mov_b32_e32 v58, v31
	v_mov_b32_e32 v59, v61
	v_pk_add_f32 v[54:55], v[58:59], v[54:55]
	v_mov_b32_e32 v31, v60
	v_pk_add_f32 v[30:31], v[30:31], v[54:55]
	ds_bpermute_b32 v55, v48, v31
	ds_bpermute_b32 v54, v48, v30
	global_store_short v[50:51], v53, off offset:128
	v_mul_f32_e32 v58, v52, v71
	v_mul_f32_e32 v48, 0x45800000, v73
	v_cndmask_b32_e32 v59, v73, v48, vcc
	s_waitcnt lgkmcnt(0)
	v_pk_add_f32 v[30:31], v[30:31], v[54:55]
	ds_bpermute_b32 v53, v49, v31
	ds_bpermute_b32 v52, v49, v30
	v_add_u32_e32 v48, v70, v191
	v_mul_f32_e32 v44, v44, v59
	v_mad_i64_i32 v[48:49], s[0:1], v48, s77, v[16:17]
	s_waitcnt lgkmcnt(0)
	v_pk_add_f32 v[30:31], v[30:31], v[52:53]
	ds_bpermute_b32 v53, v64, v31
	ds_bpermute_b32 v52, v64, v30
	v_mul_f32_e32 v44, v131, v44
	v_cvt_pk_bf16_f32 v44, v44, s0
	global_store_short v[48:49], v44, off
	v_mul_f32_e32 v54, v45, v59
	s_waitcnt lgkmcnt(0)
	v_pk_add_f32 v[30:31], v[30:31], v[52:53]
	ds_bpermute_b32 v45, v65, v31
	ds_bpermute_b32 v44, v65, v30
	v_mul_f32_e32 v29, v29, v59
	v_mul_f32_e32 v52, v130, v54
	v_mul_f32_e32 v29, v129, v29
	v_cvt_pk_bf16_f32 v52, v52, s0
	s_waitcnt lgkmcnt(0)
	v_pk_add_f32 v[30:31], v[30:31], v[44:45]
	ds_bpermute_b32 v45, v80, v31
	ds_bpermute_b32 v44, v80, v30
	v_cvt_pk_bf16_f32 v29, v29, s0
	global_store_short v[48:49], v52, off offset:64
	global_store_short v[48:49], v29, off offset:128
	v_mul_f32_e32 v52, v28, v59
	s_waitcnt lgkmcnt(0)
	v_pk_add_f32 v[28:29], v[30:31], v[44:45]
	s_nop 0
	v_pk_fma_f32 v[28:29], v[28:29], s[28:29], v[32:33] op_sel_hi:[1,0,0]
	s_nop 0
	v_mul_f32_e32 v30, 0x4b800000, v29
	v_cmp_gt_f32_e32 vcc, s80, v29
	v_mul_f32_e32 v33, 0x4b800000, v28
	s_nop 0
	v_cndmask_b32_e32 v29, v29, v30, vcc
	v_rsq_f32_e32 v29, v29
	v_add_u32_e32 v30, v74, v191
	v_mad_i64_i32 v[30:31], s[0:1], v30, s77, v[16:17]
	v_mul_f32_e32 v32, 0x45800000, v29
	v_cndmask_b32_e32 v29, v29, v32, vcc
	v_mul_f32_e32 v32, v56, v29
	v_mul_f32_e32 v32, v131, v32
	v_cvt_pk_bf16_f32 v32, v32, s0
	global_store_short v[30:31], v32, off
	v_mul_f32_e32 v32, v57, v29
	v_cmp_gt_f32_e32 vcc, s80, v28
	v_mul_f32_e32 v32, v130, v32
	v_cvt_pk_bf16_f32 v32, v32, s0
	v_cndmask_b32_e32 v28, v28, v33, vcc
	v_rsq_f32_e32 v28, v28
	global_store_short v[30:31], v32, off offset:64
	v_mul_f32_e32 v32, v43, v29
	v_mul_f32_e32 v32, v129, v32
	v_cvt_pk_bf16_f32 v32, v32, s0
	global_store_short v[30:31], v32, off offset:128
	v_mul_f32_e32 v32, 0x45800000, v28
	v_cndmask_b32_e32 v167, v28, v32, vcc
	v_add_u32_e32 v28, v76, v191
	v_mad_i64_i32 v[16:17], s[0:1], v28, s77, v[16:17]
	v_mul_f32_e32 v28, v46, v167
	v_mul_f32_e32 v28, v131, v28
	v_cvt_pk_bf16_f32 v28, v28, s0
	v_mul_f32_e32 v15, v15, v167
	global_store_short v[16:17], v28, off
	v_mul_f32_e32 v28, v47, v167
	v_mul_f32_e32 v15, v129, v15
	v_mul_f32_e32 v28, v130, v28
	v_cvt_pk_bf16_f32 v15, v15, s0
	v_mov_b32_e32 v129, v14
	v_cvt_pk_bf16_f32 v28, v28, s0
	global_store_short v[16:17], v15, off offset:128
	s_waitcnt vmcnt(13)
	v_pk_mul_f32 v[14:15], v[128:129], v[166:167]
	global_store_short v[16:17], v28, off offset:64
	v_mul_f32_e32 v28, v14, v34
	v_cvt_pk_bf16_f32 v28, v28, s0
	global_store_short v[0:1], v28, off offset:192
	v_mul_f32_e32 v0, v14, v35
	v_cvt_pk_bf16_f32 v0, v0, s0
	global_store_short v[2:3], v0, off offset:192
	v_mul_f32_e32 v0, v14, v36
	v_cvt_pk_bf16_f32 v0, v0, s0
	global_store_short v[18:19], v0, off offset:192
	v_mul_f32_e32 v0, v14, v37
	v_cvt_pk_bf16_f32 v0, v0, s0
	global_store_short v[4:5], v0, off offset:192
	v_mul_f32_e32 v0, v14, v38
	v_cvt_pk_bf16_f32 v0, v0, s0
	global_store_short v[20:21], v0, off offset:192
	v_mul_f32_e32 v0, v14, v39
	v_cvt_pk_bf16_f32 v0, v0, s0
	global_store_short v[6:7], v0, off offset:192
	v_mul_f32_e32 v0, v14, v40
	v_cvt_pk_bf16_f32 v0, v0, s0
	global_store_short v[22:23], v0, off offset:192
	v_mul_f32_e32 v0, v14, v41
	v_cvt_pk_bf16_f32 v0, v0, s0
	global_store_short v[8:9], v0, off offset:192
	v_mul_f32_e32 v0, v14, v75
	v_cvt_pk_bf16_f32 v0, v0, s0
	global_store_short v[24:25], v0, off offset:192
	v_mul_f32_e32 v0, v14, v72
	v_cvt_pk_bf16_f32 v0, v0, s0
	global_store_short v[10:11], v0, off offset:192
	v_mul_f32_e32 v0, v14, v68
	v_cvt_pk_bf16_f32 v0, v0, s0
	global_store_short v[26:27], v0, off offset:192
	v_mul_f32_e32 v0, v14, v69
	v_cvt_pk_bf16_f32 v0, v0, s0
	global_store_short v[12:13], v0, off offset:192
	v_mul_f32_e32 v0, v14, v58
	v_cvt_pk_bf16_f32 v0, v0, s0
	global_store_short v[50:51], v0, off offset:192
	v_mul_f32_e32 v0, v14, v52
	v_mul_f32_e32 v29, v42, v29
	v_cvt_pk_bf16_f32 v0, v0, s0
	global_store_short v[48:49], v0, off offset:192
	v_mul_f32_e32 v0, v14, v29
	v_cvt_pk_bf16_f32 v0, v0, s0
	global_store_short v[30:31], v0, off offset:192
	v_mul_f32_e32 v0, v14, v15
	s_branch .LBB0_1476

; #define MFMA32(a, b, c) __builtin_amdgcn_mfma_f32_32x32x16_bf16((a), (b), (c), 0, 0, 0)
; __device__ __forceinline__ void attn_item_A(const Params& p, int layer, int head, int q0u, char* lds) {
;     ...
;   for (int t = 0; t < ntiles; ++t) {
;     const int buf = t & 1;
;     const bool more = (t + 1 < ntiles);
;     if (more) { ATT_LOADK(t + 1); ATT_LOADV(t + 1); }
;     const u16* kt_ = Ks + buf * 32 * KLD + r * KLD + 8 * h;
;     bf16x8 a0, a1, b0, b1;
;     {
;       f32x16 sx, sy;
; #pragma unroll
;       for (int e = 0; e < 16; ++e) { sx[e] = 0.f; sy[e] = 0.f; }
; #pragma unroll
;       for (int s = 0; s < 4; ++s) {
;         const bf16x8 kf = *(const bf16x8*)(kt_ + 16 * s);
;         const bf16x8 qf = *(const bf16x8*)(Qs + s * 1024);
;         sx = MFMA32(kf, qf, sx);
;       }
; #pragma unroll
;       for (int s = 4; s < 8; ++s) {
;         const bf16x8 kf = *(const bf16x8*)(kt_ + 16 * s);
;         const bf16x8 qf = *(const bf16x8*)(Qs + s * 1024);
;         sy = MFMA32(kf, qf, sy);
;       }
;       {
;         float w[16];
; #pragma unroll
;         for (int e = 0; e < 16; ++e) { w[e] = __builtin_amdgcn_exp2f(fmaf(sx[e], CS, -bA)); lA += w[e]; }
;         const u32x4 p0 = {pk2(w[0], w[1]), pk2(w[2], w[3]), pk2(w[4], w[5]), pk2(w[6], w[7])};
;         const u32x4 p1 = {pk2(w[8], w[9]), pk2(w[10], w[11]), pk2(w[12], w[13]), pk2(w[14], w[15])};
;         a0 = __builtin_bit_cast(bf16x8, p0); a1 = __builtin_bit_cast(bf16x8, p1);
;       }
;       {
;         float w[16];
; #pragma unroll
;         for (int e = 0; e < 16; ++e) { w[e] = __builtin_amdgcn_exp2f(fmaf(sy[e], CS, -bB)); lB += w[e]; }
;         const u32x4 p0 = {pk2(w[0], w[1]), pk2(w[2], w[3]), pk2(w[4], w[5]), pk2(w[6], w[7])};
;         const u32x4 p1 = {pk2(w[8], w[9]), pk2(w[10], w[11]), pk2(w[12], w[13]), pk2(w[14], w[15])};
;         b0 = __builtin_bit_cast(bf16x8, p0); b1 = __builtin_bit_cast(bf16x8, p1);
;       }
;     }
;     const u16* vt = Vt + buf * 128 * VLD + r * VLD + 4 * h;
; #pragma unroll
;     for (int d = 0; d < 4; d += 2) {
;       const s16x4 l0 = *(const s16x4*)(vt + d * 32 * VLD), h0 = *(const s16x4*)(vt + d * 32 * VLD + 8);
;       const s16x4 l1 = *(const s16x4*)(vt + d * 32 * VLD + 16), h1 = *(const s16x4*)(vt + d * 32 * VLD + 24);
;       const s16x4 m0 = *(const s16x4*)(vt + (d + 1) * 32 * VLD), n0 = *(const s16x4*)(vt + (d + 1) * 32 * VLD + 8);
.LBB0_2327:
	s_setprio 1
	s_and_b32 s0, s8, 1
	s_mul_i32 s1, s0, 0x2200
	v_add_u32_e32 v196, v192, v193
	v_add_u32_e32 v197, s1, v195
	ds_read_b128 v[128:131], v196 offset:37888
	ds_read_b128 v[160:163], v196 offset:38912
	ds_read_b128 v[144:147], v196 offset:41984
	ds_read_b128 v[178:181], v196 offset:43008
	ds_read_b128 v[132:135], v197
	ds_read_b128 v[198:201], v197 offset:32
	ds_read_b128 v[148:151], v197 offset:128
	ds_read_b128 v[202:205], v197 offset:160
	ds_read_b128 v[206:209], v197 offset:64
	ds_read_b128 v[216:219], v197 offset:96
	ds_read_b128 v[220:223], v197 offset:192
	ds_read_b128 v[224:227], v197 offset:224
	s_waitcnt lgkmcnt(7)
	v_mfma_f32_32x32x16_bf16 v[128:143], v[132:135], v[128:131], 0
	s_mul_i32 s1, s0, 0x2400
	s_ashr_i32 s7, s6, 31
	s_xor_b32 s0, s0, 1
	s_add_i32 s8, s8, 1
	s_waitcnt lgkmcnt(5)
	v_mfma_f32_32x32x16_bf16 v[144:159], v[148:151], v[144:147], 0
	v_mfma_f32_32x32x16_bf16 v[128:143], v[198:201], v[160:163], v[128:143]
	s_waitcnt lgkmcnt(4)
	v_mfma_f32_32x32x16_bf16 v[144:159], v[202:205], v[178:181], v[144:159]
	s_waitcnt lgkmcnt(3)
	v_mfma_f32_32x32x16_bf16 v[128:143], v[206:209], v[240:243], v[128:143]
	v_add_u32_e32 v197, s1, v164
	v_add_u32_e32 v210, 0x4000, v197
	v_add_u32_e32 v215, 0x4800, v197
	v_add_u32_e32 v238, 0x5000, v197
	v_add_u32_e32 v197, 0x5800, v197
	v_lshl_add_u64 v[178:179], s[6:7], 1, v[170:171]
	s_waitcnt lgkmcnt(1)
	v_mfma_f32_32x32x16_bf16 v[144:159], v[220:223], v[248:251], v[144:159]
	v_add_u32_e32 v160, s6, v194
	v_mad_i64_i32 v[180:181], s[10:11], v160, s68, v[176:177]
	global_load_dwordx4 v[160:163], v[180:181], off offset:1040
	s_add_i32 s6, s6, 32
	s_mul_i32 s1, s0, 0x2200
	s_mulk_i32 s0, 0x2400
	v_mfma_f32_32x32x16_bf16 v[128:143], v[216:219], v[244:247], v[128:143]
	ds_read2_b64 v[198:201], v210 offset0:128 offset1:130
	s_cmpk_eq_i32 s6, 0x4100
	s_waitcnt lgkmcnt(1)
	v_mfma_f32_32x32x16_bf16 v[144:159], v[224:227], v[252:255], v[144:159]
	s_nop 7
	v_fmamk_f32 v128, v128, 0x3e38aa3b, v175
	v_fmamk_f32 v129, v129, 0x3e38aa3b, v175
	v_fmamk_f32 v130, v130, 0x3e38aa3b, v175
	v_fmamk_f32 v131, v131, 0x3e38aa3b, v175
	v_fmamk_f32 v132, v132, 0x3e38aa3b, v175
	v_fmamk_f32 v133, v133, 0x3e38aa3b, v175
	v_fmamk_f32 v202, v134, 0x3e38aa3b, v175
	v_fmamk_f32 v135, v135, 0x3e38aa3b, v175
	v_fmamk_f32 v203, v144, 0x3e38aa3b, v173
	v_fmamk_f32 v145, v145, 0x3e38aa3b, v173
	v_fmamk_f32 v204, v146, 0x3e38aa3b, v173
	v_fmamk_f32 v205, v147, 0x3e38aa3b, v173
	v_fmamk_f32 v206, v148, 0x3e38aa3b, v173
	v_fmamk_f32 v207, v149, 0x3e38aa3b, v173
	v_fmamk_f32 v208, v150, 0x3e38aa3b, v173
	v_fmamk_f32 v209, v151, 0x3e38aa3b, v173
	v_exp_f32_e32 v150, v128
	v_exp_f32_e32 v148, v129
	v_exp_f32_e32 v146, v130
	v_exp_f32_e32 v144, v131
	v_exp_f32_e32 v134, v132
	v_exp_f32_e32 v130, v133
	v_exp_f32_e32 v132, v202
	v_exp_f32_e32 v128, v135
	v_exp_f32_e32 v151, v203
	v_exp_f32_e32 v149, v145
	v_exp_f32_e32 v147, v204
	v_exp_f32_e32 v145, v205
	v_exp_f32_e32 v135, v206
	v_exp_f32_e32 v131, v207
	v_exp_f32_e32 v133, v208
	v_exp_f32_e32 v129, v209
	v_cvt_pk_bf16_f32 v202, v150, v148
	v_cvt_pk_bf16_f32 v203, v146, v144
	v_cvt_pk_bf16_f32 v204, v134, v130
	v_cvt_pk_bf16_f32 v205, v132, v128
	v_cvt_pk_bf16_f32 v206, v151, v149
	v_cvt_pk_bf16_f32 v207, v147, v145
	v_cvt_pk_bf16_f32 v208, v135, v131
	v_cvt_pk_bf16_f32 v209, v133, v129
	s_waitcnt lgkmcnt(0)
	v_mfma_f32_32x32x16_bf16 v[64:79], v[202:205], v[198:201], v[64:79]
	v_fmamk_f32 v152, v152, 0x3e38aa3b, v173
	v_fmamk_f32 v153, v153, 0x3e38aa3b, v173
	v_fmamk_f32 v154, v154, 0x3e38aa3b, v173
	v_fmamk_f32 v155, v155, 0x3e38aa3b, v173
	v_fmamk_f32 v156, v156, 0x3e38aa3b, v173
	v_fmamk_f32 v157, v157, 0x3e38aa3b, v173
	v_fmamk_f32 v158, v158, 0x3e38aa3b, v173
	v_mfma_f32_32x32x16_bf16 v[48:63], v[206:209], v[198:201], v[48:63]
	ds_read2_b64 v[198:201], v215 offset0:160 offset1:162
	ds_read2_b64 v[216:219], v210 offset0:132 offset1:134
	ds_read2_b64 v[220:223], v238 offset0:192 offset1:194
	ds_read2_b64 v[224:227], v197 offset0:224 offset1:226
	v_fmamk_f32 v159, v159, 0x3e38aa3b, v173
	v_exp_f32_e32 v213, v152
	v_exp_f32_e32 v229, v153
	v_exp_f32_e32 v231, v154
	v_exp_f32_e32 v233, v157
	s_waitcnt lgkmcnt(1)
	v_mfma_f32_32x32x16_bf16 v[96:111], v[202:205], v[220:223], v[96:111]
	v_exp_f32_e32 v235, v158
	v_exp_f32_e32 v237, v159
	v_fmamk_f32 v136, v136, 0x3e38aa3b, v175
	v_fmamk_f32 v137, v137, 0x3e38aa3b, v175
	v_fmamk_f32 v138, v138, 0x3e38aa3b, v175
	v_fmamk_f32 v139, v139, 0x3e38aa3b, v175
	v_fmamk_f32 v140, v140, 0x3e38aa3b, v175
	v_mfma_f32_32x32x16_bf16 v[16:31], v[206:209], v[220:223], v[16:31]
	v_exp_f32_e32 v221, v155
	v_exp_f32_e32 v223, v156
	global_load_dwordx4 v[152:155], v[180:181], off offset:1024
	global_load_dwordx4 v[156:159], v[178:179], off
	v_fmamk_f32 v141, v141, 0x3e38aa3b, v175
	global_load_dwordx4 v[178:181], v[178:179], off offset:16
	v_fmamk_f32 v142, v142, 0x3e38aa3b, v175
	v_fmamk_f32 v143, v143, 0x3e38aa3b, v175
	v_exp_f32_e32 v212, v136
	v_exp_f32_e32 v228, v137
	v_exp_f32_e32 v230, v138
	v_exp_f32_e32 v220, v139
	v_exp_f32_e32 v222, v140
	v_exp_f32_e32 v232, v141
	v_exp_f32_e32 v234, v142
	v_exp_f32_e32 v236, v143
	v_mfma_f32_32x32x16_bf16 v[80:95], v[202:205], v[198:201], v[80:95]
	v_cvt_pk_bf16_f32 v136, v212, v228
	v_cvt_pk_bf16_f32 v137, v230, v220
	v_cvt_pk_bf16_f32 v138, v222, v232
	v_cvt_pk_bf16_f32 v139, v234, v236
	v_cvt_pk_bf16_f32 v140, v213, v229
	v_cvt_pk_bf16_f32 v141, v231, v221
	v_cvt_pk_bf16_f32 v142, v223, v233
	v_mfma_f32_32x32x16_bf16 v[32:47], v[206:209], v[198:201], v[32:47]
	v_cvt_pk_bf16_f32 v143, v235, v237
	ds_read2_b64 v[198:201], v215 offset0:164 offset1:166
	v_add_f32_e64 v150, v168, v150
	v_add_f32_e64 v151, v169, v151
	v_add_f32_e64 v148, v148, v150
	v_add_f32_e64 v149, v149, v151
	v_pk_add_f32 v[146:147], v[146:147], v[148:149]
	s_waitcnt lgkmcnt(1)
; __device__ __forceinline__ void attn_item_A(const Params& p, int layer, int head, int q0u, char* lds) {
;     ...
; #pragma unroll
;       for (int s = 0; s < 4; ++s) {
;         const bf16x8 kf = *(const bf16x8*)(kt_ + 16 * s);
;         const bf16x8 qf = *(const bf16x8*)(Qs + s * 1024);
;         sx = MFMA32(kf, qf, sx);
;       }
; #pragma unroll
;       for (int s = 4; s < 8; ++s) {
;         const bf16x8 kf = *(const bf16x8*)(kt_ + 16 * s);
;         const bf16x8 qf = *(const bf16x8*)(Qs + s * 1024);
;         sy = MFMA32(kf, qf, sy);
;       }
;       {
;         float w[16];
; #pragma unroll
;         for (int e = 0; e < 16; ++e) { w[e] = __builtin_amdgcn_exp2f(fmaf(sx[e], CS, -bA)); lA += w[e]; }
;         const u32x4 p0 = {pk2(w[0], w[1]), pk2(w[2], w[3]), pk2(w[4], w[5]), pk2(w[6], w[7])};
;         const u32x4 p1 = {pk2(w[8], w[9]), pk2(w[10], w[11]), pk2(w[12], w[13]), pk2(w[14], w[15])};
;         a0 = __builtin_bit_cast(bf16x8, p0); a1 = __builtin_bit_cast(bf16x8, p1);
;       }
;       {
;         float w[16];
; #pragma unroll
;         for (int e = 0; e < 16; ++e) { w[e] = __builtin_amdgcn_exp2f(fmaf(sy[e], CS, -bB)); lB += w[e]; }
;         const u32x4 p0 = {pk2(w[0], w[1]), pk2(w[2], w[3]), pk2(w[4], w[5]), pk2(w[6], w[7])};
;         const u32x4 p1 = {pk2(w[8], w[9]), pk2(w[10], w[11]), pk2(w[12], w[13]), pk2(w[14], w[15])};
;         b0 = __builtin_bit_cast(bf16x8, p0); b1 = __builtin_bit_cast(bf16x8, p1);
;       }
;     }
;     const u16* vt = Vt + buf * 128 * VLD + r * VLD + 4 * h;
; #pragma unroll
;     for (int d = 0; d < 4; d += 2) {
;       const s16x4 l0 = *(const s16x4*)(vt + d * 32 * VLD), h0 = *(const s16x4*)(vt + d * 32 * VLD + 8);
;       const s16x4 l1 = *(const s16x4*)(vt + d * 32 * VLD + 16), h1 = *(const s16x4*)(vt + d * 32 * VLD + 24);
;       const s16x4 m0 = *(const s16x4*)(vt + (d + 1) * 32 * VLD), n0 = *(const s16x4*)(vt + (d + 1) * 32 * VLD + 8);
;       const s16x4 m1 = *(const s16x4*)(vt + (d + 1) * 32 * VLD + 16), n1 = *(const s16x4*)(vt + (d + 1) * 32 * VLD + 24);
;       const bf16x8 v0 = {l0[0], l0[1], l0[2], l0[3], h0[0], h0[1], h0[2], h0[3]};
;       const bf16x8 v1 = {l1[0], l1[1], l1[2], l1[3], h1[0], h1[1], h1[2], h1[3]};
;       const bf16x8 u0 = {m0[0], m0[1], m0[2], m0[3], n0[0], n0[1], n0[2], n0[3]};
;       const bf16x8 u1 = {m1[0], m1[1], m1[2], m1[3], n1[0], n1[1], n1[2], n1[3]};
	v_mfma_f32_32x32x16_bf16 v[112:127], v[202:205], v[224:227], v[112:127]
	ds_read2_b64 v[202:205], v197 offset0:228 offset1:230
	v_add_f32_e64 v144, v144, v146
	v_add_f32_e64 v145, v145, v147
	v_add_f32_e64 v134, v134, v144
	v_add_f32_e64 v135, v135, v145
	v_pk_add_f32 v[130:131], v[130:131], v[134:135]
	v_mfma_f32_32x32x16_bf16 v[0:15], v[206:209], v[224:227], v[0:15]
	v_add_f32_e64 v130, v132, v130
	v_add_f32_e64 v131, v133, v131
	v_add_u32_e32 v206, s1, v172
	v_add_f32_e64 v128, v128, v130
	v_add_f32_e64 v129, v129, v131
	v_add_u32_e32 v207, s0, v174
	v_pk_add_f32 v[128:129], v[212:213], v[128:129]
	v_add_u32_e32 v197, 0x4400, v207
	v_pk_add_f32 v[128:129], v[228:229], v[128:129]
	s_waitcnt lgkmcnt(1)
	v_mfma_f32_32x32x16_bf16 v[80:95], v[136:139], v[198:201], v[80:95]
	v_add_f32_e64 v128, v230, v128
	v_add_f32_e64 v129, v231, v129
	v_add_u32_e32 v207, 0x4410, v207
	v_add_f32_e64 v128, v220, v128
	v_add_f32_e64 v129, v221, v129
	v_pk_add_f32 v[128:129], v[222:223], v[128:129]
	s_nop 0
	v_pk_add_f32 v[128:129], v[232:233], v[128:129]
	v_mfma_f32_32x32x16_bf16 v[32:47], v[140:143], v[198:201], v[32:47]
	ds_read2_b64 v[198:201], v238 offset0:196 offset1:198
	v_add_f32_e64 v128, v234, v128
	v_add_f32_e64 v129, v235, v129
	s_setprio 0
	s_waitcnt vmcnt(2)
	ds_write_b128 v206, v[152:155]
	ds_write_b128 v206, v[160:163] offset:16
	s_waitcnt vmcnt(1)
	ds_write2_b64 v197, v[156:157], v[158:159] offset1:1
	s_waitcnt vmcnt(0)
	ds_write2_b64 v207, v[178:179], v[180:181] offset1:1
	v_mfma_f32_32x32x16_bf16 v[64:79], v[136:139], v[216:219], v[64:79]
	v_add_f32_e64 v168, v236, v128
	v_add_f32_e64 v169, v237, v129
	s_waitcnt lgkmcnt(0)
	s_barrier
	v_mfma_f32_32x32x16_bf16 v[48:63], v[140:143], v[216:219], v[48:63]
	v_mfma_f32_32x32x16_bf16 v[96:111], v[136:139], v[198:201], v[96:111]
	v_mfma_f32_32x32x16_bf16 v[16:31], v[140:143], v[198:201], v[16:31]
	v_mfma_f32_32x32x16_bf16 v[112:127], v[136:139], v[202:205], v[112:127]
	v_mfma_f32_32x32x16_bf16 v[0:15], v[140:143], v[202:205], v[0:15]
	s_cbranch_scc0 .LBB0_2327
	ds_read_b128 v[128:131], v195 offset:8704
	ds_read_b128 v[132:135], v196 offset:37888
	ds_read_b128 v[136:139], v195 offset:8736
	ds_read_b128 v[140:143], v196 offset:38912
	s_waitcnt lgkmcnt(2)
	v_mfma_f32_32x32x16_bf16 v[144:159], v[128:131], v[132:135], 0
	ds_read_b128 v[128:131], v195 offset:8768
	ds_read_b128 v[132:135], v196 offset:39936
	ds_read_b128 v[160:163], v195 offset:8800
	ds_read_b128 v[176:179], v196 offset:40960
	s_waitcnt lgkmcnt(4)
	v_mfma_f32_32x32x16_bf16 v[144:159], v[136:139], v[140:143], v[144:159]
	s_waitcnt lgkmcnt(2)
	v_mfma_f32_32x32x16_bf16 v[144:159], v[128:131], v[132:135], v[144:159]
	ds_read_b128 v[128:131], v195 offset:8832
	ds_read_b128 v[132:135], v196 offset:41984
	ds_read_b128 v[198:201], v195 offset:8864
	ds_read_b128 v[202:205], v196 offset:43008
	ds_read_b128 v[206:209], v195 offset:8896
	ds_read_b128 v[192:195], v195 offset:8928
	ds_read_b128 v[216:219], v196 offset:44032
	ds_read_b128 v[220:223], v196 offset:45056
	s_waitcnt lgkmcnt(6)
	v_mfma_f32_32x32x16_bf16 v[128:143], v[128:131], v[132:135], 0
	s_waitcnt lgkmcnt(4)
	v_mfma_f32_32x32x16_bf16 v[128:143], v[198:201], v[202:205], v[128:143]
	s_waitcnt lgkmcnt(1)
	v_mfma_f32_32x32x16_bf16 v[128:143], v[206:209], v[216:219], v[128:143]
	s_waitcnt lgkmcnt(0)
	v_mfma_f32_32x32x16_bf16 v[128:143], v[192:195], v[220:223], v[128:143]
	v_mfma_f32_32x32x16_bf16 v[144:159], v[160:163], v[176:179], v[144:159]
	s_nop 10
	v_fmamk_f32 v128, v128, 0x3e38aa3b, v173
	v_exp_f32_e32 v192, v128
	v_fmamk_f32 v128, v129, 0x3e38aa3b, v173
	v_exp_f32_e32 v193, v128
	v_fmamk_f32 v128, v130, 0x3e38aa3b, v173
	v_exp_f32_e32 v194, v128
	v_fmamk_f32 v128, v131, 0x3e38aa3b, v173
	v_exp_f32_e32 v195, v128
	v_fmamk_f32 v128, v132, 0x3e38aa3b, v173
	v_fmamk_f32 v132, v134, 0x3e38aa3b, v173
	v_fmamk_f32 v144, v144, 0x3e38aa3b, v175
	v_fmamk_f32 v145, v145, 0x3e38aa3b, v175
	v_fmamk_f32 v146, v146, 0x3e38aa3b, v175
	v_fmamk_f32 v147, v147, 0x3e38aa3b, v175
	v_fmamk_f32 v148, v148, 0x3e38aa3b, v175
	v_fmamk_f32 v149, v149, 0x3e38aa3b, v175
	v_fmamk_f32 v150, v150, 0x3e38aa3b, v175
	v_fmamk_f32 v151, v151, 0x3e38aa3b, v175
	v_exp_f32_e32 v201, v128
	v_fmamk_f32 v128, v133, 0x3e38aa3b, v173
	v_exp_f32_e32 v203, v132
	v_fmamk_f32 v132, v135, 0x3e38aa3b, v173
	v_exp_f32_e32 v170, v144
	v_exp_f32_e32 v171, v145
	v_exp_f32_e32 v172, v146
	v_exp_f32_e32 v174, v147
	v_exp_f32_e32 v176, v148
	v_exp_f32_e32 v177, v149
	v_exp_f32_e32 v178, v150
	v_exp_f32_e32 v179, v151
	v_fmamk_f32 v144, v155, 0x3e38aa3b, v175
	v_exp_f32_e32 v202, v128
	v_exp_f32_e32 v204, v132
	v_exp_f32_e32 v197, v144
	v_fmamk_f32 v144, v156, 0x3e38aa3b, v175
	v_fmamk_f32 v152, v152, 0x3e38aa3b, v175
	v_exp_f32_e32 v198, v144
	v_fmamk_f32 v144, v157, 0x3e38aa3b, v175
	v_exp_f32_e32 v180, v152
	v_exp_f32_e32 v199, v144
	v_fmamk_f32 v144, v158, 0x3e38aa3b, v175
	v_add_u32_e32 v152, 0x6800, v164
	v_fmamk_f32 v136, v136, 0x3e38aa3b, v173
	v_exp_f32_e32 v200, v144
	v_cvt_pk_bf16_f32 v144, v170, v171
	v_cvt_pk_bf16_f32 v145, v172, v174
	v_cvt_pk_bf16_f32 v146, v176, v177
	v_cvt_pk_bf16_f32 v147, v178, v179
	ds_read2_b64 v[128:131], v152 offset1:2
	v_cvt_pk_bf16_f32 v132, v192, v193
	v_cvt_pk_bf16_f32 v133, v194, v195
	v_cvt_pk_bf16_f32 v134, v201, v202
	v_cvt_pk_bf16_f32 v135, v203, v204
	v_exp_f32_e32 v205, v136
	v_fmamk_f32 v136, v137, 0x3e38aa3b, v173
	v_exp_f32_e32 v206, v136
	v_fmamk_f32 v136, v138, 0x3e38aa3b, v173
	v_exp_f32_e32 v207, v136
	v_fmamk_f32 v136, v139, 0x3e38aa3b, v173
	v_fmamk_f32 v153, v153, 0x3e38aa3b, v175
	v_exp_f32_e32 v208, v136
	v_fmamk_f32 v136, v140, 0x3e38aa3b, v173
	v_exp_f32_e32 v181, v153
	v_add_u32_e32 v153, 0x7000, v164
	v_exp_f32_e32 v209, v136
	v_fmamk_f32 v136, v141, 0x3e38aa3b, v173
	v_fmamk_f32 v154, v154, 0x3e38aa3b, v175
	v_fmac_f32_e32 v175, 0x3e38aa3b, v159
	s_waitcnt lgkmcnt(0)
; __device__ __forceinline__ void attn_item_A(const Params& p, int layer, int head, int q0u, char* lds) {
;     ...
;     const u16* vt = Vt + buf * 128 * VLD + r * VLD + 4 * h;
; #pragma unroll
;     for (int d = 0; d < 4; d += 2) {
;       const s16x4 l0 = *(const s16x4*)(vt + d * 32 * VLD), h0 = *(const s16x4*)(vt + d * 32 * VLD + 8);
;       const s16x4 l1 = *(const s16x4*)(vt + d * 32 * VLD + 16), h1 = *(const s16x4*)(vt + d * 32 * VLD + 24);
;       const s16x4 m0 = *(const s16x4*)(vt + (d + 1) * 32 * VLD), n0 = *(const s16x4*)(vt + (d + 1) * 32 * VLD + 8);
;       const s16x4 m1 = *(const s16x4*)(vt + (d + 1) * 32 * VLD + 16), n1 = *(const s16x4*)(vt + (d + 1) * 32 * VLD + 24);
;       const bf16x8 v0 = {l0[0], l0[1], l0[2], l0[3], h0[0], h0[1], h0[2], h0[3]};
;       const bf16x8 v1 = {l1[0], l1[1], l1[2], l1[3], h1[0], h1[1], h1[2], h1[3]};
;       const bf16x8 u0 = {m0[0], m0[1], m0[2], m0[3], n0[0], n0[1], n0[2], n0[3]};
;       const bf16x8 u1 = {m1[0], m1[1], m1[2], m1[3], n1[0], n1[1], n1[2], n1[3]};
;       o1[d] = MFMA32(a0, v0, o1[d]);
;       o2[d] = MFMA32(b0, v0, o2[d]);
;       o1[d + 1] = MFMA32(a0, u0, o1[d + 1]);
;       o2[d + 1] = MFMA32(b0, u0, o2[d + 1]);
;       o1[d] = MFMA32(a1, v1, o1[d]);
;       o2[d] = MFMA32(b1, v1, o2[d]);
;       o1[d + 1] = MFMA32(a1, u1, o1[d + 1]);
;       o2[d + 1] = MFMA32(b1, u1, o2[d + 1]);
;     }
;     if (more) { ATT_STOREK(buf ^ 1); ATT_STOREV(buf ^ 1); }
;     __syncthreads();
;   }
;   int lane_e = lane; asm volatile("" : "+v"(lane_e));
;   const int r_e = lane_e & 31, h_e = lane_e >> 5;
;   lA += __shfl_xor(lA, 32); lB += __shfl_xor(lB, 32);
;   const float lam = ((const float*)(p.ws + OFF_LAM))[layer];
;   const float iA = 1.f / lA, iB = lam / lB;
;   u16* Mx = (u16*)(p.ws + OFF_M);
;   const int orow0 = q0u + wid * 32;
;   const float lam_init = 0.8f - 0.6f * expf(-0.3f * (float)layer);
;   float sw[4];
; #pragma unroll
;   for (int d = 0; d < 4; ++d) sw[d] = p.subln[layer * 128 + d * 32 + r_e] * (1.f - lam_init);
; #pragma unroll
;   for (int e = 0; e < 16; ++e) {
;     const int qq = crow(e, h_e);
;     const float ia = __shfl(iA, qq), ib = __shfl(iB, qq);
;     float ov[4];
;     float ss = 0.f;
; #pragma unroll
;     for (int d = 0; d < 4; ++d) { ov[d] = o1[d][e] * ia - o2[d][e] * ib; ss += ov[d] * ov[d]; }
; #pragma unroll
;     for (int x = 16; x >= 1; x >>= 1) ss += __shfl_xor(ss, x);
	v_mfma_f32_32x32x16_bf16 v[64:79], v[144:147], v[128:131], v[64:79]
	v_exp_f32_e32 v210, v136
	v_fmamk_f32 v136, v142, 0x3e38aa3b, v173
	v_fmac_f32_e32 v173, 0x3e38aa3b, v143
	v_exp_f32_e32 v196, v154
	v_exp_f32_e32 v175, v175
	v_exp_f32_e32 v212, v136
	v_exp_f32_e32 v173, v173
	v_mfma_f32_32x32x16_bf16 v[48:63], v[132:135], v[128:131], v[48:63]
	ds_read2_b64 v[128:131], v153 offset0:32 offset1:34
	v_cvt_pk_bf16_f32 v148, v180, v181
	v_cvt_pk_bf16_f32 v149, v196, v197
	v_cvt_pk_bf16_f32 v150, v198, v199
	v_cvt_pk_bf16_f32 v151, v200, v175
	v_cvt_pk_bf16_f32 v136, v205, v206
	v_cvt_pk_bf16_f32 v137, v207, v208
	s_waitcnt lgkmcnt(0)
	v_mfma_f32_32x32x16_bf16 v[80:95], v[144:147], v[128:131], v[80:95]
	v_cvt_pk_bf16_f32 v138, v209, v210
	v_cvt_pk_bf16_f32 v139, v212, v173
	v_add_u32_e32 v160, 0x8000, v164
	v_mfma_f32_32x32x16_bf16 v[32:47], v[132:135], v[128:131], v[32:47]
	ds_read2_b64 v[128:131], v152 offset0:4 offset1:6
	v_add_u32_e32 v152, 0x7800, v164
	ds_read2_b64 v[140:143], v152 offset0:64 offset1:66
	s_waitcnt lgkmcnt(1)
	v_mfma_f32_32x32x16_bf16 v[64:79], v[148:151], v[128:131], v[64:79]
	v_mfma_f32_32x32x16_bf16 v[48:63], v[136:139], v[128:131], v[48:63]
	ds_read2_b64 v[128:131], v153 offset0:36 offset1:38
	ds_read2_b64 v[152:155], v152 offset0:68 offset1:70
	ds_read2_b64 v[156:159], v160 offset0:96 offset1:98
	ds_read2_b64 v[160:163], v160 offset0:100 offset1:102
	s_waitcnt lgkmcnt(0)
	s_barrier
	global_load_dword v164, v165, s[18:19]
	v_mfma_f32_32x32x16_bf16 v[96:111], v[144:147], v[140:143], v[96:111]
	v_and_b32_e32 v213, 31, v167
	v_mfma_f32_32x32x16_bf16 v[16:31], v[132:135], v[140:143], v[16:31]
	v_add_f32_e32 v140, v169, v192
	v_add_f32_e32 v140, v193, v140
	v_add_f32_e32 v140, v194, v140
	v_add_f32_e32 v140, v195, v140
	v_add_f32_e32 v140, v201, v140
	v_add_f32_e32 v140, v202, v140
	v_add_f32_e32 v140, v203, v140
	v_add_f32_e32 v140, v204, v140
	v_add_f32_e32 v140, v205, v140
	v_add_f32_e32 v140, v206, v140
	v_mfma_f32_32x32x16_bf16 v[0:15], v[132:135], v[156:159], v[0:15]
	v_add_f32_e32 v132, v207, v140
	v_add_f32_e32 v132, v208, v132
	v_add_f32_e32 v132, v209, v132
	v_add_f32_e32 v132, v210, v132
	v_add_f32_e32 v132, v212, v132
	v_add_f32_e32 v132, v173, v132
	ds_bpermute_b32 v133, v191, v132
	v_mfma_f32_32x32x16_bf16 v[80:95], v[148:151], v[128:131], v[80:95]
	s_waitcnt lgkmcnt(0)
	v_add_f32_e32 v132, v132, v133
	s_waitcnt vmcnt(0)
	v_div_scale_f32 v133, s[0:1], v132, v132, v164
	v_mfma_f32_32x32x16_bf16 v[32:47], v[136:139], v[128:131], v[32:47]
	v_add_f32_e32 v131, v168, v170
	v_add_f32_e32 v131, v171, v131
	v_add_f32_e32 v131, v172, v131
	v_add_f32_e32 v131, v174, v131
	v_add_f32_e32 v131, v176, v131
	v_add_f32_e32 v131, v177, v131
	v_add_f32_e32 v131, v178, v131
	v_add_f32_e32 v131, v179, v131
	v_add_f32_e32 v131, v180, v131
	v_add_f32_e32 v131, v181, v131
	v_lshlrev_b32_e32 v128, 2, v213
	v_add_f32_e32 v131, v196, v131
	v_rcp_f32_e32 v134, v133
	global_load_dword v129, v128, s[54:55] offset:512
	global_load_dword v130, v128, s[54:55] offset:640
	global_load_dword v215, v128, s[54:55] offset:768
	v_add_f32_e32 v131, v197, v131
	v_add_f32_e32 v131, v198, v131
	v_add_f32_e32 v131, v199, v131
	v_add_f32_e32 v131, v200, v131
	v_fma_f32 v140, -v133, v134, 1.0
	v_add_f32_e32 v131, v175, v131
	v_fmac_f32_e32 v134, v140, v134
	v_div_scale_f32 v140, vcc, v164, v132, v164
	ds_bpermute_b32 v135, v191, v131
	v_mul_f32_e32 v141, v140, v134
	v_fma_f32 v142, -v133, v141, v140
	v_fmac_f32_e32 v141, v142, v134
	v_fma_f32 v133, -v133, v141, v140
	v_div_fmas_f32 v133, v133, v134, v141
	v_div_fixup_f32 v132, v133, v132, v164
	s_waitcnt lgkmcnt(0)
	v_add_f32_e32 v133, v131, v135
	v_div_scale_f32 v134, s[0:1], v133, v133, 1.0
	v_rcp_f32_e32 v135, v134
	v_mfma_f32_32x32x16_bf16 v[0:15], v[136:139], v[160:163], v[0:15]
	v_mov_b32_e32 v143, v32
	v_mov_b32_e32 v140, v64
	v_mov_b32_e32 v142, v48
	v_mov_b32_e32 v141, v80
	v_mov_b32_e32 v80, v65
	s_add_u32 s0, s34, s4
	s_addc_u32 s1, s35, s5
	v_mfma_f32_32x32x16_bf16 v[112:127], v[144:147], v[156:159], v[112:127]
	s_nop 3
	v_mov_b32_e32 v146, v0
	v_xor_b32_e32 v0, 16, v214
	v_lshlrev_b32_e32 v164, 1, v213
	global_load_dword v128, v128, s[54:55] offset:896
	s_waitcnt vmcnt(3)
	v_mul_f32_e32 v131, 0x3f24fd5c, v129
	v_mfma_f32_32x32x16_bf16 v[16:31], v[136:139], v[152:155], v[16:31]
	v_fma_f32 v136, -v134, v135, 1.0
	v_fmac_f32_e32 v135, v136, v135
	v_div_scale_f32 v136, vcc, 1.0, v133, 1.0
	v_mul_f32_e32 v137, v136, v135
	v_fma_f32 v138, -v134, v137, v136
	v_fmac_f32_e32 v137, v138, v135
	v_fma_f32 v134, -v134, v137, v136
	v_div_fmas_f32 v134, v134, v135, v137
	v_ashrrev_i32_e32 v135, 3, v167
	v_div_fixup_f32 v133, v134, v133, 1.0
	v_and_b32_e32 v134, -4, v135
	v_mfma_f32_32x32x16_bf16 v[96:111], v[148:151], v[152:155], v[96:111]
	v_cmp_lt_i32_e32 vcc, v0, v187
	v_and_or_b32 v136, v135, 60, v186
	v_mov_b32_e32 v147, v16
	v_cndmask_b32_e32 v16, v214, v0, vcc
	v_lshlrev_b32_e32 v137, 2, v136
	ds_bpermute_b32 v138, v137, v132
	ds_bpermute_b32 v136, v137, v133
	v_mfma_f32_32x32x16_bf16 v[112:127], v[148:151], v[160:163], v[112:127]
	v_or_b32_e32 v150, 1, v134
	v_and_or_b32 v0, v150, 61, v186
	v_lshlrev_b32_e32 v32, 2, v0
	ds_bpermute_b32 v0, v32, v132
	ds_bpermute_b32 v64, v32, v133
	v_mov_b32_e32 v32, v49
	s_waitcnt lgkmcnt(3)
	v_pk_mul_f32 v[142:143], v[142:143], v[138:139] op_sel_hi:[1,0]
	s_nop 3
	v_mov_b32_e32 v144, v112
	v_mov_b32_e32 v145, v96
	v_pk_mul_f32 v[138:139], v[146:147], v[138:139] op_sel_hi:[1,0]
	v_lshlrev_b32_e32 v48, 2, v16
	s_waitcnt lgkmcnt(1)
; DI u16 f2bf(float a) { return (u16)(pk2(a, 0.f) & 0xffffu); }
; DI int crow(int i, int h) { return (i & 3) + 8 * (i >> 2) + 4 * h; }
; __device__ __forceinline__ void attn_item_A(const Params& p, int layer, int head, int q0u, char* lds) {
;     ...
; #pragma unroll
;   for (int e = 0; e < 16; ++e) {
;     const int qq = crow(e, h_e);
;     const float ia = __shfl(iA, qq), ib = __shfl(iB, qq);
;     float ov[4];
;     float ss = 0.f;
; #pragma unroll
;     for (int d = 0; d < 4; ++d) { ov[d] = o1[d][e] * ia - o2[d][e] * ib; ss += ov[d] * ov[d]; }
; #pragma unroll
;     for (int x = 16; x >= 1; x >>= 1) ss += __shfl_xor(ss, x);
;     const float rs = rsqrtf(ss * (1.f / 128.f) + LN_EPS);
;     const size_t rowoff = (size_t)(orow0 + qq) * LDX + ocol + r_e;
; #pragma unroll
;     for (int d = 0; d < 4; ++d) Mx[rowoff + d * 32] = f2bf(ov[d] * rs * sw[d]);
;   }
	v_pk_mul_f32 v[32:33], v[32:33], v[0:1] op_sel_hi:[1,0]
	v_mov_b32_e32 v16, v1
	v_pk_fma_f32 v[140:141], v[140:141], v[136:137], v[142:143] op_sel_hi:[1,0,1] neg_lo:[0,0,1] neg_hi:[0,0,1]
	v_pk_fma_f32 v[136:137], v[144:145], v[136:137], v[138:139] op_sel_hi:[1,0,1] neg_lo:[0,0,1] neg_hi:[0,0,1]
	s_waitcnt lgkmcnt(0)
	v_pk_fma_f32 v[144:145], v[80:81], v[64:65], v[32:33] op_sel_hi:[1,0,1] neg_lo:[0,0,1] neg_hi:[0,0,1]
	v_mov_b32_e32 v96, v113
	v_pk_mul_f32 v[0:1], v[16:17], v[0:1] op_sel_hi:[1,0]
	v_pk_mul_f32 v[142:143], v[140:141], v[140:141]
	v_pk_mul_f32 v[32:33], v[144:145], v[144:145]
	v_pk_fma_f32 v[96:97], v[96:97], v[64:65], v[0:1] op_sel_hi:[1,0,1] neg_lo:[0,0,1] neg_hi:[0,0,1]
	v_pk_mul_f32 v[138:139], v[136:137], v[136:137]
	v_pk_mul_f32 v[0:1], v[96:97], v[96:97]
	v_mov_b32_e32 v16, v32
	v_mov_b32_e32 v17, v142
	v_mov_b32_e32 v142, v33
	v_pk_add_f32 v[16:17], v[16:17], v[142:143]
	v_mov_b32_e32 v32, v1
	v_mov_b32_e32 v33, v139
	v_pk_add_f32 v[16:17], v[32:33], v[16:17]
	v_mov_b32_e32 v1, v138
	v_pk_add_f32 v[0:1], v[0:1], v[16:17]
	ds_bpermute_b32 v17, v48, v1
	ds_bpermute_b32 v16, v48, v0
	v_xor_b32_e32 v32, 8, v214
	v_cmp_lt_i32_e32 vcc, v32, v187
	s_waitcnt vmcnt(2)
	v_mul_f32_e32 v130, 0x3f24fd5c, v130
	s_waitcnt vmcnt(1)
	v_mul_f32_e32 v129, 0x3f24fd5c, v215
	v_cndmask_b32_e32 v32, v214, v32, vcc
	v_lshlrev_b32_e32 v49, 2, v32
	s_waitcnt lgkmcnt(0)
	v_pk_add_f32 v[0:1], v[0:1], v[16:17]
	ds_bpermute_b32 v17, v49, v1
	ds_bpermute_b32 v16, v49, v0
	v_xor_b32_e32 v32, 4, v214
	v_cmp_lt_i32_e32 vcc, v32, v187
	v_or_b32_e32 v152, 2, v134
	v_or_b32_e32 v135, 3, v135
	v_cndmask_b32_e32 v32, v214, v32, vcc
	v_lshlrev_b32_e32 v64, 2, v32
	s_waitcnt lgkmcnt(0)
	v_pk_add_f32 v[0:1], v[0:1], v[16:17]
	ds_bpermute_b32 v17, v64, v1
	ds_bpermute_b32 v16, v64, v0
	v_xor_b32_e32 v32, 2, v214
	v_cmp_lt_i32_e32 vcc, v32, v187
	v_mov_b32_e32 v148, v2
	v_and_or_b32 v2, v135, 63, v186
	v_cndmask_b32_e32 v32, v214, v32, vcc
	v_lshlrev_b32_e32 v65, 2, v32
	s_waitcnt lgkmcnt(0)
	v_pk_add_f32 v[0:1], v[0:1], v[16:17]
	ds_bpermute_b32 v17, v65, v1
	ds_bpermute_b32 v16, v65, v0
	v_xor_b32_e32 v32, 1, v214
	v_cmp_lt_i32_e32 vcc, v32, v187
	v_mov_b32_e32 v149, v18
	v_lshlrev_b32_e32 v18, 2, v2
	v_cndmask_b32_e32 v32, v214, v32, vcc
	v_lshlrev_b32_e32 v80, 2, v32
	s_waitcnt lgkmcnt(0)
	v_pk_add_f32 v[0:1], v[0:1], v[16:17]
	ds_bpermute_b32 v33, v80, v1
	ds_bpermute_b32 v32, v80, v0
	v_lshl_add_u64 v[16:17], s[0:1], 0, v[164:165]
	ds_bpermute_b32 v2, v18, v132
	v_mov_b32_e32 v142, v50
	ds_bpermute_b32 v50, v18, v133
	s_waitcnt lgkmcnt(2)
	v_pk_add_f32 v[0:1], v[0:1], v[32:33]
	v_mov_b64_e32 v[32:33], s[36:37]
	v_pk_fma_f32 v[112:113], v[0:1], s[30:31], v[32:33] op_sel_hi:[1,0,0]
	v_mov_b32_e32 v143, v34
	v_mul_f32_e32 v0, 0x4b800000, v113
	v_cmp_gt_f32_e32 vcc, s81, v113
	v_mov_b32_e32 v34, v51
	s_waitcnt lgkmcnt(1)
	v_pk_mul_f32 v[34:35], v[34:35], v[2:3] op_sel_hi:[1,0]
	v_cndmask_b32_e32 v0, v113, v0, vcc
	v_rsq_f32_e32 v81, v0
	v_add_u32_e32 v0, v134, v190
	v_mad_i64_i32 v[0:1], s[0:1], v0, s78, v[16:17]
	v_mul_f32_e32 v113, 0x45800000, v81
	v_cndmask_b32_e32 v81, v81, v113, vcc
	v_mul_f32_e32 v113, v140, v81
	v_mul_f32_e32 v113, v131, v113
	v_cvt_pk_bf16_f32 v113, v113, s0
	global_store_short v[0:1], v113, off
	v_mul_f32_e32 v113, v141, v81
	v_mul_f32_e32 v113, v130, v113
	v_cvt_pk_bf16_f32 v113, v113, s0
	global_store_short v[0:1], v113, off offset:64
	v_mul_f32_e32 v113, v137, v81
	v_mul_f32_e32 v113, v129, v113
	v_cvt_pk_bf16_f32 v137, v113, s0
	v_mul_f32_e32 v113, 0x4b800000, v112
	v_cmp_gt_f32_e32 vcc, s81, v112
	v_mov_b32_e32 v140, v66
	v_mov_b32_e32 v141, v82
	v_cndmask_b32_e32 v112, v112, v113, vcc
	v_rsq_f32_e32 v151, v112
	v_and_or_b32 v112, v152, 62, v186
	v_lshlrev_b32_e32 v113, 2, v112
	ds_bpermute_b32 v138, v113, v132
	ds_bpermute_b32 v112, v113, v133
	v_mov_b32_e32 v82, v67
	v_mov_b32_e32 v18, v3
	v_mov_b32_e32 v146, v114
	s_waitcnt lgkmcnt(1)
	v_pk_mul_f32 v[142:143], v[142:143], v[138:139] op_sel_hi:[1,0]
	v_mov_b32_e32 v147, v98
	s_waitcnt lgkmcnt(0)
	v_pk_fma_f32 v[140:141], v[140:141], v[112:113], v[142:143] op_sel_hi:[1,0,1] neg_lo:[0,0,1] neg_hi:[0,0,1]
	v_pk_mul_f32 v[138:139], v[148:149], v[138:139] op_sel_hi:[1,0]
	v_pk_fma_f32 v[66:67], v[82:83], v[50:51], v[34:35] op_sel_hi:[1,0,1] neg_lo:[0,0,1] neg_hi:[0,0,1]
	v_mov_b32_e32 v98, v115
	v_pk_mul_f32 v[2:3], v[18:19], v[2:3] op_sel_hi:[1,0]
	v_pk_mul_f32 v[142:143], v[140:141], v[140:141]
	v_pk_fma_f32 v[112:113], v[146:147], v[112:113], v[138:139] op_sel_hi:[1,0,1] neg_lo:[0,0,1] neg_hi:[0,0,1]
	v_pk_mul_f32 v[34:35], v[66:67], v[66:67]
	v_pk_fma_f32 v[50:51], v[98:99], v[50:51], v[2:3] op_sel_hi:[1,0,1] neg_lo:[0,0,1] neg_hi:[0,0,1]
	v_pk_mul_f32 v[138:139], v[112:113], v[112:113]
	v_pk_mul_f32 v[2:3], v[50:51], v[50:51]
	v_mov_b32_e32 v18, v34
	v_mov_b32_e32 v19, v142
	v_mov_b32_e32 v142, v35
	v_pk_add_f32 v[18:19], v[18:19], v[142:143]
	v_mov_b32_e32 v34, v3
	v_mov_b32_e32 v35, v139
	v_pk_add_f32 v[18:19], v[34:35], v[18:19]
	v_mov_b32_e32 v3, v138
	v_pk_add_f32 v[2:3], v[2:3], v[18:19]
	ds_bpermute_b32 v19, v48, v3
	ds_bpermute_b32 v18, v48, v2
	v_mul_f32_e32 v35, 0x45800000, v151
	v_cndmask_b32_e32 v35, v151, v35, vcc
	v_mul_f32_e32 v34, v136, v81
	v_mul_f32_e32 v81, v144, v35
	s_waitcnt lgkmcnt(0)
	v_pk_add_f32 v[18:19], v[2:3], v[18:19]
	ds_bpermute_b32 v83, v49, v19
	ds_bpermute_b32 v82, v49, v18
	v_add_u32_e32 v2, v150, v190
	v_mad_i64_i32 v[2:3], s[0:1], v2, s78, v[16:17]
	v_mul_f32_e32 v81, v131, v81
	s_waitcnt lgkmcnt(0)
	v_pk_add_f32 v[18:19], v[18:19], v[82:83]
	ds_bpermute_b32 v83, v64, v19
	ds_bpermute_b32 v82, v64, v18
	v_cvt_pk_bf16_f32 v81, v81, s0
	global_store_short v[2:3], v81, off
	v_mul_f32_e32 v81, v145, v35
	v_mul_f32_e32 v81, v130, v81
	s_waitcnt lgkmcnt(0)
; DI u16 f2bf(float a) { return (u16)(pk2(a, 0.f) & 0xffffu); }
; DI int crow(int i, int h) { return (i & 3) + 8 * (i >> 2) + 4 * h; }
; __device__ __forceinline__ void attn_item_A(const Params& p, int layer, int head, int q0u, char* lds) {
;     ...
; #pragma unroll
;   for (int e = 0; e < 16; ++e) {
;     const int qq = crow(e, h_e);
;     const float ia = __shfl(iA, qq), ib = __shfl(iB, qq);
;     float ov[4];
;     float ss = 0.f;
; #pragma unroll
;     for (int d = 0; d < 4; ++d) { ov[d] = o1[d][e] * ia - o2[d][e] * ib; ss += ov[d] * ov[d]; }
; #pragma unroll
;     for (int x = 16; x >= 1; x >>= 1) ss += __shfl_xor(ss, x);
;     const float rs = rsqrtf(ss * (1.f / 128.f) + LN_EPS);
;     const size_t rowoff = (size_t)(orow0 + qq) * LDX + ocol + r_e;
; #pragma unroll
;     for (int d = 0; d < 4; ++d) Mx[rowoff + d * 32] = f2bf(ov[d] * rs * sw[d]);
;   }
	v_pk_add_f32 v[18:19], v[18:19], v[82:83]
	ds_bpermute_b32 v83, v65, v19
	ds_bpermute_b32 v82, v65, v18
	v_cvt_pk_bf16_f32 v81, v81, s0
	global_store_short v[2:3], v81, off offset:64
	v_mul_f32_e32 v81, v97, v35
	v_mul_f32_e32 v81, v129, v81
	s_waitcnt lgkmcnt(0)
	v_pk_add_f32 v[18:19], v[18:19], v[82:83]
	ds_bpermute_b32 v83, v80, v19
	ds_bpermute_b32 v82, v80, v18
	v_cvt_pk_bf16_f32 v81, v81, s0
	global_store_short v[2:3], v81, off offset:128
	v_mov_b32_e32 v136, v116
	v_add_u32_e32 v116, 9, v134
	s_waitcnt lgkmcnt(0)
	v_pk_add_f32 v[18:19], v[18:19], v[82:83]
	v_mov_b32_e32 v138, v4
	v_pk_fma_f32 v[82:83], v[18:19], s[30:31], v[32:33] op_sel_hi:[1,0,0]
	v_and_or_b32 v4, v116, 61, v186
	v_mul_f32_e32 v18, 0x4b800000, v83
	v_cmp_gt_f32_e32 vcc, s81, v83
	v_mov_b32_e32 v139, v20
	v_lshlrev_b32_e32 v20, 2, v4
	v_cndmask_b32_e32 v18, v83, v18, vcc
	v_rsq_f32_e32 v81, v18
	v_add_u32_e32 v18, v152, v190
	v_mad_i64_i32 v[18:19], s[0:1], v18, s78, v[16:17]
	v_mul_f32_e32 v83, 0x45800000, v81
	v_cndmask_b32_e32 v81, v81, v83, vcc
	v_mul_f32_e32 v83, v140, v81
	v_mul_f32_e32 v83, v131, v83
	v_cvt_pk_bf16_f32 v83, v83, s0
	global_store_short v[18:19], v83, off
	v_mul_f32_e32 v83, v141, v81
	v_mul_f32_e32 v83, v130, v83
	v_cvt_pk_bf16_f32 v83, v83, s0
	global_store_short v[18:19], v83, off offset:64
	v_mul_f32_e32 v83, v113, v81
	v_mul_f32_e32 v83, v129, v83
	v_cvt_pk_bf16_f32 v113, v83, s0
	v_mul_f32_e32 v83, 0x4b800000, v82
	v_cmp_gt_f32_e32 vcc, s81, v82
	v_add_u32_e32 v141, 8, v134
	v_mul_f32_e32 v35, v96, v35
	v_cndmask_b32_e32 v82, v82, v83, vcc
	v_rsq_f32_e32 v140, v82
	v_and_or_b32 v82, v141, 60, v186
	v_lshlrev_b32_e32 v83, 2, v82
	ds_bpermute_b32 v96, v83, v132
	ds_bpermute_b32 v4, v20, v132
	ds_bpermute_b32 v82, v83, v133
	v_mov_b32_e32 v114, v52
	ds_bpermute_b32 v52, v20, v133
	v_mov_b32_e32 v115, v36
	v_mov_b32_e32 v36, v53
	v_mov_b32_e32 v98, v68
	v_mov_b32_e32 v99, v84
	s_waitcnt lgkmcnt(3)
	v_pk_mul_f32 v[114:115], v[114:115], v[96:97] op_sel_hi:[1,0]
	v_mov_b32_e32 v84, v69
	s_waitcnt lgkmcnt(2)
	v_pk_mul_f32 v[36:37], v[36:37], v[4:5] op_sel_hi:[1,0]
	v_mov_b32_e32 v20, v5
	global_store_short v[0:1], v137, off offset:128
	s_waitcnt lgkmcnt(1)
	v_pk_fma_f32 v[98:99], v[98:99], v[82:83], v[114:115] op_sel_hi:[1,0,1] neg_lo:[0,0,1] neg_hi:[0,0,1]
	v_mov_b32_e32 v137, v100
	v_pk_mul_f32 v[96:97], v[138:139], v[96:97] op_sel_hi:[1,0]
	s_waitcnt lgkmcnt(0)
	v_pk_fma_f32 v[68:69], v[84:85], v[52:53], v[36:37] op_sel_hi:[1,0,1] neg_lo:[0,0,1] neg_hi:[0,0,1]
	v_mov_b32_e32 v100, v117
	v_pk_mul_f32 v[4:5], v[20:21], v[4:5] op_sel_hi:[1,0]
	v_pk_mul_f32 v[114:115], v[98:99], v[98:99]
	v_pk_fma_f32 v[82:83], v[136:137], v[82:83], v[96:97] op_sel_hi:[1,0,1] neg_lo:[0,0,1] neg_hi:[0,0,1]
	v_pk_mul_f32 v[36:37], v[68:69], v[68:69]
	v_pk_fma_f32 v[52:53], v[100:101], v[52:53], v[4:5] op_sel_hi:[1,0,1] neg_lo:[0,0,1] neg_hi:[0,0,1]
	v_pk_mul_f32 v[96:97], v[82:83], v[82:83]
	v_pk_mul_f32 v[4:5], v[52:53], v[52:53]
	v_mov_b32_e32 v20, v36
	v_mov_b32_e32 v21, v114
	v_mov_b32_e32 v114, v37
	v_pk_add_f32 v[20:21], v[20:21], v[114:115]
	v_mov_b32_e32 v36, v5
	v_mov_b32_e32 v37, v97
	v_pk_add_f32 v[20:21], v[36:37], v[20:21]
	v_mov_b32_e32 v5, v96
	v_pk_add_f32 v[4:5], v[4:5], v[20:21]
	ds_bpermute_b32 v21, v48, v5
	ds_bpermute_b32 v20, v48, v4
	v_mul_f32_e32 v37, 0x45800000, v140
	v_cndmask_b32_e32 v37, v140, v37, vcc
	v_mul_f32_e32 v66, v66, v37
	v_mul_f32_e32 v66, v131, v66
	s_waitcnt lgkmcnt(0)
	v_pk_add_f32 v[20:21], v[4:5], v[20:21]
	ds_bpermute_b32 v85, v49, v21
	ds_bpermute_b32 v84, v49, v20
	v_add_u32_e32 v4, v135, v190
	v_mad_i64_i32 v[4:5], s[0:1], v4, s78, v[16:17]
	v_mul_f32_e32 v36, v112, v81
	s_waitcnt lgkmcnt(0)
	v_pk_add_f32 v[20:21], v[20:21], v[84:85]
	ds_bpermute_b32 v85, v64, v21
	ds_bpermute_b32 v84, v64, v20
	v_cvt_pk_bf16_f32 v66, v66, s0
	global_store_short v[4:5], v66, off
	v_mul_f32_e32 v81, v67, v37
	v_mul_f32_e32 v51, v51, v37
	s_waitcnt lgkmcnt(0)
	v_pk_add_f32 v[20:21], v[20:21], v[84:85]
	ds_bpermute_b32 v67, v65, v21
	ds_bpermute_b32 v66, v65, v20
	v_mul_f32_e32 v51, v129, v51
	v_cvt_pk_bf16_f32 v51, v51, s0
	global_store_short v[4:5], v51, off offset:128
	v_mul_f32_e32 v37, v50, v37
	s_waitcnt lgkmcnt(0)
	v_pk_add_f32 v[20:21], v[20:21], v[66:67]
	ds_bpermute_b32 v67, v80, v21
	ds_bpermute_b32 v66, v80, v20
	v_mul_f32_e32 v81, v130, v81
	v_cvt_pk_bf16_f32 v81, v81, s0
	global_store_short v[4:5], v81, off offset:64
	global_store_short v[18:19], v113, off offset:128
	s_waitcnt lgkmcnt(0)
	v_pk_add_f32 v[20:21], v[20:21], v[66:67]
	v_add_u32_e32 v113, 10, v134
	v_pk_fma_f32 v[50:51], v[20:21], s[30:31], v[32:33] op_sel_hi:[1,0,0]
	v_mov_b32_e32 v96, v54
	v_mul_f32_e32 v20, 0x4b800000, v51
	v_cmp_gt_f32_e32 vcc, s81, v51
	v_mov_b32_e32 v97, v38
	v_mov_b32_e32 v100, v6
	v_cndmask_b32_e32 v20, v51, v20, vcc
	v_rsq_f32_e32 v51, v20
	v_add_u32_e32 v20, v141, v190
	v_mad_i64_i32 v[20:21], s[0:1], v20, s78, v[16:17]
	v_mul_f32_e32 v66, 0x45800000, v51
	v_cndmask_b32_e32 v81, v51, v66, vcc
	v_mul_f32_e32 v51, v98, v81
	v_mul_f32_e32 v51, v131, v51
	v_cvt_pk_bf16_f32 v51, v51, s0
	global_store_short v[20:21], v51, off
	v_mul_f32_e32 v51, v99, v81
	v_mul_f32_e32 v51, v130, v51
	v_cvt_pk_bf16_f32 v51, v51, s0
	global_store_short v[20:21], v51, off offset:64
	v_mul_f32_e32 v51, v83, v81
	v_mul_f32_e32 v51, v129, v51
	v_cvt_pk_bf16_f32 v83, v51, s0
	v_mul_f32_e32 v51, 0x4b800000, v50
	v_cmp_gt_f32_e32 vcc, s81, v50
	v_mov_b32_e32 v101, v22
	v_mov_b32_e32 v84, v70
	v_cndmask_b32_e32 v50, v50, v51, vcc
	v_rsq_f32_e32 v112, v50
	v_and_or_b32 v50, v113, 62, v186
	v_lshlrev_b32_e32 v51, 2, v50
	ds_bpermute_b32 v66, v51, v132
	ds_bpermute_b32 v50, v51, v133
	v_mov_b32_e32 v85, v86
	v_mov_b32_e32 v98, v118
	v_mov_b32_e32 v99, v102
	s_waitcnt lgkmcnt(1)
; DI u16 f2bf(float a) { return (u16)(pk2(a, 0.f) & 0xffffu); }
; DI int crow(int i, int h) { return (i & 3) + 8 * (i >> 2) + 4 * h; }
; __device__ __forceinline__ void attn_item_A(const Params& p, int layer, int head, int q0u, char* lds) {
;     ...
; #pragma unroll
;   for (int e = 0; e < 16; ++e) {
;     const int qq = crow(e, h_e);
;     const float ia = __shfl(iA, qq), ib = __shfl(iB, qq);
;     float ov[4];
;     float ss = 0.f;
; #pragma unroll
;     for (int d = 0; d < 4; ++d) { ov[d] = o1[d][e] * ia - o2[d][e] * ib; ss += ov[d] * ov[d]; }
; #pragma unroll
;     for (int x = 16; x >= 1; x >>= 1) ss += __shfl_xor(ss, x);
;     const float rs = rsqrtf(ss * (1.f / 128.f) + LN_EPS);
;     const size_t rowoff = (size_t)(orow0 + qq) * LDX + ocol + r_e;
; #pragma unroll
;     for (int d = 0; d < 4; ++d) Mx[rowoff + d * 32] = f2bf(ov[d] * rs * sw[d]);
;   }
	v_pk_mul_f32 v[96:97], v[96:97], v[66:67] op_sel_hi:[1,0]
	v_pk_mul_f32 v[66:67], v[100:101], v[66:67] op_sel_hi:[1,0]
	s_waitcnt lgkmcnt(0)
	v_pk_fma_f32 v[84:85], v[84:85], v[50:51], v[96:97] op_sel_hi:[1,0,1] neg_lo:[0,0,1] neg_hi:[0,0,1]
	v_pk_fma_f32 v[50:51], v[98:99], v[50:51], v[66:67] op_sel_hi:[1,0,1] neg_lo:[0,0,1] neg_hi:[0,0,1]
	v_add_u32_e32 v98, 11, v134
	v_and_or_b32 v6, v98, 63, v186
	v_lshlrev_b32_e32 v22, 2, v6
	ds_bpermute_b32 v6, v22, v132
	ds_bpermute_b32 v54, v22, v133
	v_mov_b32_e32 v38, v55
	v_mov_b32_e32 v86, v71
	v_mov_b32_e32 v22, v7
	s_waitcnt lgkmcnt(1)
	v_pk_mul_f32 v[38:39], v[38:39], v[6:7] op_sel_hi:[1,0]
	v_mov_b32_e32 v102, v119
	s_waitcnt lgkmcnt(0)
	v_pk_fma_f32 v[70:71], v[86:87], v[54:55], v[38:39] op_sel_hi:[1,0,1] neg_lo:[0,0,1] neg_hi:[0,0,1]
	v_pk_mul_f32 v[6:7], v[22:23], v[6:7] op_sel_hi:[1,0]
	v_pk_mul_f32 v[96:97], v[84:85], v[84:85]
	v_pk_mul_f32 v[38:39], v[70:71], v[70:71]
	v_pk_fma_f32 v[54:55], v[102:103], v[54:55], v[6:7] op_sel_hi:[1,0,1] neg_lo:[0,0,1] neg_hi:[0,0,1]
	v_pk_mul_f32 v[66:67], v[50:51], v[50:51]
	v_pk_mul_f32 v[6:7], v[54:55], v[54:55]
	v_mov_b32_e32 v22, v38
	v_mov_b32_e32 v23, v96
	v_mov_b32_e32 v96, v39
	v_pk_add_f32 v[22:23], v[22:23], v[96:97]
	v_mov_b32_e32 v38, v7
	v_mov_b32_e32 v39, v67
	v_pk_add_f32 v[22:23], v[38:39], v[22:23]
	v_mov_b32_e32 v7, v66
	v_pk_add_f32 v[6:7], v[6:7], v[22:23]
	ds_bpermute_b32 v23, v48, v7
	ds_bpermute_b32 v22, v48, v6
	v_mul_f32_e32 v39, 0x45800000, v112
	v_cndmask_b32_e32 v39, v112, v39, vcc
	v_mul_f32_e32 v68, v68, v39
	v_mul_f32_e32 v53, v53, v39
	s_waitcnt lgkmcnt(0)
	v_pk_add_f32 v[22:23], v[6:7], v[22:23]
	ds_bpermute_b32 v67, v49, v23
	ds_bpermute_b32 v66, v49, v22
	v_add_u32_e32 v6, v116, v190
	v_mad_i64_i32 v[6:7], s[0:1], v6, s78, v[16:17]
	v_mul_f32_e32 v68, v131, v68
	s_waitcnt lgkmcnt(0)
	v_pk_add_f32 v[22:23], v[22:23], v[66:67]
	ds_bpermute_b32 v67, v64, v23
	ds_bpermute_b32 v66, v64, v22
	v_mul_f32_e32 v53, v129, v53
	v_cvt_pk_bf16_f32 v68, v68, s0
	v_cvt_pk_bf16_f32 v53, v53, s0
	global_store_short v[6:7], v68, off
	s_waitcnt lgkmcnt(0)
	v_pk_add_f32 v[22:23], v[22:23], v[66:67]
	ds_bpermute_b32 v67, v65, v23
	ds_bpermute_b32 v66, v65, v22
	v_mul_f32_e32 v68, v69, v39
	global_store_short v[6:7], v53, off offset:128
	v_mul_f32_e32 v39, v52, v39
	v_mul_f32_e32 v38, v82, v81
	s_waitcnt lgkmcnt(0)
	v_pk_add_f32 v[22:23], v[22:23], v[66:67]
	ds_bpermute_b32 v67, v80, v23
	ds_bpermute_b32 v66, v80, v22
	v_mul_f32_e32 v68, v130, v68
	v_cvt_pk_bf16_f32 v68, v68, s0
	v_add_u32_e32 v97, 16, v134
	global_store_short v[20:21], v83, off offset:128
	s_waitcnt lgkmcnt(0)
	v_pk_add_f32 v[22:23], v[22:23], v[66:67]
	v_mov_b32_e32 v82, v56
	v_pk_fma_f32 v[52:53], v[22:23], s[30:31], v[32:33] op_sel_hi:[1,0,0]
	v_mov_b32_e32 v83, v40
	v_mul_f32_e32 v22, 0x4b800000, v53
	v_cmp_gt_f32_e32 vcc, s81, v53
	v_mov_b32_e32 v86, v8
	v_mov_b32_e32 v87, v24
	v_cndmask_b32_e32 v22, v53, v22, vcc
	v_rsq_f32_e32 v53, v22
	v_add_u32_e32 v22, v113, v190
	v_mad_i64_i32 v[22:23], s[0:1], v22, s78, v[16:17]
	v_mul_f32_e32 v66, 0x45800000, v53
	v_cndmask_b32_e32 v81, v53, v66, vcc
	v_mul_f32_e32 v53, v84, v81
	v_mul_f32_e32 v53, v131, v53
	v_cvt_pk_bf16_f32 v53, v53, s0
	global_store_short v[22:23], v53, off
	v_mul_f32_e32 v53, v85, v81
	v_mul_f32_e32 v53, v130, v53
	v_cvt_pk_bf16_f32 v53, v53, s0
	global_store_short v[22:23], v53, off offset:64
	v_mul_f32_e32 v53, 0x4b800000, v52
	v_cmp_gt_f32_e32 vcc, s81, v52
	global_store_short v[6:7], v68, off offset:64
	v_mov_b32_e32 v68, v72
	v_cndmask_b32_e32 v52, v52, v53, vcc
	v_rsq_f32_e32 v96, v52
	v_and_or_b32 v52, v97, 60, v186
	v_lshlrev_b32_e32 v53, 2, v52
	ds_bpermute_b32 v66, v53, v132
	ds_bpermute_b32 v52, v53, v133
	v_mov_b32_e32 v69, v88
	v_mov_b32_e32 v84, v120
	v_mov_b32_e32 v85, v104
	s_waitcnt lgkmcnt(1)
	v_pk_mul_f32 v[82:83], v[82:83], v[66:67] op_sel_hi:[1,0]
	v_pk_mul_f32 v[66:67], v[86:87], v[66:67] op_sel_hi:[1,0]
	s_waitcnt lgkmcnt(0)
	v_pk_fma_f32 v[68:69], v[68:69], v[52:53], v[82:83] op_sel_hi:[1,0,1] neg_lo:[0,0,1] neg_hi:[0,0,1]
	v_pk_fma_f32 v[52:53], v[84:85], v[52:53], v[66:67] op_sel_hi:[1,0,1] neg_lo:[0,0,1] neg_hi:[0,0,1]
	v_add_u32_e32 v84, 17, v134
	v_and_or_b32 v8, v84, 61, v186
	v_lshlrev_b32_e32 v24, 2, v8
	ds_bpermute_b32 v8, v24, v132
	ds_bpermute_b32 v56, v24, v133
	v_mov_b32_e32 v40, v57
	v_mov_b32_e32 v88, v73
	v_mov_b32_e32 v24, v9
	s_waitcnt lgkmcnt(1)
	v_pk_mul_f32 v[40:41], v[40:41], v[8:9] op_sel_hi:[1,0]
	v_mov_b32_e32 v104, v121
	s_waitcnt lgkmcnt(0)
	v_pk_fma_f32 v[72:73], v[88:89], v[56:57], v[40:41] op_sel_hi:[1,0,1] neg_lo:[0,0,1] neg_hi:[0,0,1]
	v_pk_mul_f32 v[8:9], v[24:25], v[8:9] op_sel_hi:[1,0]
	v_pk_mul_f32 v[82:83], v[68:69], v[68:69]
	v_pk_mul_f32 v[40:41], v[72:73], v[72:73]
	v_pk_fma_f32 v[56:57], v[104:105], v[56:57], v[8:9] op_sel_hi:[1,0,1] neg_lo:[0,0,1] neg_hi:[0,0,1]
	v_pk_mul_f32 v[66:67], v[52:53], v[52:53]
	v_pk_mul_f32 v[8:9], v[56:57], v[56:57]
	v_mov_b32_e32 v24, v40
	v_mov_b32_e32 v25, v82
	v_mov_b32_e32 v82, v41
	v_pk_add_f32 v[24:25], v[24:25], v[82:83]
	v_mov_b32_e32 v40, v9
	v_mov_b32_e32 v41, v67
	v_pk_add_f32 v[24:25], v[40:41], v[24:25]
	v_mov_b32_e32 v9, v66
	v_pk_add_f32 v[8:9], v[8:9], v[24:25]
	ds_bpermute_b32 v25, v48, v9
	ds_bpermute_b32 v24, v48, v8
	v_mul_f32_e32 v51, v51, v81
	v_mul_f32_e32 v51, v129, v51
	v_cvt_pk_bf16_f32 v51, v51, s0
	global_store_short v[22:23], v51, off offset:128
	s_waitcnt lgkmcnt(0)
	v_pk_add_f32 v[24:25], v[8:9], v[24:25]
	v_mul_f32_e32 v40, v50, v81
	ds_bpermute_b32 v51, v49, v25
	ds_bpermute_b32 v50, v49, v24
	v_mul_f32_e32 v41, 0x45800000, v96
	v_cndmask_b32_e32 v41, v96, v41, vcc
	v_add_u32_e32 v8, v98, v190
	v_mul_f32_e32 v66, v70, v41
	s_waitcnt lgkmcnt(0)
; DI u16 f2bf(float a) { return (u16)(pk2(a, 0.f) & 0xffffu); }
; DI int crow(int i, int h) { return (i & 3) + 8 * (i >> 2) + 4 * h; }
; __device__ __forceinline__ void attn_item_A(const Params& p, int layer, int head, int q0u, char* lds) {
;     ...
; #pragma unroll
;   for (int e = 0; e < 16; ++e) {
;     const int qq = crow(e, h_e);
;     const float ia = __shfl(iA, qq), ib = __shfl(iB, qq);
;     float ov[4];
;     float ss = 0.f;
; #pragma unroll
;     for (int d = 0; d < 4; ++d) { ov[d] = o1[d][e] * ia - o2[d][e] * ib; ss += ov[d] * ov[d]; }
; #pragma unroll
;     for (int x = 16; x >= 1; x >>= 1) ss += __shfl_xor(ss, x);
;     const float rs = rsqrtf(ss * (1.f / 128.f) + LN_EPS);
;     const size_t rowoff = (size_t)(orow0 + qq) * LDX + ocol + r_e;
; #pragma unroll
;     for (int d = 0; d < 4; ++d) Mx[rowoff + d * 32] = f2bf(ov[d] * rs * sw[d]);
;   }
	v_pk_add_f32 v[24:25], v[24:25], v[50:51]
	ds_bpermute_b32 v51, v64, v25
	ds_bpermute_b32 v50, v64, v24
	v_mad_i64_i32 v[8:9], s[0:1], v8, s78, v[16:17]
	v_mul_f32_e32 v66, v131, v66
	s_nop 0
	v_cvt_pk_bf16_f32 v66, v66, s0
	s_waitcnt lgkmcnt(0)
	v_pk_add_f32 v[24:25], v[24:25], v[50:51]
	ds_bpermute_b32 v51, v65, v25
	ds_bpermute_b32 v50, v65, v24
	global_store_short v[8:9], v66, off
	v_mul_f32_e32 v66, v71, v41
	v_mul_f32_e32 v55, v55, v41
	v_mul_f32_e32 v41, v54, v41
	s_waitcnt lgkmcnt(0)
	v_pk_add_f32 v[24:25], v[24:25], v[50:51]
	ds_bpermute_b32 v51, v80, v25
	ds_bpermute_b32 v50, v80, v24
	v_mul_f32_e32 v66, v130, v66
	v_mul_f32_e32 v55, v129, v55
	v_cvt_pk_bf16_f32 v66, v66, s0
	v_cvt_pk_bf16_f32 v55, v55, s0
	s_waitcnt lgkmcnt(0)
	v_pk_add_f32 v[24:25], v[24:25], v[50:51]
	v_add_u32_e32 v86, 18, v134
	v_pk_fma_f32 v[50:51], v[24:25], s[30:31], v[32:33] op_sel_hi:[1,0,0]
	global_store_short v[8:9], v66, off offset:64
	v_mul_f32_e32 v24, 0x4b800000, v51
	v_cmp_gt_f32_e32 vcc, s81, v51
	v_mov_b32_e32 v66, v74
	v_add_u32_e32 v74, 19, v134
	v_cndmask_b32_e32 v24, v51, v24, vcc
	v_rsq_f32_e32 v51, v24
	v_add_u32_e32 v24, v97, v190
	v_mad_i64_i32 v[24:25], s[0:1], v24, s78, v[16:17]
	v_mul_f32_e32 v54, 0x45800000, v51
	v_cndmask_b32_e32 v81, v51, v54, vcc
	v_mul_f32_e32 v51, v68, v81
	v_mul_f32_e32 v51, v131, v51
	v_cvt_pk_bf16_f32 v51, v51, s0
	global_store_short v[24:25], v51, off
	v_mul_f32_e32 v51, v69, v81
	v_mul_f32_e32 v51, v130, v51
	v_cvt_pk_bf16_f32 v51, v51, s0
	global_store_short v[24:25], v51, off offset:64
	v_mul_f32_e32 v51, v53, v81
	v_mul_f32_e32 v51, v129, v51
	v_cvt_pk_bf16_f32 v53, v51, s0
	v_mul_f32_e32 v51, 0x4b800000, v50
	v_cmp_gt_f32_e32 vcc, s81, v50
	v_mov_b32_e32 v82, v10
	v_and_or_b32 v10, v74, 63, v186
	v_cndmask_b32_e32 v50, v50, v51, vcc
	v_rsq_f32_e32 v85, v50
	v_and_or_b32 v50, v86, 62, v186
	v_lshlrev_b32_e32 v51, 2, v50
	ds_bpermute_b32 v54, v51, v132
	ds_bpermute_b32 v50, v51, v133
	v_mov_b32_e32 v68, v58
	v_mov_b32_e32 v69, v42
	v_mov_b32_e32 v83, v26
	v_lshlrev_b32_e32 v26, 2, v10
	global_store_short v[8:9], v55, off offset:128
	v_mov_b32_e32 v67, v90
	s_waitcnt lgkmcnt(1)
	v_pk_mul_f32 v[68:69], v[68:69], v[54:55] op_sel_hi:[1,0]
	v_mov_b32_e32 v70, v122
	v_mov_b32_e32 v71, v106
	v_pk_mul_f32 v[54:55], v[82:83], v[54:55] op_sel_hi:[1,0]
	ds_bpermute_b32 v10, v26, v132
	s_waitcnt lgkmcnt(1)
	v_pk_fma_f32 v[66:67], v[66:67], v[50:51], v[68:69] op_sel_hi:[1,0,1] neg_lo:[0,0,1] neg_hi:[0,0,1]
	v_pk_fma_f32 v[50:51], v[70:71], v[50:51], v[54:55] op_sel_hi:[1,0,1] neg_lo:[0,0,1] neg_hi:[0,0,1]
	ds_bpermute_b32 v54, v26, v133
	v_mov_b32_e32 v42, v59
	v_mov_b32_e32 v90, v75
	s_waitcnt lgkmcnt(1)
	v_pk_mul_f32 v[42:43], v[42:43], v[10:11] op_sel_hi:[1,0]
	v_mov_b32_e32 v26, v11
	s_waitcnt lgkmcnt(0)
	v_pk_fma_f32 v[42:43], v[90:91], v[54:55], v[42:43] op_sel_hi:[1,0,1] neg_lo:[0,0,1] neg_hi:[0,0,1]
	v_mov_b32_e32 v106, v123
	v_pk_mul_f32 v[10:11], v[26:27], v[10:11] op_sel_hi:[1,0]
	v_pk_mul_f32 v[68:69], v[66:67], v[66:67]
	v_pk_mul_f32 v[58:59], v[42:43], v[42:43]
	v_pk_fma_f32 v[54:55], v[106:107], v[54:55], v[10:11] op_sel_hi:[1,0,1] neg_lo:[0,0,1] neg_hi:[0,0,1]
	v_pk_mul_f32 v[70:71], v[50:51], v[50:51]
	v_pk_mul_f32 v[10:11], v[54:55], v[54:55]
	v_mov_b32_e32 v26, v58
	v_mov_b32_e32 v27, v68
	v_mov_b32_e32 v68, v59
	v_pk_add_f32 v[26:27], v[26:27], v[68:69]
	v_mov_b32_e32 v58, v11
	v_mov_b32_e32 v59, v71
	v_pk_add_f32 v[26:27], v[58:59], v[26:27]
	v_mov_b32_e32 v11, v70
	v_pk_add_f32 v[10:11], v[10:11], v[26:27]
	ds_bpermute_b32 v27, v48, v11
	ds_bpermute_b32 v26, v48, v10
	v_mul_f32_e32 v75, v52, v81
	v_mul_f32_e32 v52, 0x45800000, v85
	global_store_short v[24:25], v53, off offset:128
	v_cndmask_b32_e32 v58, v85, v52, vcc
	s_waitcnt lgkmcnt(0)
	v_pk_add_f32 v[26:27], v[10:11], v[26:27]
	ds_bpermute_b32 v53, v49, v27
	ds_bpermute_b32 v52, v49, v26
	v_add_u32_e32 v10, v84, v190
	v_mul_f32_e32 v59, v72, v58
	v_mad_i64_i32 v[10:11], s[0:1], v10, s78, v[16:17]
	s_waitcnt lgkmcnt(0)
	v_pk_add_f32 v[26:27], v[26:27], v[52:53]
	ds_bpermute_b32 v53, v64, v27
	ds_bpermute_b32 v52, v64, v26
	v_mul_f32_e32 v59, v131, v59
	v_cvt_pk_bf16_f32 v59, v59, s0
	v_mul_f32_e32 v72, v56, v58
	global_store_short v[10:11], v59, off
	s_waitcnt lgkmcnt(0)
	v_pk_add_f32 v[26:27], v[26:27], v[52:53]
	ds_bpermute_b32 v53, v65, v27
	ds_bpermute_b32 v52, v65, v26
	v_mul_f32_e32 v59, v73, v58
	v_mul_f32_e32 v57, v57, v58
	v_mul_f32_e32 v59, v130, v59
	v_mul_f32_e32 v57, v129, v57
	s_waitcnt lgkmcnt(0)
	v_pk_add_f32 v[26:27], v[26:27], v[52:53]
	ds_bpermute_b32 v53, v80, v27
	ds_bpermute_b32 v52, v80, v26
	v_cvt_pk_bf16_f32 v59, v59, s0
	v_cvt_pk_bf16_f32 v57, v57, s0
	v_add_u32_e32 v82, 24, v134
	v_mov_b32_e32 v70, v12
	s_waitcnt lgkmcnt(0)
	v_pk_add_f32 v[26:27], v[26:27], v[52:53]
	v_mov_b32_e32 v71, v28
	v_pk_fma_f32 v[52:53], v[26:27], s[30:31], v[32:33] op_sel_hi:[1,0,0]
	global_store_short v[10:11], v57, off offset:128
	v_mul_f32_e32 v26, 0x4b800000, v53
	v_cmp_gt_f32_e32 vcc, s81, v53
	global_store_short v[10:11], v59, off offset:64
	v_mov_b32_e32 v58, v76
	v_cndmask_b32_e32 v26, v53, v26, vcc
	v_rsq_f32_e32 v53, v26
	v_add_u32_e32 v26, v86, v190
	v_mad_i64_i32 v[26:27], s[0:1], v26, s78, v[16:17]
	v_mul_f32_e32 v56, 0x45800000, v53
	v_cndmask_b32_e32 v73, v53, v56, vcc
	v_mul_f32_e32 v53, v66, v73
	v_mul_f32_e32 v53, v131, v53
	v_cvt_pk_bf16_f32 v53, v53, s0
	global_store_short v[26:27], v53, off
	v_mul_f32_e32 v53, v67, v73
	v_mul_f32_e32 v53, v130, v53
	v_cvt_pk_bf16_f32 v53, v53, s0
	global_store_short v[26:27], v53, off offset:64
	v_mul_f32_e32 v53, 0x4b800000, v52
	v_cmp_gt_f32_e32 vcc, s81, v52
	v_mov_b32_e32 v66, v60
	v_mov_b32_e32 v67, v44
	v_cndmask_b32_e32 v52, v52, v53, vcc
	v_rsq_f32_e32 v81, v52
	v_and_or_b32 v52, v82, 60, v186
	v_lshlrev_b32_e32 v53, 2, v52
	ds_bpermute_b32 v56, v53, v132
	ds_bpermute_b32 v52, v53, v133
	v_mov_b32_e32 v59, v92
	v_mov_b32_e32 v68, v124
	v_mov_b32_e32 v69, v108
	s_waitcnt lgkmcnt(1)
; DI u16 f2bf(float a) { return (u16)(pk2(a, 0.f) & 0xffffu); }
; DI int crow(int i, int h) { return (i & 3) + 8 * (i >> 2) + 4 * h; }
; __device__ __forceinline__ void attn_item_A(const Params& p, int layer, int head, int q0u, char* lds) {
;     ...
; #pragma unroll
;   for (int e = 0; e < 16; ++e) {
;     const int qq = crow(e, h_e);
;     const float ia = __shfl(iA, qq), ib = __shfl(iB, qq);
;     float ov[4];
;     float ss = 0.f;
; #pragma unroll
;     for (int d = 0; d < 4; ++d) { ov[d] = o1[d][e] * ia - o2[d][e] * ib; ss += ov[d] * ov[d]; }
; #pragma unroll
;     for (int x = 16; x >= 1; x >>= 1) ss += __shfl_xor(ss, x);
;     const float rs = rsqrtf(ss * (1.f / 128.f) + LN_EPS);
;     const size_t rowoff = (size_t)(orow0 + qq) * LDX + ocol + r_e;
; #pragma unroll
;     for (int d = 0; d < 4; ++d) Mx[rowoff + d * 32] = f2bf(ov[d] * rs * sw[d]);
;   }
	v_pk_mul_f32 v[66:67], v[66:67], v[56:57] op_sel_hi:[1,0]
	v_pk_mul_f32 v[56:57], v[70:71], v[56:57] op_sel_hi:[1,0]
	v_add_u32_e32 v70, 25, v134
	v_and_or_b32 v12, v70, 61, v186
	v_lshlrev_b32_e32 v28, 2, v12
	ds_bpermute_b32 v12, v28, v132
	s_waitcnt lgkmcnt(1)
	v_pk_fma_f32 v[58:59], v[58:59], v[52:53], v[66:67] op_sel_hi:[1,0,1] neg_lo:[0,0,1] neg_hi:[0,0,1]
	v_pk_fma_f32 v[52:53], v[68:69], v[52:53], v[56:57] op_sel_hi:[1,0,1] neg_lo:[0,0,1] neg_hi:[0,0,1]
	ds_bpermute_b32 v56, v28, v133
	v_mov_b32_e32 v44, v61
	v_mov_b32_e32 v92, v77
	s_waitcnt lgkmcnt(1)
	v_pk_mul_f32 v[44:45], v[44:45], v[12:13] op_sel_hi:[1,0]
	v_mov_b32_e32 v28, v13
	s_waitcnt lgkmcnt(0)
	v_pk_fma_f32 v[44:45], v[92:93], v[56:57], v[44:45] op_sel_hi:[1,0,1] neg_lo:[0,0,1] neg_hi:[0,0,1]
	v_mov_b32_e32 v108, v125
	v_pk_mul_f32 v[12:13], v[28:29], v[12:13] op_sel_hi:[1,0]
	v_pk_mul_f32 v[66:67], v[58:59], v[58:59]
	v_pk_mul_f32 v[60:61], v[44:45], v[44:45]
	v_pk_fma_f32 v[28:29], v[108:109], v[56:57], v[12:13] op_sel_hi:[1,0,1] neg_lo:[0,0,1] neg_hi:[0,0,1]
	v_pk_mul_f32 v[68:69], v[52:53], v[52:53]
	v_pk_mul_f32 v[12:13], v[28:29], v[28:29]
	v_mov_b32_e32 v56, v60
	v_mov_b32_e32 v57, v66
	v_mov_b32_e32 v66, v61
	v_pk_add_f32 v[56:57], v[56:57], v[66:67]
	v_mov_b32_e32 v60, v13
	v_mov_b32_e32 v61, v69
	v_pk_add_f32 v[56:57], v[60:61], v[56:57]
	v_mov_b32_e32 v13, v68
	v_pk_add_f32 v[12:13], v[12:13], v[56:57]
	ds_bpermute_b32 v57, v48, v13
	ds_bpermute_b32 v56, v48, v12
	v_mul_f32_e32 v51, v51, v73
	v_mul_f32_e32 v51, v129, v51
	v_cvt_pk_bf16_f32 v51, v51, s0
	v_mul_f32_e32 v68, v50, v73
	v_mul_f32_e32 v50, 0x45800000, v81
	global_store_short v[26:27], v51, off offset:128
	v_cndmask_b32_e32 v60, v81, v50, vcc
	s_waitcnt lgkmcnt(0)
	v_pk_add_f32 v[50:51], v[12:13], v[56:57]
	ds_bpermute_b32 v57, v49, v51
	ds_bpermute_b32 v56, v49, v50
	v_add_u32_e32 v12, v74, v190
	v_mul_f32_e32 v42, v42, v60
	v_mad_i64_i32 v[12:13], s[0:1], v12, s78, v[16:17]
	s_waitcnt lgkmcnt(0)
	v_pk_add_f32 v[50:51], v[50:51], v[56:57]
	ds_bpermute_b32 v57, v64, v51
	ds_bpermute_b32 v56, v64, v50
	v_mul_f32_e32 v42, v131, v42
	v_cvt_pk_bf16_f32 v42, v42, s0
	global_store_short v[12:13], v42, off
	v_mul_f32_e32 v61, v43, v60
	s_waitcnt lgkmcnt(0)
	v_pk_add_f32 v[42:43], v[50:51], v[56:57]
	ds_bpermute_b32 v51, v65, v43
	ds_bpermute_b32 v50, v65, v42
	v_mul_f32_e32 v69, v54, v60
	v_mul_f32_e32 v55, v55, v60
	v_mul_f32_e32 v56, v130, v61
	v_mul_f32_e32 v55, v129, v55
	s_waitcnt lgkmcnt(0)
	v_pk_add_f32 v[42:43], v[42:43], v[50:51]
	ds_bpermute_b32 v51, v80, v43
	ds_bpermute_b32 v50, v80, v42
	v_cvt_pk_bf16_f32 v56, v56, s0
	v_cvt_pk_bf16_f32 v55, v55, s0
	v_add_u32_e32 v74, 26, v134
	v_add_u32_e32 v76, 27, v134
	s_waitcnt lgkmcnt(0)
	v_pk_add_f32 v[42:43], v[42:43], v[50:51]
	v_mov_b32_e32 v66, v14
	v_pk_fma_f32 v[42:43], v[42:43], s[30:31], v[32:33] op_sel_hi:[1,0,0]
	v_mov_b32_e32 v67, v30
	v_mul_f32_e32 v50, 0x4b800000, v43
	v_cmp_gt_f32_e32 vcc, s81, v43
	v_and_or_b32 v14, v76, 63, v186
	global_store_short v[12:13], v56, off offset:64
	v_cndmask_b32_e32 v43, v43, v50, vcc
	v_rsq_f32_e32 v43, v43
	v_add_u32_e32 v50, v82, v190
	v_mad_i64_i32 v[50:51], s[0:1], v50, s78, v[16:17]
	v_mul_f32_e32 v54, 0x45800000, v43
	v_cndmask_b32_e32 v71, v43, v54, vcc
	v_mul_f32_e32 v43, v58, v71
	v_mul_f32_e32 v43, v131, v43
	v_cvt_pk_bf16_f32 v43, v43, s0
	global_store_short v[50:51], v43, off
	v_mul_f32_e32 v43, v59, v71
	v_mul_f32_e32 v43, v130, v43
	v_cvt_pk_bf16_f32 v43, v43, s0
	global_store_short v[50:51], v43, off offset:64
	v_mul_f32_e32 v43, v53, v71
	v_mul_f32_e32 v43, v129, v43
	v_cvt_pk_bf16_f32 v53, v43, s0
	v_mul_f32_e32 v43, 0x4b800000, v42
	v_cmp_gt_f32_e32 vcc, s81, v42
	v_mov_b32_e32 v58, v62
	v_mov_b32_e32 v59, v46
	v_cndmask_b32_e32 v42, v42, v43, vcc
	v_rsq_f32_e32 v73, v42
	v_and_or_b32 v42, v74, 62, v186
	v_lshlrev_b32_e32 v43, 2, v42
	ds_bpermute_b32 v54, v43, v132
	ds_bpermute_b32 v42, v43, v133
	global_store_short v[12:13], v55, off offset:128
	v_mov_b32_e32 v56, v78
	v_mov_b32_e32 v57, v94
	s_waitcnt lgkmcnt(1)
	v_pk_mul_f32 v[58:59], v[58:59], v[54:55] op_sel_hi:[1,0]
	v_mov_b32_e32 v60, v126
	v_mov_b32_e32 v61, v110
	v_pk_mul_f32 v[54:55], v[66:67], v[54:55] op_sel_hi:[1,0]
	v_lshlrev_b32_e32 v14, 2, v14
	s_waitcnt lgkmcnt(0)
	v_pk_fma_f32 v[56:57], v[56:57], v[42:43], v[58:59] op_sel_hi:[1,0,1] neg_lo:[0,0,1] neg_hi:[0,0,1]
	v_pk_fma_f32 v[42:43], v[60:61], v[42:43], v[54:55] op_sel_hi:[1,0,1] neg_lo:[0,0,1] neg_hi:[0,0,1]
	ds_bpermute_b32 v55, v14, v132
	ds_bpermute_b32 v54, v14, v133
	v_mov_b32_e32 v46, v63
	v_mov_b32_e32 v94, v79
	v_pk_mul_f32 v[58:59], v[56:57], v[56:57]
	s_waitcnt lgkmcnt(1)
	v_mov_b32_e32 v14, v55
	v_pk_mul_f32 v[46:47], v[46:47], v[14:15] op_sel_hi:[1,0]
	v_mov_b32_e32 v14, v127
	s_waitcnt lgkmcnt(0)
; DI u16 f2bf(float a) { return (u16)(pk2(a, 0.f) & 0xffffu); }
; DI int crow(int i, int h) { return (i & 3) + 8 * (i >> 2) + 4 * h; }
; __device__ __forceinline__ void attn_item_A(const Params& p, int layer, int head, int q0u, char* lds) {
;     ...
; #pragma unroll
;   for (int e = 0; e < 16; ++e) {
;     const int qq = crow(e, h_e);
;     const float ia = __shfl(iA, qq), ib = __shfl(iB, qq);
;     float ov[4];
;     float ss = 0.f;
; #pragma unroll
;     for (int d = 0; d < 4; ++d) { ov[d] = o1[d][e] * ia - o2[d][e] * ib; ss += ov[d] * ov[d]; }
; #pragma unroll
;     for (int x = 16; x >= 1; x >>= 1) ss += __shfl_xor(ss, x);
;     const float rs = rsqrtf(ss * (1.f / 128.f) + LN_EPS);
;     const size_t rowoff = (size_t)(orow0 + qq) * LDX + ocol + r_e;
; #pragma unroll
;     for (int d = 0; d < 4; ++d) Mx[rowoff + d * 32] = f2bf(ov[d] * rs * sw[d]);
;   }
	v_pk_mul_f32 v[14:15], v[14:15], v[54:55]
	v_pk_fma_f32 v[46:47], v[94:95], v[54:55], v[46:47] op_sel_hi:[1,0,1] neg_lo:[0,0,1] neg_hi:[0,0,1]
	v_mul_f32_e32 v67, v111, v54
	v_mul_f32_e32 v31, v31, v55
	v_mov_b32_e32 v66, v14
	v_mov_b32_e32 v30, v15
	v_pk_mul_f32 v[62:63], v[46:47], v[46:47]
	v_pk_add_f32 v[14:15], v[66:67], v[30:31] neg_lo:[0,1] neg_hi:[0,1]
	v_pk_mul_f32 v[60:61], v[42:43], v[42:43]
	v_pk_mul_f32 v[30:31], v[14:15], v[14:15]
	v_mov_b32_e32 v54, v62
	v_mov_b32_e32 v55, v58
	v_mov_b32_e32 v58, v63
	v_pk_add_f32 v[54:55], v[54:55], v[58:59]
	v_mov_b32_e32 v58, v31
	v_mov_b32_e32 v59, v61
	v_pk_add_f32 v[54:55], v[58:59], v[54:55]
	v_mov_b32_e32 v31, v60
	v_pk_add_f32 v[30:31], v[30:31], v[54:55]
	ds_bpermute_b32 v55, v48, v31
	ds_bpermute_b32 v54, v48, v30
	global_store_short v[50:51], v53, off offset:128
	v_mul_f32_e32 v58, v52, v71
	v_mul_f32_e32 v48, 0x45800000, v73
	v_cndmask_b32_e32 v59, v73, v48, vcc
	s_waitcnt lgkmcnt(0)
	v_pk_add_f32 v[30:31], v[30:31], v[54:55]
	ds_bpermute_b32 v53, v49, v31
	ds_bpermute_b32 v52, v49, v30
	v_add_u32_e32 v48, v70, v190
	v_mul_f32_e32 v44, v44, v59
	v_mad_i64_i32 v[48:49], s[0:1], v48, s78, v[16:17]
	s_waitcnt lgkmcnt(0)
	v_pk_add_f32 v[30:31], v[30:31], v[52:53]
	ds_bpermute_b32 v53, v64, v31
	ds_bpermute_b32 v52, v64, v30
	v_mul_f32_e32 v44, v131, v44
	v_cvt_pk_bf16_f32 v44, v44, s0
	global_store_short v[48:49], v44, off
	v_mul_f32_e32 v54, v45, v59
	s_waitcnt lgkmcnt(0)
	v_pk_add_f32 v[30:31], v[30:31], v[52:53]
	ds_bpermute_b32 v45, v65, v31
	ds_bpermute_b32 v44, v65, v30
	v_mul_f32_e32 v29, v29, v59
	v_mul_f32_e32 v52, v130, v54
	v_mul_f32_e32 v29, v129, v29
	v_cvt_pk_bf16_f32 v52, v52, s0
	s_waitcnt lgkmcnt(0)
	v_pk_add_f32 v[30:31], v[30:31], v[44:45]
	ds_bpermute_b32 v45, v80, v31
	ds_bpermute_b32 v44, v80, v30
	v_cvt_pk_bf16_f32 v29, v29, s0
	global_store_short v[48:49], v52, off offset:64
	global_store_short v[48:49], v29, off offset:128
	v_mul_f32_e32 v52, v28, v59
	s_waitcnt lgkmcnt(0)
	v_pk_add_f32 v[28:29], v[30:31], v[44:45]
	s_nop 0
	v_pk_fma_f32 v[28:29], v[28:29], s[30:31], v[32:33] op_sel_hi:[1,0,0]
	s_nop 0
	v_mul_f32_e32 v30, 0x4b800000, v29
	v_cmp_gt_f32_e32 vcc, s81, v29
	v_mul_f32_e32 v33, 0x4b800000, v28
	s_nop 0
	v_cndmask_b32_e32 v29, v29, v30, vcc
	v_rsq_f32_e32 v29, v29
	v_add_u32_e32 v30, v74, v190
	v_mad_i64_i32 v[30:31], s[0:1], v30, s78, v[16:17]
	v_mul_f32_e32 v32, 0x45800000, v29
	v_cndmask_b32_e32 v29, v29, v32, vcc
	v_mul_f32_e32 v32, v56, v29
	v_mul_f32_e32 v32, v131, v32
	v_cvt_pk_bf16_f32 v32, v32, s0
	global_store_short v[30:31], v32, off
	v_mul_f32_e32 v32, v57, v29
	v_cmp_gt_f32_e32 vcc, s81, v28
	v_mul_f32_e32 v32, v130, v32
	v_cvt_pk_bf16_f32 v32, v32, s0
	v_cndmask_b32_e32 v28, v28, v33, vcc
	v_rsq_f32_e32 v28, v28
	global_store_short v[30:31], v32, off offset:64
	v_mul_f32_e32 v32, v43, v29
	v_mul_f32_e32 v32, v129, v32
	v_cvt_pk_bf16_f32 v32, v32, s0
	global_store_short v[30:31], v32, off offset:128
	v_mul_f32_e32 v32, 0x45800000, v28
	v_cndmask_b32_e32 v167, v28, v32, vcc
	v_add_u32_e32 v28, v76, v190
	v_mad_i64_i32 v[16:17], s[0:1], v28, s78, v[16:17]
	v_mul_f32_e32 v28, v46, v167
	v_mul_f32_e32 v28, v131, v28
	v_cvt_pk_bf16_f32 v28, v28, s0
	v_mul_f32_e32 v15, v15, v167
	global_store_short v[16:17], v28, off
	v_mul_f32_e32 v28, v47, v167
	v_mul_f32_e32 v15, v129, v15
	v_mul_f32_e32 v28, v130, v28
	v_cvt_pk_bf16_f32 v15, v15, s0
	v_mov_b32_e32 v129, v14
	v_cvt_pk_bf16_f32 v28, v28, s0
	global_store_short v[16:17], v15, off offset:128
	s_waitcnt vmcnt(47)
	v_pk_mul_f32 v[14:15], v[128:129], v[166:167]
	global_store_short v[16:17], v28, off offset:64
	v_mul_f32_e32 v28, v14, v34
	v_cvt_pk_bf16_f32 v28, v28, s0
	global_store_short v[0:1], v28, off offset:192
	v_mul_f32_e32 v0, v14, v35
	v_cvt_pk_bf16_f32 v0, v0, s0
	global_store_short v[2:3], v0, off offset:192
	v_mul_f32_e32 v0, v14, v36
	v_cvt_pk_bf16_f32 v0, v0, s0
	global_store_short v[18:19], v0, off offset:192
	v_mul_f32_e32 v0, v14, v37
	v_cvt_pk_bf16_f32 v0, v0, s0
	global_store_short v[4:5], v0, off offset:192
	v_mul_f32_e32 v0, v14, v38
	v_cvt_pk_bf16_f32 v0, v0, s0
	global_store_short v[20:21], v0, off offset:192
	v_mul_f32_e32 v0, v14, v39
	v_cvt_pk_bf16_f32 v0, v0, s0
	global_store_short v[6:7], v0, off offset:192
	v_mul_f32_e32 v0, v14, v40
	v_cvt_pk_bf16_f32 v0, v0, s0
	global_store_short v[22:23], v0, off offset:192
	v_mul_f32_e32 v0, v14, v41
	v_cvt_pk_bf16_f32 v0, v0, s0
	global_store_short v[8:9], v0, off offset:192
	v_mul_f32_e32 v0, v14, v75
	v_cvt_pk_bf16_f32 v0, v0, s0
	global_store_short v[24:25], v0, off offset:192
	v_mul_f32_e32 v0, v14, v72
	v_cvt_pk_bf16_f32 v0, v0, s0
	global_store_short v[10:11], v0, off offset:192
	v_mul_f32_e32 v0, v14, v68
	v_cvt_pk_bf16_f32 v0, v0, s0
	global_store_short v[26:27], v0, off offset:192
	v_mul_f32_e32 v0, v14, v69
	v_cvt_pk_bf16_f32 v0, v0, s0
	global_store_short v[12:13], v0, off offset:192
	v_mul_f32_e32 v0, v14, v58
	v_cvt_pk_bf16_f32 v0, v0, s0
	global_store_short v[50:51], v0, off offset:192
	v_mul_f32_e32 v0, v14, v52
	v_mul_f32_e32 v29, v42, v29
	v_cvt_pk_bf16_f32 v0, v0, s0
	global_store_short v[48:49], v0, off offset:192
	v_mul_f32_e32 v0, v14, v29
	v_cvt_pk_bf16_f32 v0, v0, s0
	global_store_short v[30:31], v0, off offset:192
	v_mul_f32_e32 v0, v14, v15
	s_branch .LBB0_2240
